# device-scope write-through (sc1) on the wide intermediate stores of N1/AT/G2/G3/N2/G4/G5; the grid barrier's L2 write-back runs only behind PRE and G1 (the phases that keep write-back stores)
# speedup vs baseline: 1.0149x; 1.0149x over previous
.LBB0_53:
	s_andn2_saveexec_b64 s[20:21], s[20:21]
	s_cbranch_execz .LBB0_73
	s_mov_b64 s[20:21], exec
	s_cmp_eq_u32 s16, 1
	s_cbranch_scc1 .Lbar_wb
	s_and_b32 s22, s16, 7
	s_cmp_lg_u32 s22, 3
	s_cbranch_scc1 .Lbar_nowb
.Lbar_wb:
	buffer_wbl2 sc1
.Lbar_nowb:
	s_waitcnt lgkmcnt(0)
	s_waitcnt vmcnt(0)
	v_mbcnt_lo_u32_b32 v0, s20, 0
	v_mbcnt_hi_u32_b32 v0, s21, v0
	v_cmp_eq_u32_e32 vcc, 0, v0
	s_and_saveexec_b64 s[22:23], vcc
	s_cbranch_execz .LBB0_56
	s_bcnt1_i32_b64 s8, s[20:21]
	v_readlane_b32 s20, v254, 15
	v_mov_b32_e32 v3, s8
	v_readlane_b32 s21, v254, 16
	s_nop 4
	global_atomic_add v3, v1, v3, s[20:21] sc0

.LBB0_93:
	s_or_b64 exec, exec, s[22:23]
	s_movk_i32 s22, 0x4400
	v_mul_lo_u32 v4, v136, s22
	v_lshl_or_b32 v2, v138, 2, v4
	s_movk_i32 s22, 0x440
	v_mad_u32_u24 v2, v135, s22, v2
	v_add_u32_e32 v5, 0x1000, v2
	v_add_u32_e32 v6, 0x1400, v2
	s_waitcnt vmcnt(0) lgkmcnt(0)
	s_barrier
	ds_write2_b32 v2, v102, v90 offset1:16
	ds_write2_b32 v2, v103, v91 offset0:68 offset1:84
	ds_write2_b32 v2, v104, v92 offset0:136 offset1:152
	ds_write2_b32 v2, v105, v93 offset0:204 offset1:220
	ds_write2_b32 v2, v74, v94 offset0:32 offset1:48
	ds_write2_b32 v2, v75, v95 offset0:100 offset1:116
	ds_write2_b32 v2, v76, v96 offset0:168 offset1:184
	ds_write2_b32 v2, v77, v97 offset0:236 offset1:252
	ds_write2_b32 v5, v98, v78 offset0:64 offset1:80
	ds_write2_b32 v5, v99, v79 offset0:132 offset1:148
	ds_write2_b32 v5, v100, v80 offset0:200 offset1:216
	ds_write2_b32 v6, v101, v81 offset0:12 offset1:28
	ds_write2_b32 v5, v58, v82 offset0:96 offset1:112
	ds_write2_b32 v5, v59, v83 offset0:164 offset1:180
	ds_write2_b32 v5, v60, v84 offset0:232 offset1:248
	ds_write2_b32 v6, v61, v85 offset0:44 offset1:60
	v_add_u32_e32 v5, 0x2000, v2
	v_add_u32_e32 v6, 0x2400, v2
	ds_write2_b32 v5, v86, v62 offset0:128 offset1:144
	ds_write2_b32 v5, v87, v63 offset0:196 offset1:212
	ds_write2_b32 v6, v88, v64 offset0:8 offset1:24
	ds_write2_b32 v6, v89, v65 offset0:76 offset1:92
	ds_write2_b32 v5, v38, v66 offset0:160 offset1:176
	ds_write2_b32 v5, v39, v67 offset0:228 offset1:244
	ds_write2_b32 v6, v40, v68 offset0:40 offset1:56
	ds_write2_b32 v6, v41, v69 offset0:108 offset1:124
	v_add_u32_e32 v5, 0x3000, v2
	v_add_u32_e32 v2, 0x3400, v2
	ds_write2_b32 v5, v70, v50 offset0:192 offset1:208
	ds_write2_b32 v2, v71, v51 offset0:4 offset1:20
	ds_write2_b32 v2, v72, v52 offset0:72 offset1:88
	ds_write2_b32 v2, v73, v53 offset0:140 offset1:156
	ds_write2_b32 v5, v30, v34 offset0:224 offset1:240
	ds_write2_b32 v2, v31, v35 offset0:36 offset1:52
	ds_write2_b32 v2, v32, v36 offset0:104 offset1:120
	ds_write2_b32 v2, v33, v37 offset0:172 offset1:188
	v_lshlrev_b32_e32 v2, 3, v134
	v_lshlrev_b32_e32 v3, 6, v139
	v_lshl_add_u32 v5, v0, 6, s31
	v_lshrrev_b32_e32 v0, 3, v134
	v_and_b32_e32 v7, 56, v2
	v_or_b32_e32 v2, v5, v0
	v_or3_b32 v6, v3, s19, v7
	v_mul_u32_u24_e32 v0, 0x110, v0
	v_lshlrev_b32_e32 v3, 2, v7
	v_add3_u32 v0, v4, v0, v3
	v_add_u32_e32 v3, 0xfffff000, v5
	v_lshrrev_b32_e32 v10, 10, v3
	v_cmp_lt_i32_e32 vcc, s1, v2
	v_mov_b64_e32 v[4:5], s[14:15]
	v_ashrrev_i32_e32 v7, 31, v6
	v_cndmask_b32_e32 v3, 4, v10, vcc
	v_add_u32_e32 v3, s8, v3
	v_mad_i64_i32 v[12:13], s[22:23], v3, s82, v[4:5]
	v_lshlrev_b64 v[8:9], 2, v[6:7]
	v_ashrrev_i32_e32 v3, 31, v2
	v_lshl_add_u64 v[20:21], v[12:13], 0, v[8:9]
	v_lshlrev_b64 v[12:13], 11, v[2:3]
	v_lshl_add_u64 v[12:13], s[66:67], 0, v[12:13]
	v_lshlrev_b64 v[6:7], 1, v[6:7]
	v_lshl_add_u64 v[28:29], v[12:13], 0, v[6:7]
	global_load_dwordx4 v[12:15], v[28:29], off
	s_mov_b64 s[24:25], 0x8605000
	s_mov_b32 s19, 0x8605000
	v_lshl_add_u64 v[24:25], v[20:21], 0, s[24:25]
	v_add_co_u32_e32 v20, vcc, s19, v20
	s_add_i32 s17, s17, s64
	s_nop 0
	v_addc_co_u32_e32 v21, vcc, 0, v21, vcc
	s_cmpk_gt_i32 s17, 0xff
	s_waitcnt vmcnt(0)
	v_lshlrev_b32_e32 v30, 16, v12
	v_and_b32_e32 v31, 0xffff0000, v12
	v_lshlrev_b32_e32 v32, 16, v13
	v_and_b32_e32 v33, 0xffff0000, v13
	v_lshlrev_b32_e32 v34, 16, v14
	v_and_b32_e32 v35, 0xffff0000, v14
	v_lshlrev_b32_e32 v36, 16, v15
	v_and_b32_e32 v37, 0xffff0000, v15
	ds_read_b128 v[12:15], v0
	ds_read_b128 v[16:19], v0 offset:16
	global_load_dwordx4 v[20:23], v[20:21], off
	s_nop 0
	global_load_dwordx4 v[24:27], v[24:25], off offset:16
	s_waitcnt vmcnt(1) lgkmcnt(1)
	v_pk_fma_f32 v[12:13], v[12:13], v[20:21], v[30:31]
	v_pk_fma_f32 v[14:15], v[14:15], v[22:23], v[32:33]
	s_waitcnt vmcnt(0) lgkmcnt(0)
	v_pk_fma_f32 v[16:17], v[16:17], v[24:25], v[34:35]
	v_pk_fma_f32 v[18:19], v[18:19], v[26:27], v[36:37]
	v_cvt_pk_bf16_f32 v12, v12, v13
	v_cvt_pk_bf16_f32 v13, v14, v15
	v_cvt_pk_bf16_f32 v14, v16, v17
	v_cvt_pk_bf16_f32 v15, v18, v19
	global_store_dwordx4 v[28:29], v[12:15], off sc1
	s_nop 1
	v_or_b32_e32 v12, 8, v2
	v_cmp_lt_i32_e32 vcc, s1, v12
	v_ashrrev_i32_e32 v13, 31, v12
	v_lshlrev_b64 v[12:13], 11, v[12:13]
	v_cndmask_b32_e32 v3, 4, v10, vcc
	v_add_u32_e32 v3, s8, v3
	v_lshl_add_u64 v[12:13], s[66:67], 0, v[12:13]
	v_mad_i64_i32 v[14:15], s[22:23], v3, s82, v[4:5]
	v_lshl_add_u64 v[24:25], v[12:13], 0, v[6:7]
	v_lshl_add_u64 v[16:17], v[14:15], 0, v[8:9]
	global_load_dwordx4 v[12:15], v[24:25], off
	v_lshl_add_u64 v[20:21], v[16:17], 0, s[24:25]
	v_add_co_u32_e32 v16, vcc, s19, v16
	s_waitcnt vmcnt(0)
	v_lshlrev_b32_e32 v26, 16, v12
	v_addc_co_u32_e32 v17, vcc, 0, v17, vcc
	v_and_b32_e32 v27, 0xffff0000, v12
	v_lshlrev_b32_e32 v28, 16, v13
	v_and_b32_e32 v29, 0xffff0000, v13
	v_lshlrev_b32_e32 v30, 16, v14
	v_and_b32_e32 v31, 0xffff0000, v14
	v_lshlrev_b32_e32 v32, 16, v15
	v_and_b32_e32 v33, 0xffff0000, v15
	ds_read_b128 v[12:15], v0 offset:2176
	global_load_dwordx4 v[16:19], v[16:17], off
	s_nop 0
	global_load_dwordx4 v[20:23], v[20:21], off offset:16
	s_waitcnt vmcnt(1) lgkmcnt(0)
	v_pk_fma_f32 v[16:17], v[12:13], v[16:17], v[26:27]
	v_pk_fma_f32 v[18:19], v[14:15], v[18:19], v[28:29]
	ds_read_b128 v[12:15], v0 offset:2192
	s_waitcnt vmcnt(0) lgkmcnt(0)
	v_pk_fma_f32 v[20:21], v[12:13], v[20:21], v[30:31]
	v_pk_fma_f32 v[22:23], v[14:15], v[22:23], v[32:33]
	v_cvt_pk_bf16_f32 v12, v16, v17
	v_cvt_pk_bf16_f32 v13, v18, v19
	v_cvt_pk_bf16_f32 v14, v20, v21
	v_cvt_pk_bf16_f32 v15, v22, v23
	global_store_dwordx4 v[24:25], v[12:15], off sc1
	s_nop 1
	v_or_b32_e32 v12, 16, v2
	v_cmp_lt_i32_e32 vcc, s1, v12
	v_ashrrev_i32_e32 v13, 31, v12
	v_lshlrev_b64 v[12:13], 11, v[12:13]
	v_cndmask_b32_e32 v3, 4, v10, vcc
	v_add_u32_e32 v3, s8, v3
	v_lshl_add_u64 v[12:13], s[66:67], 0, v[12:13]
	v_mad_i64_i32 v[14:15], s[22:23], v3, s82, v[4:5]
	v_lshl_add_u64 v[24:25], v[12:13], 0, v[6:7]
	v_lshl_add_u64 v[16:17], v[14:15], 0, v[8:9]
	global_load_dwordx4 v[12:15], v[24:25], off
	v_lshl_add_u64 v[20:21], v[16:17], 0, s[24:25]
	v_add_co_u32_e32 v16, vcc, s19, v16
	s_waitcnt vmcnt(0)
	v_lshlrev_b32_e32 v26, 16, v12
	v_addc_co_u32_e32 v17, vcc, 0, v17, vcc
	v_and_b32_e32 v27, 0xffff0000, v12
	v_lshlrev_b32_e32 v28, 16, v13
	v_and_b32_e32 v29, 0xffff0000, v13
	v_lshlrev_b32_e32 v30, 16, v14
	v_and_b32_e32 v31, 0xffff0000, v14
	v_lshlrev_b32_e32 v32, 16, v15
	v_and_b32_e32 v33, 0xffff0000, v15
	ds_read_b128 v[12:15], v0 offset:4352
	global_load_dwordx4 v[16:19], v[16:17], off
	s_nop 0
	global_load_dwordx4 v[20:23], v[20:21], off offset:16
	s_waitcnt vmcnt(1) lgkmcnt(0)
	v_pk_fma_f32 v[16:17], v[12:13], v[16:17], v[26:27]
	v_pk_fma_f32 v[18:19], v[14:15], v[18:19], v[28:29]
	ds_read_b128 v[12:15], v0 offset:4368
	s_waitcnt vmcnt(0) lgkmcnt(0)
	v_pk_fma_f32 v[20:21], v[12:13], v[20:21], v[30:31]
	v_pk_fma_f32 v[22:23], v[14:15], v[22:23], v[32:33]
	v_cvt_pk_bf16_f32 v12, v16, v17
	v_cvt_pk_bf16_f32 v13, v18, v19
	v_cvt_pk_bf16_f32 v14, v20, v21
	v_cvt_pk_bf16_f32 v15, v22, v23
	global_store_dwordx4 v[24:25], v[12:15], off sc1
	s_nop 1
	v_or_b32_e32 v12, 24, v2
	v_cmp_lt_i32_e32 vcc, s1, v12
	v_ashrrev_i32_e32 v13, 31, v12
	v_lshlrev_b64 v[12:13], 11, v[12:13]
	v_cndmask_b32_e32 v3, 4, v10, vcc
	v_add_u32_e32 v3, s8, v3
	v_lshl_add_u64 v[12:13], s[66:67], 0, v[12:13]
	v_mad_i64_i32 v[14:15], s[22:23], v3, s82, v[4:5]
	v_lshl_add_u64 v[28:29], v[12:13], 0, v[6:7]
	v_lshl_add_u64 v[20:21], v[14:15], 0, v[8:9]
	global_load_dwordx4 v[12:15], v[28:29], off
	v_lshl_add_u64 v[24:25], v[20:21], 0, s[24:25]
	v_add_co_u32_e32 v20, vcc, s19, v20
	s_waitcnt vmcnt(0)
	v_lshlrev_b32_e32 v30, 16, v12
	v_addc_co_u32_e32 v21, vcc, 0, v21, vcc
	v_and_b32_e32 v31, 0xffff0000, v12
	v_lshlrev_b32_e32 v32, 16, v13
	v_and_b32_e32 v33, 0xffff0000, v13
	v_lshlrev_b32_e32 v34, 16, v14
	v_and_b32_e32 v35, 0xffff0000, v14
	v_lshlrev_b32_e32 v36, 16, v15
	v_and_b32_e32 v37, 0xffff0000, v15
	ds_read_b128 v[12:15], v0 offset:6528
	ds_read_b128 v[16:19], v0 offset:6544
	global_load_dwordx4 v[20:23], v[20:21], off
	s_nop 0
	global_load_dwordx4 v[24:27], v[24:25], off offset:16
	s_waitcnt vmcnt(1) lgkmcnt(1)
	v_pk_fma_f32 v[12:13], v[12:13], v[20:21], v[30:31]
	v_pk_fma_f32 v[14:15], v[14:15], v[22:23], v[32:33]
	s_waitcnt vmcnt(0) lgkmcnt(0)
	v_pk_fma_f32 v[16:17], v[16:17], v[24:25], v[34:35]
	v_pk_fma_f32 v[18:19], v[18:19], v[26:27], v[36:37]
	v_cvt_pk_bf16_f32 v12, v12, v13
	v_cvt_pk_bf16_f32 v13, v14, v15
	v_cvt_pk_bf16_f32 v14, v16, v17
	v_cvt_pk_bf16_f32 v15, v18, v19
	global_store_dwordx4 v[28:29], v[12:15], off sc1
	s_nop 1
	v_or_b32_e32 v12, 32, v2
	v_cmp_lt_i32_e32 vcc, s1, v12
	v_ashrrev_i32_e32 v13, 31, v12
	v_lshlrev_b64 v[12:13], 11, v[12:13]
	v_cndmask_b32_e32 v3, 4, v10, vcc
	v_add_u32_e32 v3, s8, v3
	v_lshl_add_u64 v[12:13], s[66:67], 0, v[12:13]
	v_mad_i64_i32 v[14:15], s[22:23], v3, s82, v[4:5]
	v_lshl_add_u64 v[28:29], v[12:13], 0, v[6:7]
	v_lshl_add_u64 v[20:21], v[14:15], 0, v[8:9]
	global_load_dwordx4 v[12:15], v[28:29], off
	v_lshl_add_u64 v[24:25], v[20:21], 0, s[24:25]
	v_add_co_u32_e32 v20, vcc, s19, v20
	s_waitcnt vmcnt(0)
	v_lshlrev_b32_e32 v30, 16, v12
	v_addc_co_u32_e32 v21, vcc, 0, v21, vcc
	v_and_b32_e32 v31, 0xffff0000, v12
	v_lshlrev_b32_e32 v32, 16, v13
	v_and_b32_e32 v33, 0xffff0000, v13
	v_lshlrev_b32_e32 v34, 16, v14
	v_and_b32_e32 v35, 0xffff0000, v14
	v_lshlrev_b32_e32 v36, 16, v15
	v_and_b32_e32 v37, 0xffff0000, v15
	ds_read_b128 v[12:15], v0 offset:8704
	ds_read_b128 v[16:19], v0 offset:8720
	global_load_dwordx4 v[20:23], v[20:21], off
	s_nop 0
	global_load_dwordx4 v[24:27], v[24:25], off offset:16
	s_waitcnt vmcnt(1) lgkmcnt(1)
	v_pk_fma_f32 v[12:13], v[12:13], v[20:21], v[30:31]
	v_pk_fma_f32 v[14:15], v[14:15], v[22:23], v[32:33]
	s_waitcnt vmcnt(0) lgkmcnt(0)
	v_pk_fma_f32 v[16:17], v[16:17], v[24:25], v[34:35]
	v_pk_fma_f32 v[18:19], v[18:19], v[26:27], v[36:37]
	v_cvt_pk_bf16_f32 v12, v12, v13
	v_cvt_pk_bf16_f32 v13, v14, v15
	v_cvt_pk_bf16_f32 v14, v16, v17
	v_cvt_pk_bf16_f32 v15, v18, v19
	global_store_dwordx4 v[28:29], v[12:15], off sc1
	s_nop 1
	v_or_b32_e32 v12, 40, v2
	v_cmp_lt_i32_e32 vcc, s1, v12
	v_ashrrev_i32_e32 v13, 31, v12
	v_lshlrev_b64 v[12:13], 11, v[12:13]
	v_cndmask_b32_e32 v3, 4, v10, vcc
	v_add_u32_e32 v3, s8, v3
	v_lshl_add_u64 v[12:13], s[66:67], 0, v[12:13]
	v_mad_i64_i32 v[14:15], s[22:23], v3, s82, v[4:5]
	v_lshl_add_u64 v[28:29], v[12:13], 0, v[6:7]
	v_lshl_add_u64 v[20:21], v[14:15], 0, v[8:9]
	global_load_dwordx4 v[12:15], v[28:29], off
	v_lshl_add_u64 v[24:25], v[20:21], 0, s[24:25]
	v_add_co_u32_e32 v20, vcc, s19, v20
	s_waitcnt vmcnt(0)
	v_lshlrev_b32_e32 v30, 16, v12
	v_addc_co_u32_e32 v21, vcc, 0, v21, vcc
	v_and_b32_e32 v31, 0xffff0000, v12
	v_lshlrev_b32_e32 v32, 16, v13
	v_and_b32_e32 v33, 0xffff0000, v13
	v_lshlrev_b32_e32 v34, 16, v14
	v_and_b32_e32 v35, 0xffff0000, v14
	v_lshlrev_b32_e32 v36, 16, v15
	v_and_b32_e32 v37, 0xffff0000, v15
	ds_read_b128 v[12:15], v0 offset:10880
	ds_read_b128 v[16:19], v0 offset:10896
	global_load_dwordx4 v[20:23], v[20:21], off
	s_nop 0
	global_load_dwordx4 v[24:27], v[24:25], off offset:16
	s_waitcnt vmcnt(1) lgkmcnt(1)
	v_pk_fma_f32 v[12:13], v[12:13], v[20:21], v[30:31]
	v_pk_fma_f32 v[14:15], v[14:15], v[22:23], v[32:33]
	s_waitcnt vmcnt(0) lgkmcnt(0)
	v_pk_fma_f32 v[16:17], v[16:17], v[24:25], v[34:35]
	v_pk_fma_f32 v[18:19], v[18:19], v[26:27], v[36:37]
	v_cvt_pk_bf16_f32 v12, v12, v13
	v_cvt_pk_bf16_f32 v13, v14, v15
	v_cvt_pk_bf16_f32 v14, v16, v17
	v_cvt_pk_bf16_f32 v15, v18, v19
	global_store_dwordx4 v[28:29], v[12:15], off sc1
	s_nop 1
	v_or_b32_e32 v12, 48, v2
	v_cmp_lt_i32_e32 vcc, s1, v12
	v_ashrrev_i32_e32 v13, 31, v12
	v_lshlrev_b64 v[12:13], 11, v[12:13]
	v_cndmask_b32_e32 v3, 4, v10, vcc
	v_add_u32_e32 v3, s8, v3
	v_lshl_add_u64 v[12:13], s[66:67], 0, v[12:13]
	v_mad_i64_i32 v[14:15], s[22:23], v3, s82, v[4:5]
	v_lshl_add_u64 v[28:29], v[12:13], 0, v[6:7]
	v_lshl_add_u64 v[20:21], v[14:15], 0, v[8:9]
	global_load_dwordx4 v[12:15], v[28:29], off
	v_lshl_add_u64 v[24:25], v[20:21], 0, s[24:25]
	v_add_co_u32_e32 v20, vcc, s19, v20
	v_or_b32_e32 v2, 56, v2
	s_nop 0
	v_addc_co_u32_e32 v21, vcc, 0, v21, vcc
	v_cmp_lt_i32_e32 vcc, s1, v2
	s_waitcnt vmcnt(0)
	v_lshlrev_b32_e32 v30, 16, v12
	v_and_b32_e32 v31, 0xffff0000, v12
	v_lshlrev_b32_e32 v32, 16, v13
	v_and_b32_e32 v33, 0xffff0000, v13
	v_lshlrev_b32_e32 v34, 16, v14
	v_and_b32_e32 v35, 0xffff0000, v14
	v_lshlrev_b32_e32 v36, 16, v15
	v_and_b32_e32 v37, 0xffff0000, v15
	ds_read_b128 v[12:15], v0 offset:13056
	ds_read_b128 v[16:19], v0 offset:13072
	global_load_dwordx4 v[20:23], v[20:21], off
	s_nop 0
	global_load_dwordx4 v[24:27], v[24:25], off offset:16
	v_cndmask_b32_e32 v3, 4, v10, vcc
	v_add_u32_e32 v3, s8, v3
	v_mad_i64_i32 v[4:5], s[22:23], v3, s82, v[4:5]
	v_ashrrev_i32_e32 v3, 31, v2
	v_lshlrev_b64 v[2:3], 11, v[2:3]
	v_lshl_add_u64 v[2:3], s[66:67], 0, v[2:3]
	v_lshl_add_u64 v[10:11], v[4:5], 0, v[8:9]
	s_waitcnt vmcnt(1) lgkmcnt(1)
	v_pk_fma_f32 v[12:13], v[12:13], v[20:21], v[30:31]
	v_pk_fma_f32 v[14:15], v[14:15], v[22:23], v[32:33]
	s_waitcnt vmcnt(0) lgkmcnt(0)
	v_pk_fma_f32 v[18:19], v[18:19], v[26:27], v[36:37]
	v_cvt_pk_bf16_f32 v12, v12, v13
	v_cvt_pk_bf16_f32 v13, v14, v15
	v_cvt_pk_bf16_f32 v15, v18, v19
	v_lshl_add_u64 v[18:19], v[2:3], 0, v[6:7]
	global_load_dwordx4 v[2:5], v[18:19], off
	v_pk_fma_f32 v[16:17], v[16:17], v[24:25], v[34:35]
	s_waitcnt vmcnt(0)
	v_lshlrev_b32_e32 v20, 16, v2
	v_cvt_pk_bf16_f32 v14, v16, v17
	global_store_dwordx4 v[28:29], v[12:15], off sc1
	v_and_b32_e32 v21, 0xffff0000, v2
	v_lshlrev_b32_e32 v22, 16, v3
	v_lshl_add_u64 v[14:15], v[10:11], 0, s[24:25]
	v_add_co_u32_e32 v10, vcc, s19, v10
	v_and_b32_e32 v23, 0xffff0000, v3
	s_nop 0
	v_addc_co_u32_e32 v11, vcc, 0, v11, vcc
	v_lshlrev_b32_e32 v24, 16, v4
	v_and_b32_e32 v25, 0xffff0000, v4
	v_lshlrev_b32_e32 v26, 16, v5
	v_and_b32_e32 v27, 0xffff0000, v5
	ds_read_b128 v[2:5], v0 offset:15232
	ds_read_b128 v[6:9], v0 offset:15248
	global_load_dwordx4 v[10:13], v[10:11], off
	s_nop 0
	global_load_dwordx4 v[14:17], v[14:15], off offset:16
	s_waitcnt vmcnt(1) lgkmcnt(1)
	v_pk_fma_f32 v[2:3], v[2:3], v[10:11], v[20:21]
	v_pk_fma_f32 v[4:5], v[4:5], v[12:13], v[22:23]
	s_waitcnt vmcnt(0) lgkmcnt(0)
	v_pk_fma_f32 v[6:7], v[6:7], v[14:15], v[24:25]
	v_pk_fma_f32 v[8:9], v[8:9], v[16:17], v[26:27]
	v_cvt_pk_bf16_f32 v2, v2, v3
	v_cvt_pk_bf16_f32 v3, v4, v5
	v_cvt_pk_bf16_f32 v4, v6, v7
	v_cvt_pk_bf16_f32 v5, v8, v9
	global_store_dwordx4 v[18:19], v[2:5], off sc1
	s_cbranch_scc1 .LBB0_114

.LBB0_137:
	s_or_b64 exec, exec, s[20:21]
	s_movk_i32 s8, 0x4400
	v_mul_lo_u32 v4, v136, s8
	v_lshl_or_b32 v2, v138, 2, v4
	s_movk_i32 s8, 0x440
	v_mad_u32_u24 v2, v135, s8, v2
	v_add_u32_e32 v5, 0x1000, v2
	v_add_u32_e32 v6, 0x1400, v2
	s_waitcnt vmcnt(0) lgkmcnt(0)
	s_barrier
	ds_write2_b32 v2, v102, v90 offset1:16
	ds_write2_b32 v2, v103, v91 offset0:68 offset1:84
	ds_write2_b32 v2, v104, v92 offset0:136 offset1:152
	ds_write2_b32 v2, v105, v93 offset0:204 offset1:220
	ds_write2_b32 v2, v74, v94 offset0:32 offset1:48
	ds_write2_b32 v2, v75, v95 offset0:100 offset1:116
	ds_write2_b32 v2, v76, v96 offset0:168 offset1:184
	ds_write2_b32 v2, v77, v97 offset0:236 offset1:252
	ds_write2_b32 v5, v98, v78 offset0:64 offset1:80
	ds_write2_b32 v5, v99, v79 offset0:132 offset1:148
	ds_write2_b32 v5, v100, v80 offset0:200 offset1:216
	ds_write2_b32 v6, v101, v81 offset0:12 offset1:28
	ds_write2_b32 v5, v58, v82 offset0:96 offset1:112
	ds_write2_b32 v5, v59, v83 offset0:164 offset1:180
	ds_write2_b32 v5, v60, v84 offset0:232 offset1:248
	ds_write2_b32 v6, v61, v85 offset0:44 offset1:60
	v_add_u32_e32 v5, 0x2000, v2
	v_add_u32_e32 v6, 0x2400, v2
	ds_write2_b32 v5, v86, v62 offset0:128 offset1:144
	ds_write2_b32 v5, v87, v63 offset0:196 offset1:212
	ds_write2_b32 v6, v88, v64 offset0:8 offset1:24
	ds_write2_b32 v6, v89, v65 offset0:76 offset1:92
	ds_write2_b32 v5, v38, v66 offset0:160 offset1:176
	ds_write2_b32 v5, v39, v67 offset0:228 offset1:244
	ds_write2_b32 v6, v40, v68 offset0:40 offset1:56
	ds_write2_b32 v6, v41, v69 offset0:108 offset1:124
	v_add_u32_e32 v5, 0x3000, v2
	v_add_u32_e32 v2, 0x3400, v2
	v_readlane_b32 s8, v254, 46
	ds_write2_b32 v5, v70, v50 offset0:192 offset1:208
	ds_write2_b32 v2, v71, v51 offset0:4 offset1:20
	ds_write2_b32 v2, v72, v52 offset0:72 offset1:88
	ds_write2_b32 v2, v73, v53 offset0:140 offset1:156
	ds_write2_b32 v5, v30, v34 offset0:224 offset1:240
	ds_write2_b32 v2, v31, v35 offset0:36 offset1:52
	ds_write2_b32 v2, v32, v36 offset0:104 offset1:120
	ds_write2_b32 v2, v33, v37 offset0:172 offset1:188
	v_lshl_add_u32 v0, v0, 6, s8
	v_lshrrev_b32_e32 v5, 3, v134
	v_lshlrev_b32_e32 v2, 3, v134
	v_and_b32_e32 v6, 56, v2
	v_or_b32_e32 v2, v0, v5
	v_add_u32_e32 v0, 0xfffff000, v0
	v_lshlrev_b32_e32 v3, 6, v139
	v_readlane_b32 s8, v254, 47
	v_lshrrev_b32_e32 v9, 10, v0
	v_cmp_lt_i32_e32 vcc, s1, v2
	v_or3_b32 v12, v3, s8, v6
	v_mul_u32_u24_e32 v3, 0x110, v5
	v_lshlrev_b32_e32 v5, 2, v6
	v_cndmask_b32_e32 v0, 4, v9, vcc
	s_mul_i32 s8, s18, 5
	v_add3_u32 v8, v4, v3, v5
	v_add_u32_e32 v0, s8, v0
	v_mov_b64_e32 v[4:5], s[14:15]
	v_mad_i64_i32 v[6:7], s[20:21], v0, s82, v[4:5]
	v_lshlrev_b32_e32 v0, 2, v12
	v_ashrrev_i32_e32 v3, 31, v2
	v_lshl_add_u64 v[18:19], v[6:7], 0, v[0:1]
	v_lshlrev_b64 v[6:7], 11, v[2:3]
	v_lshl_add_u64 v[10:11], s[66:67], 0, v[6:7]
	v_lshlrev_b32_e32 v6, 1, v12
	v_mov_b32_e32 v7, v1
	v_lshl_add_u64 v[26:27], v[10:11], 0, v[6:7]
	s_mov_b64 s[22:23], 0x8605000
	v_lshl_add_u64 v[18:19], v[18:19], 0, s[22:23]
	global_load_dwordx4 v[36:39], v[18:19], off
	global_load_dwordx4 v[40:43], v[18:19], off offset:16
	global_load_dwordx4 v[44:47], v[26:27], off
	v_or_b32_e32 v10, 8, v2
	v_ashrrev_i32_e32 v11, 31, v10
	v_lshlrev_b64 v[10:11], 11, v[10:11]
	v_lshl_add_u64 v[10:11], s[66:67], 0, v[10:11]
	v_lshl_add_u64 v[102:103], v[10:11], 0, v[6:7]
	global_load_dwordx4 v[48:51], v[102:103], off
	v_or_b32_e32 v10, 16, v2
	v_ashrrev_i32_e32 v11, 31, v10
	v_lshlrev_b64 v[10:11], 11, v[10:11]
	v_lshl_add_u64 v[10:11], s[66:67], 0, v[10:11]
	v_lshl_add_u64 v[104:105], v[10:11], 0, v[6:7]
	global_load_dwordx4 v[52:55], v[104:105], off
	v_or_b32_e32 v10, 24, v2
	v_ashrrev_i32_e32 v11, 31, v10
	v_lshlrev_b64 v[10:11], 11, v[10:11]
	v_lshl_add_u64 v[10:11], s[66:67], 0, v[10:11]
	v_lshl_add_u64 v[106:107], v[10:11], 0, v[6:7]
	global_load_dwordx4 v[56:59], v[106:107], off
	v_or_b32_e32 v10, 32, v2
	v_ashrrev_i32_e32 v11, 31, v10
	v_lshlrev_b64 v[10:11], 11, v[10:11]
	v_lshl_add_u64 v[10:11], s[66:67], 0, v[10:11]
	v_lshl_add_u64 v[108:109], v[10:11], 0, v[6:7]
	global_load_dwordx4 v[60:63], v[108:109], off
	v_or_b32_e32 v10, 40, v2
	v_ashrrev_i32_e32 v11, 31, v10
	v_lshlrev_b64 v[10:11], 11, v[10:11]
	v_lshl_add_u64 v[10:11], s[66:67], 0, v[10:11]
	v_lshl_add_u64 v[110:111], v[10:11], 0, v[6:7]
	global_load_dwordx4 v[64:67], v[110:111], off
	v_or_b32_e32 v10, 48, v2
	v_ashrrev_i32_e32 v11, 31, v10
	v_lshlrev_b64 v[10:11], 11, v[10:11]
	v_lshl_add_u64 v[10:11], s[66:67], 0, v[10:11]
	v_lshl_add_u64 v[112:113], v[10:11], 0, v[6:7]
	global_load_dwordx4 v[68:71], v[112:113], off
	v_or_b32_e32 v10, 56, v2
	v_ashrrev_i32_e32 v11, 31, v10
	v_lshlrev_b64 v[10:11], 11, v[10:11]
	v_lshl_add_u64 v[10:11], s[66:67], 0, v[10:11]
	v_lshl_add_u64 v[114:115], v[10:11], 0, v[6:7]
	global_load_dwordx4 v[72:75], v[114:115], off
	ds_read_b128 v[84:87], v8
	ds_read_b128 v[88:91], v8 offset:16
	ds_read_b128 v[92:95], v8 offset:2176
	ds_read_b128 v[96:99], v8 offset:2192
	s_waitcnt vmcnt(7)
	v_lshlrev_b32_e32 v116, 16, v44
	v_and_b32_e32 v117, 0xffff0000, v44
	v_lshlrev_b32_e32 v118, 16, v45
	v_and_b32_e32 v119, 0xffff0000, v45
	v_lshlrev_b32_e32 v120, 16, v46
	v_and_b32_e32 v121, 0xffff0000, v46
	v_lshlrev_b32_e32 v122, 16, v47
	v_and_b32_e32 v123, 0xffff0000, v47
	s_waitcnt lgkmcnt(2)
	v_pk_fma_f32 v[116:117], v[84:85], v[36:37], v[116:117]
	v_pk_fma_f32 v[118:119], v[86:87], v[38:39], v[118:119]
	v_pk_fma_f32 v[120:121], v[88:89], v[40:41], v[120:121]
	v_pk_fma_f32 v[122:123], v[90:91], v[42:43], v[122:123]
	v_cvt_pk_bf16_f32 v132, v116, v117
	v_cvt_pk_bf16_f32 v133, v118, v119
	v_cvt_pk_bf16_f32 v134, v120, v121
	v_cvt_pk_bf16_f32 v135, v122, v123
	global_store_dwordx4 v[26:27], v[132:135], off sc1
	ds_read_b128 v[84:87], v8 offset:4352
	ds_read_b128 v[88:91], v8 offset:4368
	s_waitcnt vmcnt(7)
	v_lshlrev_b32_e32 v124, 16, v48
	v_and_b32_e32 v125, 0xffff0000, v48
	v_lshlrev_b32_e32 v126, 16, v49
	v_and_b32_e32 v127, 0xffff0000, v49
	v_lshlrev_b32_e32 v128, 16, v50
	v_and_b32_e32 v129, 0xffff0000, v50
	v_lshlrev_b32_e32 v130, 16, v51
	v_and_b32_e32 v131, 0xffff0000, v51
	s_waitcnt lgkmcnt(2)
	v_pk_fma_f32 v[124:125], v[92:93], v[36:37], v[124:125]
	v_pk_fma_f32 v[126:127], v[94:95], v[38:39], v[126:127]
	v_pk_fma_f32 v[128:129], v[96:97], v[40:41], v[128:129]
	v_pk_fma_f32 v[130:131], v[98:99], v[42:43], v[130:131]
	v_cvt_pk_bf16_f32 v136, v124, v125
	v_cvt_pk_bf16_f32 v137, v126, v127
	v_cvt_pk_bf16_f32 v138, v128, v129
	v_cvt_pk_bf16_f32 v139, v130, v131
	global_store_dwordx4 v[102:103], v[136:139], off sc1
	ds_read_b128 v[92:95], v8 offset:6528
	ds_read_b128 v[96:99], v8 offset:6544
	s_waitcnt vmcnt(7)
	v_lshlrev_b32_e32 v116, 16, v52
	v_and_b32_e32 v117, 0xffff0000, v52
	v_lshlrev_b32_e32 v118, 16, v53
	v_and_b32_e32 v119, 0xffff0000, v53
	v_lshlrev_b32_e32 v120, 16, v54
	v_and_b32_e32 v121, 0xffff0000, v54
	v_lshlrev_b32_e32 v122, 16, v55
	v_and_b32_e32 v123, 0xffff0000, v55
	s_waitcnt lgkmcnt(2)
	v_pk_fma_f32 v[116:117], v[84:85], v[36:37], v[116:117]
	v_pk_fma_f32 v[118:119], v[86:87], v[38:39], v[118:119]
	v_pk_fma_f32 v[120:121], v[88:89], v[40:41], v[120:121]
	v_pk_fma_f32 v[122:123], v[90:91], v[42:43], v[122:123]
	v_cvt_pk_bf16_f32 v132, v116, v117
	v_cvt_pk_bf16_f32 v133, v118, v119
	v_cvt_pk_bf16_f32 v134, v120, v121
	v_cvt_pk_bf16_f32 v135, v122, v123
	global_store_dwordx4 v[104:105], v[132:135], off sc1
	ds_read_b128 v[84:87], v8 offset:8704
	ds_read_b128 v[88:91], v8 offset:8720
	s_waitcnt vmcnt(7)
	v_lshlrev_b32_e32 v124, 16, v56
	v_and_b32_e32 v125, 0xffff0000, v56
	v_lshlrev_b32_e32 v126, 16, v57
	v_and_b32_e32 v127, 0xffff0000, v57
	v_lshlrev_b32_e32 v128, 16, v58
	v_and_b32_e32 v129, 0xffff0000, v58
	v_lshlrev_b32_e32 v130, 16, v59
	v_and_b32_e32 v131, 0xffff0000, v59
	s_waitcnt lgkmcnt(2)
	v_pk_fma_f32 v[124:125], v[92:93], v[36:37], v[124:125]
	v_pk_fma_f32 v[126:127], v[94:95], v[38:39], v[126:127]
	v_pk_fma_f32 v[128:129], v[96:97], v[40:41], v[128:129]
	v_pk_fma_f32 v[130:131], v[98:99], v[42:43], v[130:131]
	v_cvt_pk_bf16_f32 v136, v124, v125
	v_cvt_pk_bf16_f32 v137, v126, v127
	v_cvt_pk_bf16_f32 v138, v128, v129
	v_cvt_pk_bf16_f32 v139, v130, v131
	global_store_dwordx4 v[106:107], v[136:139], off sc1
	ds_read_b128 v[92:95], v8 offset:10880
	ds_read_b128 v[96:99], v8 offset:10896
	s_waitcnt vmcnt(7)
	v_lshlrev_b32_e32 v116, 16, v60
	v_and_b32_e32 v117, 0xffff0000, v60
	v_lshlrev_b32_e32 v118, 16, v61
	v_and_b32_e32 v119, 0xffff0000, v61
	v_lshlrev_b32_e32 v120, 16, v62
	v_and_b32_e32 v121, 0xffff0000, v62
	v_lshlrev_b32_e32 v122, 16, v63
	v_and_b32_e32 v123, 0xffff0000, v63
	s_waitcnt lgkmcnt(2)
	v_pk_fma_f32 v[116:117], v[84:85], v[36:37], v[116:117]
	v_pk_fma_f32 v[118:119], v[86:87], v[38:39], v[118:119]
	v_pk_fma_f32 v[120:121], v[88:89], v[40:41], v[120:121]
	v_pk_fma_f32 v[122:123], v[90:91], v[42:43], v[122:123]
	v_cvt_pk_bf16_f32 v132, v116, v117
	v_cvt_pk_bf16_f32 v133, v118, v119
	v_cvt_pk_bf16_f32 v134, v120, v121
	v_cvt_pk_bf16_f32 v135, v122, v123
	global_store_dwordx4 v[108:109], v[132:135], off sc1
	ds_read_b128 v[84:87], v8 offset:13056
	ds_read_b128 v[88:91], v8 offset:13072
	s_waitcnt vmcnt(7)
	v_lshlrev_b32_e32 v124, 16, v64
	v_and_b32_e32 v125, 0xffff0000, v64
	v_lshlrev_b32_e32 v126, 16, v65
	v_and_b32_e32 v127, 0xffff0000, v65
	v_lshlrev_b32_e32 v128, 16, v66
	v_and_b32_e32 v129, 0xffff0000, v66
	v_lshlrev_b32_e32 v130, 16, v67
	v_and_b32_e32 v131, 0xffff0000, v67
	s_waitcnt lgkmcnt(2)
	v_pk_fma_f32 v[124:125], v[92:93], v[36:37], v[124:125]
	v_pk_fma_f32 v[126:127], v[94:95], v[38:39], v[126:127]
	v_pk_fma_f32 v[128:129], v[96:97], v[40:41], v[128:129]
	v_pk_fma_f32 v[130:131], v[98:99], v[42:43], v[130:131]
	v_cvt_pk_bf16_f32 v136, v124, v125
	v_cvt_pk_bf16_f32 v137, v126, v127
	v_cvt_pk_bf16_f32 v138, v128, v129
	v_cvt_pk_bf16_f32 v139, v130, v131
	global_store_dwordx4 v[110:111], v[136:139], off sc1
	ds_read_b128 v[92:95], v8 offset:15232
	ds_read_b128 v[96:99], v8 offset:15248
	s_waitcnt vmcnt(7)
	v_lshlrev_b32_e32 v116, 16, v68
	v_and_b32_e32 v117, 0xffff0000, v68
	v_lshlrev_b32_e32 v118, 16, v69
	v_and_b32_e32 v119, 0xffff0000, v69
	v_lshlrev_b32_e32 v120, 16, v70
	v_and_b32_e32 v121, 0xffff0000, v70
	v_lshlrev_b32_e32 v122, 16, v71
	v_and_b32_e32 v123, 0xffff0000, v71
	s_waitcnt lgkmcnt(2)
	v_pk_fma_f32 v[116:117], v[84:85], v[36:37], v[116:117]
	v_pk_fma_f32 v[118:119], v[86:87], v[38:39], v[118:119]
	v_pk_fma_f32 v[120:121], v[88:89], v[40:41], v[120:121]
	v_pk_fma_f32 v[122:123], v[90:91], v[42:43], v[122:123]
	v_cvt_pk_bf16_f32 v132, v116, v117
	v_cvt_pk_bf16_f32 v133, v118, v119
	v_cvt_pk_bf16_f32 v134, v120, v121
	v_cvt_pk_bf16_f32 v135, v122, v123
	global_store_dwordx4 v[112:113], v[132:135], off sc1
	s_waitcnt vmcnt(7)
	v_lshlrev_b32_e32 v124, 16, v72
	v_and_b32_e32 v125, 0xffff0000, v72
	v_lshlrev_b32_e32 v126, 16, v73
	v_and_b32_e32 v127, 0xffff0000, v73
	v_lshlrev_b32_e32 v128, 16, v74
	v_and_b32_e32 v129, 0xffff0000, v74
	v_lshlrev_b32_e32 v130, 16, v75
	v_and_b32_e32 v131, 0xffff0000, v75
	s_waitcnt lgkmcnt(0)
	v_pk_fma_f32 v[124:125], v[92:93], v[36:37], v[124:125]
	v_pk_fma_f32 v[126:127], v[94:95], v[38:39], v[126:127]
	v_pk_fma_f32 v[128:129], v[96:97], v[40:41], v[128:129]
	v_pk_fma_f32 v[130:131], v[98:99], v[42:43], v[130:131]
	v_cvt_pk_bf16_f32 v136, v124, v125
	v_cvt_pk_bf16_f32 v137, v126, v127
	v_cvt_pk_bf16_f32 v138, v128, v129
	v_cvt_pk_bf16_f32 v139, v130, v131
	global_store_dwordx4 v[114:115], v[136:139], off sc1

.LBB0_143:
	s_or_b64 exec, exec, s[20:21]
	v_mul_f32_e32 v124, 0xbfb8aa3b, v158
	v_mul_f32_e32 v128, 0xbfb8aa3b, v118
	v_exp_f32_e32 v124, v124
	v_exp_f32_e32 v128, v128
	s_movk_i32 s20, 0x4400
	v_mul_lo_u32 v122, v197, s20
	v_add_f32_e32 v124, 1.0, v124
	v_add_f32_e32 v128, 1.0, v128
	v_rcp_f32_e32 v124, v124
	v_rcp_f32_e32 v128, v128
	v_lshl_or_b32 v123, v199, 2, v122
	s_movk_i32 s20, 0x440
	v_mul_f32_e32 v124, v158, v124
	v_mul_f32_e32 v118, v118, v128
	v_mul_f32_e32 v124, v124, v154
	v_mad_u32_u24 v123, v196, s20, v123
	v_mul_f32_e32 v114, v118, v114
	s_waitcnt vmcnt(0) lgkmcnt(0)
	s_barrier
	v_mul_f32_e32 v125, 0xbfb8aa3b, v159
	ds_write2_b32 v123, v124, v114 offset1:16
	v_mul_f32_e32 v114, 0xbfb8aa3b, v119
	v_exp_f32_e32 v125, v125
	v_exp_f32_e32 v114, v114
	v_mul_f32_e32 v126, 0xbfb8aa3b, v160
	v_exp_f32_e32 v126, v126
	v_add_f32_e32 v125, 1.0, v125
	v_add_f32_e32 v114, 1.0, v114
	v_rcp_f32_e32 v125, v125
	v_rcp_f32_e32 v114, v114
	v_add_f32_e32 v126, 1.0, v126
	v_rcp_f32_e32 v126, v126
	v_mul_f32_e32 v125, v159, v125
	v_mul_f32_e32 v114, v119, v114
	v_mul_f32_e32 v125, v125, v155
	v_mul_f32_e32 v114, v114, v115
	ds_write2_b32 v123, v125, v114 offset0:68 offset1:84
	v_mul_f32_e32 v114, 0xbfb8aa3b, v120
	v_exp_f32_e32 v114, v114
	v_mul_f32_e32 v126, v160, v126
	v_mul_f32_e32 v126, v126, v156
	v_mul_f32_e32 v127, 0xbfb8aa3b, v161
	v_add_f32_e32 v114, 1.0, v114
	v_rcp_f32_e32 v114, v114
	v_exp_f32_e32 v127, v127
	s_lshl_b32 s17, s17, 7
	v_lshl_add_u32 v0, v0, 6, s19
	v_mul_f32_e32 v114, v120, v114
	v_mul_f32_e32 v114, v114, v116
	ds_write2_b32 v123, v126, v114 offset0:136 offset1:152
	v_mul_f32_e32 v114, 0xbfb8aa3b, v121
	v_exp_f32_e32 v114, v114
	v_add_f32_e32 v127, 1.0, v127
	v_rcp_f32_e32 v127, v127
	s_add_i32 s8, s8, s64
	v_add_f32_e32 v114, 1.0, v114
	v_rcp_f32_e32 v114, v114
	v_mul_f32_e32 v127, v161, v127
	v_mul_f32_e32 v127, v127, v157
	s_cmpk_gt_i32 s8, 0x2bf
	v_mul_f32_e32 v114, v121, v114
	v_mul_f32_e32 v114, v114, v117
	ds_write2_b32 v123, v127, v114 offset0:204 offset1:220
	v_mul_f32_e32 v114, 0xbfb8aa3b, v110
	v_exp_f32_e32 v114, v114
	s_nop 0
	v_add_f32_e32 v114, 1.0, v114
	v_rcp_f32_e32 v114, v114
	s_nop 0
	v_mul_f32_e32 v110, v110, v114
	v_mul_f32_e32 v106, v110, v106
	v_mul_f32_e32 v110, 0xbfb8aa3b, v111
	v_exp_f32_e32 v110, v110
	s_nop 0
	v_add_f32_e32 v110, 1.0, v110
	v_rcp_f32_e32 v110, v110
	s_nop 0
	v_mul_f32_e32 v110, v111, v110
	v_mul_f32_e32 v107, v110, v107
	v_mul_f32_e32 v110, 0xbfb8aa3b, v112
	v_exp_f32_e32 v110, v110
	s_nop 0
	v_add_f32_e32 v110, 1.0, v110
	v_rcp_f32_e32 v110, v110
	s_nop 0
	v_mul_f32_e32 v110, v112, v110
	v_mul_f32_e32 v108, v110, v108
	v_mul_f32_e32 v110, 0xbfb8aa3b, v113
	v_exp_f32_e32 v110, v110
	s_nop 0
	v_add_f32_e32 v110, 1.0, v110
	v_rcp_f32_e32 v110, v110
	s_nop 0
	v_mul_f32_e32 v110, v113, v110
	v_mul_f32_e32 v109, v110, v109
	v_mul_f32_e32 v110, 0xbfb8aa3b, v102
	v_exp_f32_e32 v110, v110
	s_nop 0
	v_add_f32_e32 v110, 1.0, v110
	v_rcp_f32_e32 v110, v110
	s_nop 0
	v_mul_f32_e32 v102, v102, v110
	v_mul_f32_e32 v98, v102, v98
	ds_write2_b32 v123, v106, v98 offset0:32 offset1:48
	v_mul_f32_e32 v98, 0xbfb8aa3b, v103
	v_exp_f32_e32 v98, v98
	s_nop 0
	v_add_f32_e32 v98, 1.0, v98
	v_rcp_f32_e32 v98, v98
	s_nop 0
	v_mul_f32_e32 v98, v103, v98
	v_mul_f32_e32 v98, v98, v99
	ds_write2_b32 v123, v107, v98 offset0:100 offset1:116
	v_mul_f32_e32 v98, 0xbfb8aa3b, v104
	v_exp_f32_e32 v98, v98
	s_nop 0
	v_add_f32_e32 v98, 1.0, v98
	v_rcp_f32_e32 v98, v98
	s_nop 0
	v_mul_f32_e32 v98, v104, v98
	v_mul_f32_e32 v98, v98, v100
	ds_write2_b32 v123, v108, v98 offset0:168 offset1:184
	v_mul_f32_e32 v98, 0xbfb8aa3b, v105
	v_exp_f32_e32 v98, v98
	s_nop 0
	v_add_f32_e32 v98, 1.0, v98
	v_rcp_f32_e32 v98, v98
	s_nop 0
	v_mul_f32_e32 v98, v105, v98
	v_mul_f32_e32 v98, v98, v101
	ds_write2_b32 v123, v109, v98 offset0:236 offset1:252
	v_mul_f32_e32 v98, 0xbfb8aa3b, v94
	v_exp_f32_e32 v98, v98
	s_nop 0
	v_add_f32_e32 v98, 1.0, v98
	v_rcp_f32_e32 v98, v98
	s_nop 0
	v_mul_f32_e32 v94, v94, v98
	v_mul_f32_e32 v90, v94, v90
	v_mul_f32_e32 v94, 0xbfb8aa3b, v95
	v_exp_f32_e32 v94, v94
	s_nop 0
	v_add_f32_e32 v94, 1.0, v94
	v_rcp_f32_e32 v94, v94
	s_nop 0
	v_mul_f32_e32 v94, v95, v94
	v_mul_f32_e32 v91, v94, v91
	v_mul_f32_e32 v94, 0xbfb8aa3b, v96
	v_exp_f32_e32 v94, v94
	s_nop 0
	v_add_f32_e32 v94, 1.0, v94
	v_rcp_f32_e32 v94, v94
	s_nop 0
	v_mul_f32_e32 v94, v96, v94
	v_mul_f32_e32 v92, v94, v92
	v_mul_f32_e32 v94, 0xbfb8aa3b, v97
	v_exp_f32_e32 v94, v94
	s_nop 0
	v_add_f32_e32 v94, 1.0, v94
	v_rcp_f32_e32 v94, v94
	s_nop 0
	v_mul_f32_e32 v94, v97, v94
	v_mul_f32_e32 v93, v94, v93
	v_mul_f32_e32 v94, 0xbfb8aa3b, v86
	v_exp_f32_e32 v94, v94
	s_nop 0
	v_add_f32_e32 v94, 1.0, v94
	v_rcp_f32_e32 v94, v94
	s_nop 0
	v_mul_f32_e32 v86, v86, v94
	v_mul_f32_e32 v82, v86, v82
	v_add_u32_e32 v86, 0x1000, v123
	ds_write2_b32 v86, v90, v82 offset0:64 offset1:80
	v_mul_f32_e32 v82, 0xbfb8aa3b, v87
	v_exp_f32_e32 v82, v82
	s_nop 0
	v_add_f32_e32 v82, 1.0, v82
	v_rcp_f32_e32 v82, v82
	s_nop 0
	v_mul_f32_e32 v82, v87, v82
	v_mul_f32_e32 v82, v82, v83
	ds_write2_b32 v86, v91, v82 offset0:132 offset1:148
	v_mul_f32_e32 v82, 0xbfb8aa3b, v88
	v_exp_f32_e32 v82, v82
	v_add_u32_e32 v83, 0x1400, v123
	v_add_f32_e32 v82, 1.0, v82
	v_rcp_f32_e32 v82, v82
	s_nop 0
	v_mul_f32_e32 v82, v88, v82
	v_mul_f32_e32 v82, v82, v84
	ds_write2_b32 v86, v92, v82 offset0:200 offset1:216
	v_mul_f32_e32 v82, 0xbfb8aa3b, v89
	v_exp_f32_e32 v82, v82
	s_nop 0
	v_add_f32_e32 v82, 1.0, v82
	v_rcp_f32_e32 v82, v82
	s_nop 0
	v_mul_f32_e32 v82, v89, v82
	v_mul_f32_e32 v82, v82, v85
	ds_write2_b32 v83, v93, v82 offset0:12 offset1:28
	v_mul_f32_e32 v82, 0xbfb8aa3b, v78
	v_exp_f32_e32 v82, v82
	s_nop 0
	v_add_f32_e32 v82, 1.0, v82
	v_rcp_f32_e32 v82, v82
	s_nop 0
	v_mul_f32_e32 v78, v78, v82
	v_mul_f32_e32 v74, v78, v74
	v_mul_f32_e32 v78, 0xbfb8aa3b, v79
	v_exp_f32_e32 v78, v78
	s_nop 0
	v_add_f32_e32 v78, 1.0, v78
	v_rcp_f32_e32 v78, v78
	s_nop 0
	v_mul_f32_e32 v78, v79, v78
	v_mul_f32_e32 v75, v78, v75
	v_mul_f32_e32 v78, 0xbfb8aa3b, v80
	v_exp_f32_e32 v78, v78
	s_nop 0
	v_add_f32_e32 v78, 1.0, v78
	v_rcp_f32_e32 v78, v78
	s_nop 0
	v_mul_f32_e32 v78, v80, v78
	v_mul_f32_e32 v76, v78, v76
	v_mul_f32_e32 v78, 0xbfb8aa3b, v81
	v_exp_f32_e32 v78, v78
	s_nop 0
	v_add_f32_e32 v78, 1.0, v78
	v_rcp_f32_e32 v78, v78
	s_nop 0
	v_mul_f32_e32 v78, v81, v78
	v_mul_f32_e32 v77, v78, v77
	v_mul_f32_e32 v78, 0xbfb8aa3b, v70
	v_exp_f32_e32 v78, v78
	s_nop 0
	v_add_f32_e32 v78, 1.0, v78
	v_rcp_f32_e32 v78, v78
	s_nop 0
	v_mul_f32_e32 v70, v70, v78
	v_mul_f32_e32 v66, v70, v66
	ds_write2_b32 v86, v74, v66 offset0:96 offset1:112
	v_mul_f32_e32 v66, 0xbfb8aa3b, v71
	v_exp_f32_e32 v66, v66
	s_nop 0
	v_add_f32_e32 v66, 1.0, v66
	v_rcp_f32_e32 v66, v66
	s_nop 0
	v_mul_f32_e32 v66, v71, v66
	v_mul_f32_e32 v66, v66, v67
	ds_write2_b32 v86, v75, v66 offset0:164 offset1:180
	v_mul_f32_e32 v66, 0xbfb8aa3b, v72
	v_exp_f32_e32 v66, v66
	s_nop 0
	v_add_f32_e32 v66, 1.0, v66
	v_rcp_f32_e32 v66, v66
	s_nop 0
	v_mul_f32_e32 v66, v72, v66
	v_mul_f32_e32 v66, v66, v68
	ds_write2_b32 v86, v76, v66 offset0:232 offset1:248
	v_mul_f32_e32 v66, 0xbfb8aa3b, v73
	v_exp_f32_e32 v66, v66
	s_nop 0
	v_add_f32_e32 v66, 1.0, v66
	v_rcp_f32_e32 v66, v66
	s_nop 0
	v_mul_f32_e32 v66, v73, v66
	v_mul_f32_e32 v66, v66, v69
	ds_write2_b32 v83, v77, v66 offset0:44 offset1:60
	v_mul_f32_e32 v66, 0xbfb8aa3b, v62
	v_exp_f32_e32 v66, v66
	s_nop 0
	v_add_f32_e32 v66, 1.0, v66
	v_rcp_f32_e32 v66, v66
	s_nop 0
	v_mul_f32_e32 v62, v62, v66
	v_mul_f32_e32 v58, v62, v58
	v_mul_f32_e32 v62, 0xbfb8aa3b, v63
	v_exp_f32_e32 v62, v62
	s_nop 0
	v_add_f32_e32 v62, 1.0, v62
	v_rcp_f32_e32 v62, v62
	s_nop 0
	v_mul_f32_e32 v62, v63, v62
	v_mul_f32_e32 v59, v62, v59
	v_mul_f32_e32 v62, 0xbfb8aa3b, v64
	v_exp_f32_e32 v62, v62
	s_nop 0
	v_add_f32_e32 v62, 1.0, v62
	v_rcp_f32_e32 v62, v62
	s_nop 0
	v_mul_f32_e32 v62, v64, v62
	v_mul_f32_e32 v60, v62, v60
	v_mul_f32_e32 v62, 0xbfb8aa3b, v65
	v_exp_f32_e32 v62, v62
	s_nop 0
	v_add_f32_e32 v62, 1.0, v62
	v_rcp_f32_e32 v62, v62
	s_nop 0
	v_mul_f32_e32 v62, v65, v62
	v_mul_f32_e32 v61, v62, v61
	v_mul_f32_e32 v62, 0xbfb8aa3b, v54
	v_exp_f32_e32 v62, v62
	s_nop 0
	v_add_f32_e32 v62, 1.0, v62
	v_rcp_f32_e32 v62, v62
	s_nop 0
	v_mul_f32_e32 v54, v54, v62
	v_mul_f32_e32 v50, v54, v50
	v_add_u32_e32 v54, 0x2000, v123
	ds_write2_b32 v54, v58, v50 offset0:128 offset1:144
	v_mul_f32_e32 v50, 0xbfb8aa3b, v55
	v_exp_f32_e32 v50, v50
	s_nop 0
	v_add_f32_e32 v50, 1.0, v50
	v_rcp_f32_e32 v50, v50
	s_nop 0
	v_mul_f32_e32 v50, v55, v50
	v_mul_f32_e32 v50, v50, v51
	ds_write2_b32 v54, v59, v50 offset0:196 offset1:212
	v_mul_f32_e32 v50, 0xbfb8aa3b, v56
	v_exp_f32_e32 v50, v50
	v_add_u32_e32 v51, 0x2400, v123
	v_add_f32_e32 v50, 1.0, v50
	v_rcp_f32_e32 v50, v50
	s_nop 0
	v_mul_f32_e32 v50, v56, v50
	v_mul_f32_e32 v50, v50, v52
	ds_write2_b32 v51, v60, v50 offset0:8 offset1:24
	v_mul_f32_e32 v50, 0xbfb8aa3b, v57
	v_exp_f32_e32 v50, v50
	s_nop 0
	v_add_f32_e32 v50, 1.0, v50
	v_rcp_f32_e32 v50, v50
	s_nop 0
	v_mul_f32_e32 v50, v57, v50
	v_mul_f32_e32 v50, v50, v53
	ds_write2_b32 v51, v61, v50 offset0:76 offset1:92
	v_mul_f32_e32 v50, 0xbfb8aa3b, v46
	v_exp_f32_e32 v50, v50
	s_nop 0
	v_add_f32_e32 v50, 1.0, v50
	v_rcp_f32_e32 v50, v50
	s_nop 0
	v_mul_f32_e32 v46, v46, v50
	v_mul_f32_e32 v42, v46, v42
	v_mul_f32_e32 v46, 0xbfb8aa3b, v47
	v_exp_f32_e32 v46, v46
	s_nop 0
	v_add_f32_e32 v46, 1.0, v46
	v_rcp_f32_e32 v46, v46
	s_nop 0
	v_mul_f32_e32 v46, v47, v46
	v_mul_f32_e32 v43, v46, v43
	v_mul_f32_e32 v46, 0xbfb8aa3b, v48
	v_exp_f32_e32 v46, v46
	s_nop 0
	v_add_f32_e32 v46, 1.0, v46
	v_rcp_f32_e32 v46, v46
	s_nop 0
	v_mul_f32_e32 v46, v48, v46
	v_mul_f32_e32 v44, v46, v44
	v_mul_f32_e32 v46, 0xbfb8aa3b, v49
	v_exp_f32_e32 v46, v46
	s_nop 0
	v_add_f32_e32 v46, 1.0, v46
	v_rcp_f32_e32 v46, v46
	s_nop 0
	v_mul_f32_e32 v46, v49, v46
	v_mul_f32_e32 v45, v46, v45
	v_mul_f32_e32 v46, 0xbfb8aa3b, v38
	v_exp_f32_e32 v46, v46
	s_nop 0
	v_add_f32_e32 v46, 1.0, v46
	v_rcp_f32_e32 v46, v46
	s_nop 0
	v_mul_f32_e32 v38, v38, v46
	v_mul_f32_e32 v34, v38, v34
	ds_write2_b32 v54, v42, v34 offset0:160 offset1:176
	v_mul_f32_e32 v34, 0xbfb8aa3b, v39
	v_exp_f32_e32 v34, v34
	s_nop 0
	v_add_f32_e32 v34, 1.0, v34
	v_rcp_f32_e32 v34, v34
	s_nop 0
	v_mul_f32_e32 v34, v39, v34
	v_mul_f32_e32 v34, v34, v35
	ds_write2_b32 v54, v43, v34 offset0:228 offset1:244
	v_mul_f32_e32 v34, 0xbfb8aa3b, v40
	v_exp_f32_e32 v34, v34
	s_nop 0
	v_add_f32_e32 v34, 1.0, v34
	v_rcp_f32_e32 v34, v34
	s_nop 0
	v_mul_f32_e32 v34, v40, v34
	v_mul_f32_e32 v34, v34, v36
	ds_write2_b32 v51, v44, v34 offset0:40 offset1:56
	v_mul_f32_e32 v34, 0xbfb8aa3b, v41
	v_exp_f32_e32 v34, v34
	s_nop 0
	v_add_f32_e32 v34, 1.0, v34
	v_rcp_f32_e32 v34, v34
	s_nop 0
	v_mul_f32_e32 v34, v41, v34
	v_mul_f32_e32 v34, v34, v37
	ds_write2_b32 v51, v45, v34 offset0:108 offset1:124
	v_mul_f32_e32 v34, 0xbfb8aa3b, v30
	v_exp_f32_e32 v34, v34
	s_nop 0
	v_add_f32_e32 v34, 1.0, v34
	v_rcp_f32_e32 v34, v34
	s_nop 0
	v_mul_f32_e32 v30, v30, v34
	v_mul_f32_e32 v26, v30, v26
	v_mul_f32_e32 v30, 0xbfb8aa3b, v31
	v_exp_f32_e32 v30, v30
	s_nop 0
	v_add_f32_e32 v30, 1.0, v30
	v_rcp_f32_e32 v30, v30
	s_nop 0
	v_mul_f32_e32 v30, v31, v30
	v_mul_f32_e32 v27, v30, v27
	v_mul_f32_e32 v30, 0xbfb8aa3b, v32
	v_exp_f32_e32 v30, v30
	s_nop 0
	v_add_f32_e32 v30, 1.0, v30
	v_rcp_f32_e32 v30, v30
	s_nop 0
	v_mul_f32_e32 v30, v32, v30
	v_mul_f32_e32 v28, v30, v28
	v_mul_f32_e32 v30, 0xbfb8aa3b, v33
	v_exp_f32_e32 v30, v30
	s_nop 0
	v_add_f32_e32 v30, 1.0, v30
	v_rcp_f32_e32 v30, v30
	s_nop 0
	v_mul_f32_e32 v30, v33, v30
	v_mul_f32_e32 v29, v30, v29
	v_mul_f32_e32 v30, 0xbfb8aa3b, v22
	v_exp_f32_e32 v30, v30
	s_nop 0
	v_add_f32_e32 v30, 1.0, v30
	v_rcp_f32_e32 v30, v30
	s_nop 0
	v_mul_f32_e32 v22, v22, v30
	v_mul_f32_e32 v18, v22, v18
	v_add_u32_e32 v22, 0x3000, v123
	ds_write2_b32 v22, v26, v18 offset0:192 offset1:208
	v_mul_f32_e32 v18, 0xbfb8aa3b, v23
	v_exp_f32_e32 v18, v18
	s_nop 0
	v_add_f32_e32 v18, 1.0, v18
	v_rcp_f32_e32 v18, v18
	s_nop 0
	v_mul_f32_e32 v18, v23, v18
	v_mul_f32_e32 v18, v18, v19
	v_add_u32_e32 v19, 0x3400, v123
	ds_write2_b32 v19, v27, v18 offset0:4 offset1:20
	v_mul_f32_e32 v18, 0xbfb8aa3b, v24
	v_exp_f32_e32 v18, v18
	s_nop 0
	v_add_f32_e32 v18, 1.0, v18
	v_rcp_f32_e32 v18, v18
	s_nop 0
	v_mul_f32_e32 v18, v24, v18
	v_mul_f32_e32 v18, v18, v20
	ds_write2_b32 v19, v28, v18 offset0:72 offset1:88
	v_mul_f32_e32 v18, 0xbfb8aa3b, v25
	v_exp_f32_e32 v18, v18
	s_nop 0
	v_add_f32_e32 v18, 1.0, v18
	v_rcp_f32_e32 v18, v18
	s_nop 0
	v_mul_f32_e32 v18, v25, v18
	v_mul_f32_e32 v18, v18, v21
	ds_write2_b32 v19, v29, v18 offset0:140 offset1:156
	v_mul_f32_e32 v18, 0xbfb8aa3b, v14
	v_exp_f32_e32 v18, v18
	s_nop 0
	v_add_f32_e32 v18, 1.0, v18
	v_rcp_f32_e32 v18, v18
	s_nop 0
	v_mul_f32_e32 v14, v14, v18
	v_mul_f32_e32 v10, v14, v10
	v_mul_f32_e32 v14, 0xbfb8aa3b, v15
	v_exp_f32_e32 v14, v14
	s_nop 0
	v_add_f32_e32 v14, 1.0, v14
	v_rcp_f32_e32 v14, v14
	s_nop 0
	v_mul_f32_e32 v14, v15, v14
	v_mul_f32_e32 v11, v14, v11
	v_mul_f32_e32 v14, 0xbfb8aa3b, v16
	v_exp_f32_e32 v14, v14
	s_nop 0
	v_add_f32_e32 v14, 1.0, v14
	v_rcp_f32_e32 v14, v14
	s_nop 0
	v_mul_f32_e32 v14, v16, v14
	v_mul_f32_e32 v12, v14, v12
	v_mul_f32_e32 v14, 0xbfb8aa3b, v17
	v_exp_f32_e32 v14, v14
	s_nop 0
	v_add_f32_e32 v14, 1.0, v14
	v_rcp_f32_e32 v14, v14
	s_nop 0
	v_mul_f32_e32 v14, v17, v14
	v_mul_f32_e32 v13, v14, v13
	v_mul_f32_e32 v14, 0xbfb8aa3b, v6
	v_exp_f32_e32 v14, v14
	s_nop 0
	v_add_f32_e32 v14, 1.0, v14
	v_rcp_f32_e32 v14, v14
	s_nop 0
	v_mul_f32_e32 v6, v6, v14
	v_mul_f32_e32 v2, v6, v2
	ds_write2_b32 v22, v10, v2 offset0:224 offset1:240
	v_mul_f32_e32 v2, 0xbfb8aa3b, v7
	v_exp_f32_e32 v2, v2
	s_nop 0
	v_add_f32_e32 v2, 1.0, v2
	v_rcp_f32_e32 v2, v2
	s_nop 0
	v_mul_f32_e32 v2, v7, v2
	v_mul_f32_e32 v2, v2, v3
	ds_write2_b32 v19, v11, v2 offset0:36 offset1:52
	v_mul_f32_e32 v2, 0xbfb8aa3b, v8
	v_exp_f32_e32 v2, v2
	s_nop 0
	v_add_f32_e32 v2, 1.0, v2
	v_rcp_f32_e32 v2, v2
	s_nop 0
	v_mul_f32_e32 v2, v8, v2
	v_mul_f32_e32 v2, v2, v4
	ds_write2_b32 v19, v12, v2 offset0:104 offset1:120
	v_mul_f32_e32 v2, 0xbfb8aa3b, v9
	v_exp_f32_e32 v2, v2
	v_lshlrev_b32_e32 v4, 3, v194
	v_lshrrev_b32_e32 v12, 3, v194
	v_add_f32_e32 v2, 1.0, v2
	v_rcp_f32_e32 v2, v2
	s_nop 0
	v_mul_f32_e32 v2, v9, v2
	v_mul_f32_e32 v2, v2, v5
	ds_write2_b32 v19, v13, v2 offset0:172 offset1:188
	v_and_b32_e32 v13, 56, v4
	v_mul_u32_u24_e32 v4, 0x110, v12
	v_lshlrev_b32_e32 v5, 2, v13
	v_add3_u32 v14, v122, v4, v5
	ds_read_b128 v[4:7], v14
	ds_read_b128 v[8:11], v14 offset:16
	v_lshl_or_b32 v2, v195, 6, s17
	v_ashrrev_i32_e32 v3, 31, v2
	v_lshl_add_u64 v[2:3], v[2:3], 1, s[46:47]
	v_or_b32_e32 v12, v0, v12
	s_waitcnt lgkmcnt(1)
	v_cvt_pk_bf16_f32 v4, v4, v5
	v_cvt_pk_bf16_f32 v5, v6, v7
	s_waitcnt lgkmcnt(0)
	v_cvt_pk_bf16_f32 v6, v8, v9
	v_mad_i64_i32 v[8:9], s[20:21], v12, s5, v[2:3]
	v_lshlrev_b32_e32 v0, 1, v13
	v_cvt_pk_bf16_f32 v7, v10, v11
	v_lshl_add_u64 v[8:9], v[8:9], 0, v[0:1]
	global_store_dwordx4 v[8:9], v[4:7], off sc1
	ds_read_b128 v[4:7], v14 offset:2176
	ds_read_b128 v[8:11], v14 offset:2192
	s_waitcnt lgkmcnt(1)
	v_cvt_pk_bf16_f32 v4, v4, v5
	v_cvt_pk_bf16_f32 v5, v6, v7
	s_waitcnt lgkmcnt(0)
	v_cvt_pk_bf16_f32 v6, v8, v9
	v_or_b32_e32 v8, 8, v12
	v_mad_i64_i32 v[8:9], s[20:21], v8, s5, v[2:3]
	v_cvt_pk_bf16_f32 v7, v10, v11
	v_lshl_add_u64 v[8:9], v[8:9], 0, v[0:1]
	global_store_dwordx4 v[8:9], v[4:7], off sc1
	ds_read_b128 v[4:7], v14 offset:4352
	ds_read_b128 v[8:11], v14 offset:4368
	s_waitcnt lgkmcnt(1)
	v_cvt_pk_bf16_f32 v4, v4, v5
	v_cvt_pk_bf16_f32 v5, v6, v7
	s_waitcnt lgkmcnt(0)
	v_cvt_pk_bf16_f32 v6, v8, v9
	v_or_b32_e32 v8, 16, v12
	v_mad_i64_i32 v[8:9], s[20:21], v8, s5, v[2:3]
	v_cvt_pk_bf16_f32 v7, v10, v11
	v_lshl_add_u64 v[8:9], v[8:9], 0, v[0:1]
	global_store_dwordx4 v[8:9], v[4:7], off sc1
	ds_read_b128 v[4:7], v14 offset:6528
	ds_read_b128 v[8:11], v14 offset:6544
	s_waitcnt lgkmcnt(1)
	v_cvt_pk_bf16_f32 v4, v4, v5
	v_cvt_pk_bf16_f32 v5, v6, v7
	s_waitcnt lgkmcnt(0)
	v_cvt_pk_bf16_f32 v6, v8, v9
	v_or_b32_e32 v8, 24, v12
	v_mad_i64_i32 v[8:9], s[20:21], v8, s5, v[2:3]
	v_cvt_pk_bf16_f32 v7, v10, v11
	v_lshl_add_u64 v[8:9], v[8:9], 0, v[0:1]
	global_store_dwordx4 v[8:9], v[4:7], off sc1
	ds_read_b128 v[4:7], v14 offset:8704
	ds_read_b128 v[8:11], v14 offset:8720
	s_waitcnt lgkmcnt(1)
	v_cvt_pk_bf16_f32 v4, v4, v5
	v_cvt_pk_bf16_f32 v5, v6, v7
	s_waitcnt lgkmcnt(0)
	v_cvt_pk_bf16_f32 v6, v8, v9
	v_or_b32_e32 v8, 32, v12
	v_mad_i64_i32 v[8:9], s[20:21], v8, s5, v[2:3]
	v_cvt_pk_bf16_f32 v7, v10, v11
	v_lshl_add_u64 v[8:9], v[8:9], 0, v[0:1]
	global_store_dwordx4 v[8:9], v[4:7], off sc1
	ds_read_b128 v[4:7], v14 offset:10880
	ds_read_b128 v[8:11], v14 offset:10896
	s_waitcnt lgkmcnt(1)
	v_cvt_pk_bf16_f32 v4, v4, v5
	v_cvt_pk_bf16_f32 v5, v6, v7
	s_waitcnt lgkmcnt(0)
	v_cvt_pk_bf16_f32 v6, v8, v9
	v_or_b32_e32 v8, 40, v12
	v_mad_i64_i32 v[8:9], s[20:21], v8, s5, v[2:3]
	v_cvt_pk_bf16_f32 v7, v10, v11
	v_lshl_add_u64 v[8:9], v[8:9], 0, v[0:1]
	global_store_dwordx4 v[8:9], v[4:7], off sc1
	ds_read_b128 v[4:7], v14 offset:13056
	ds_read_b128 v[8:11], v14 offset:13072
	s_waitcnt lgkmcnt(1)
	v_cvt_pk_bf16_f32 v4, v4, v5
	v_cvt_pk_bf16_f32 v5, v6, v7
	s_waitcnt lgkmcnt(0)
	v_cvt_pk_bf16_f32 v6, v8, v9
	v_or_b32_e32 v8, 48, v12
	v_mad_i64_i32 v[8:9], s[20:21], v8, s5, v[2:3]
	v_cvt_pk_bf16_f32 v7, v10, v11
	v_lshl_add_u64 v[8:9], v[8:9], 0, v[0:1]
	global_store_dwordx4 v[8:9], v[4:7], off sc1
	ds_read_b128 v[4:7], v14 offset:15232
	ds_read_b128 v[8:11], v14 offset:15248
	s_waitcnt lgkmcnt(1)
	v_cvt_pk_bf16_f32 v4, v4, v5
	v_cvt_pk_bf16_f32 v5, v6, v7
	s_waitcnt lgkmcnt(0)
	v_cvt_pk_bf16_f32 v6, v8, v9
	v_or_b32_e32 v8, 56, v12
	v_mad_i64_i32 v[2:3], s[20:21], v8, s5, v[2:3]
	v_cvt_pk_bf16_f32 v7, v10, v11
	v_lshl_add_u64 v[2:3], v[2:3], 0, v[0:1]
	global_store_dwordx4 v[2:3], v[4:7], off sc1
	s_cbranch_scc1 .LBB0_164

.LBB0_172:
	v_add_co_u32_e32 v20, vcc, 0xfe000000, v6
	v_add_u32_e32 v3, 0xfffff000, v2
	s_nop 0
	v_addc_co_u32_e32 v21, vcc, -1, v7, vcc
	global_load_dwordx4 v[16:19], v[20:21], off offset:-1036
	s_nop 0
	global_load_dwordx4 v[20:23], v[20:21], off offset:-12
	v_lshrrev_b32_e32 v3, 10, v3
	v_cmp_lt_i32_e32 vcc, s1, v2
	s_mul_i32 s8, s18, 5
	v_mov_b64_e32 v[24:25], s[86:87]
	v_cndmask_b32_e32 v3, 4, v3, vcc
	v_add_u32_e32 v3, s8, v3
	v_mad_i64_i32 v[36:37], s[24:25], v3, s82, v[24:25]
	s_mov_b64 s[24:25], 0x3000
	v_lshl_add_u64 v[48:49], v[36:37], 0, s[76:77]
	v_lshl_add_u64 v[50:51], v[36:37], 0, s[24:25]
	v_lshl_add_u64 v[38:39], v[48:49], 0, v[0:1]
	v_lshl_add_u64 v[44:45], v[50:51], 0, v[0:1]
	global_load_dwordx4 v[24:27], v[38:39], off offset:16
	global_load_dwordx4 v[28:31], v[4:5], off offset:16
	global_load_dwordx4 v[32:35], v[4:5], off
	s_nop 0
	global_load_dwordx4 v[36:39], v[38:39], off
	s_nop 0
	global_load_dwordx4 v[40:43], v[44:45], off offset:16
	s_nop 0
	global_load_dwordx4 v[44:47], v[44:45], off
	v_add_u32_e32 v2, s70, v2
	s_waitcnt vmcnt(7)
	v_lshlrev_b32_e32 v52, 16, v16
	v_and_b32_e32 v53, 0xffff0000, v16
	v_lshlrev_b32_e32 v16, 16, v17
	v_and_b32_e32 v17, 0xffff0000, v17
	v_pk_mul_f32 v[66:67], v[52:53], v[52:53]
	v_pk_mul_f32 v[64:65], v[16:17], v[16:17]
	v_add_f32_e32 v3, v66, v67
	v_lshlrev_b32_e32 v54, 16, v18
	v_and_b32_e32 v55, 0xffff0000, v18
	v_add_f32_e32 v3, v3, v64
	s_waitcnt vmcnt(6)
	v_lshlrev_b32_e32 v60, 16, v22
	v_and_b32_e32 v61, 0xffff0000, v22
	v_lshlrev_b32_e32 v62, 16, v23
	v_and_b32_e32 v63, 0xffff0000, v23
	v_pk_mul_f32 v[22:23], v[54:55], v[54:55]
	v_add_f32_e32 v3, v65, v3
	v_lshlrev_b32_e32 v18, 16, v19
	v_and_b32_e32 v19, 0xffff0000, v19
	v_add_f32_e32 v3, v22, v3
	v_lshlrev_b32_e32 v56, 16, v20
	v_and_b32_e32 v57, 0xffff0000, v20
	v_lshlrev_b32_e32 v58, 16, v21
	v_and_b32_e32 v59, 0xffff0000, v21
	v_pk_mul_f32 v[20:21], v[18:19], v[18:19]
	v_add_f32_e32 v3, v23, v3
	v_add_f32_e32 v3, v20, v3
	v_pk_mul_f32 v[74:75], v[56:57], v[56:57]
	v_add_f32_e32 v3, v21, v3
	v_add_f32_e32 v3, v74, v3
	v_pk_mul_f32 v[72:73], v[58:59], v[58:59]
	v_add_f32_e32 v3, v75, v3
	v_add_f32_e32 v3, v72, v3
	v_pk_mul_f32 v[70:71], v[60:61], v[60:61]
	v_add_f32_e32 v3, v73, v3
	v_add_f32_e32 v3, v70, v3
	v_pk_mul_f32 v[68:69], v[62:63], v[62:63]
	v_add_f32_e32 v3, v71, v3
	v_add_f32_e32 v3, v68, v3
	v_add_f32_e32 v3, v69, v3
	ds_bpermute_b32 v9, v10, v3
	s_waitcnt vmcnt(5)
	v_pk_add_f32 v[20:21], v[24:25], 1.0 op_sel_hi:[1,0]
	s_waitcnt vmcnt(2)
	v_pk_add_f32 v[24:25], v[36:37], 1.0 op_sel_hi:[1,0]
	v_pk_add_f32 v[26:27], v[26:27], 1.0 op_sel_hi:[1,0]
	s_waitcnt lgkmcnt(0)
	v_add_f32_e32 v3, v3, v9
	ds_bpermute_b32 v9, v11, v3
	s_waitcnt lgkmcnt(0)
	v_add_f32_e32 v3, v3, v9
	ds_bpermute_b32 v9, v12, v3
	s_waitcnt lgkmcnt(0)
	v_add_f32_e32 v3, v3, v9
	ds_bpermute_b32 v9, v13, v3
	s_waitcnt lgkmcnt(0)
	v_add_f32_e32 v3, v3, v9
	ds_bpermute_b32 v9, v14, v3
	s_waitcnt lgkmcnt(0)
	v_add_f32_e32 v3, v3, v9
	ds_bpermute_b32 v22, v15, v3
	v_mov_b32_e32 v9, v1
	v_lshl_add_u64 v[48:49], v[48:49], 0, v[8:9]
	s_waitcnt lgkmcnt(0)
	v_add_f32_e32 v3, v3, v22
	v_fmamk_f32 v3, v3, 0x3a800000, v205
	v_mul_f32_e32 v22, 0x4b800000, v3
	v_cmp_gt_f32_e32 vcc, s33, v3
	s_nop 1
	v_cndmask_b32_e32 v3, v3, v22, vcc
	v_rsq_f32_e32 v3, v3
	v_pk_add_f32 v[22:23], v[38:39], 1.0 op_sel_hi:[1,0]
	v_mul_f32_e32 v36, 0x45800000, v3
	v_cndmask_b32_e32 v64, v3, v36, vcc
	v_pk_mul_f32 v[36:37], v[64:65], v[52:53] op_sel_hi:[0,1]
	v_pk_mul_f32 v[16:17], v[64:65], v[16:17] op_sel_hi:[0,1]
	v_pk_mul_f32 v[38:39], v[64:65], v[54:55] op_sel_hi:[0,1]
	v_pk_mul_f32 v[18:19], v[64:65], v[18:19] op_sel_hi:[0,1]
	v_pk_mul_f32 v[32:33], v[32:33], v[36:37]
	v_pk_mul_f32 v[16:17], v[34:35], v[16:17]
	v_pk_mul_f32 v[28:29], v[28:29], v[38:39]
	v_pk_mul_f32 v[18:19], v[30:31], v[18:19]
	s_waitcnt vmcnt(0)
	v_pk_fma_f32 v[24:25], v[24:25], v[32:33], v[44:45]
	v_pk_fma_f32 v[22:23], v[22:23], v[16:17], v[46:47]
	v_pk_fma_f32 v[20:21], v[20:21], v[28:29], v[40:41]
	v_pk_fma_f32 v[26:27], v[26:27], v[18:19], v[42:43]
	v_cvt_pk_bf16_f32 v16, v24, v25
	v_cvt_pk_bf16_f32 v17, v22, v23
	v_cvt_pk_bf16_f32 v18, v20, v21
	v_cvt_pk_bf16_f32 v19, v26, v27
	global_store_dwordx4 v[6:7], v[16:19], off offset:-1036 sc1
	global_load_dwordx4 v[16:19], v[4:5], off offset:2048
	s_nop 0
	global_load_dwordx4 v[20:23], v[48:49], off
	global_load_dwordx4 v[24:27], v[4:5], off offset:2064
	global_load_dwordx4 v[28:31], v[48:49], off offset:16
	v_lshl_add_u64 v[36:37], v[50:51], 0, v[8:9]
	global_load_dwordx4 v[32:35], v[36:37], off
	s_nop 0
	global_load_dwordx4 v[36:39], v[36:37], off offset:16
	v_pk_mul_f32 v[40:41], v[64:65], v[56:57] op_sel_hi:[0,1]
	v_pk_mul_f32 v[42:43], v[64:65], v[58:59] op_sel_hi:[0,1]
	v_pk_mul_f32 v[44:45], v[64:65], v[60:61] op_sel_hi:[0,1]
	v_pk_mul_f32 v[46:47], v[64:65], v[62:63] op_sel_hi:[0,1]
	v_cmp_lt_i32_e32 vcc, s17, v2
	s_or_b64 s[22:23], vcc, s[22:23]
	s_waitcnt vmcnt(5)
	v_pk_mul_f32 v[16:17], v[40:41], v[16:17]
	s_waitcnt vmcnt(4)
	v_pk_add_f32 v[20:21], v[20:21], 1.0 op_sel_hi:[1,0]
	v_pk_mul_f32 v[18:19], v[42:43], v[18:19]
	v_pk_add_f32 v[22:23], v[22:23], 1.0 op_sel_hi:[1,0]
	s_waitcnt vmcnt(3)
	v_pk_mul_f32 v[24:25], v[44:45], v[24:25]
	s_waitcnt vmcnt(2)
	v_pk_add_f32 v[28:29], v[28:29], 1.0 op_sel_hi:[1,0]
	v_pk_mul_f32 v[26:27], v[46:47], v[26:27]
	v_pk_add_f32 v[30:31], v[30:31], 1.0 op_sel_hi:[1,0]
	s_waitcnt vmcnt(1)
	v_pk_fma_f32 v[16:17], v[16:17], v[20:21], v[32:33]
	v_pk_fma_f32 v[18:19], v[18:19], v[22:23], v[34:35]
	s_waitcnt vmcnt(0)
	v_pk_fma_f32 v[20:21], v[24:25], v[28:29], v[36:37]
	v_pk_fma_f32 v[22:23], v[26:27], v[30:31], v[38:39]
	v_cvt_pk_bf16_f32 v16, v16, v17
	v_cvt_pk_bf16_f32 v17, v18, v19
	v_cvt_pk_bf16_f32 v18, v20, v21
	v_cvt_pk_bf16_f32 v19, v22, v23
	global_store_dwordx4 v[6:7], v[16:19], off offset:-12 sc1
	v_lshl_add_u64 v[6:7], v[6:7], 0, s[26:27]
	s_andn2_b64 exec, exec, s[22:23]
	s_cbranch_execnz .LBB0_172

.LBB0_178:
	s_or_b64 exec, exec, s[20:21]
	v_mul_f32_e32 v124, 0xbfb8aa3b, v158
	v_mul_f32_e32 v128, 0xbfb8aa3b, v118
	v_exp_f32_e32 v124, v124
	v_exp_f32_e32 v128, v128
	s_movk_i32 s19, 0x4400
	v_mul_lo_u32 v122, v197, s19
	v_add_f32_e32 v124, 1.0, v124
	v_add_f32_e32 v128, 1.0, v128
	v_rcp_f32_e32 v124, v124
	v_rcp_f32_e32 v128, v128
	v_lshl_or_b32 v123, v199, 2, v122
	s_movk_i32 s19, 0x440
	v_mul_f32_e32 v124, v158, v124
	v_mul_f32_e32 v118, v118, v128
	v_mul_f32_e32 v124, v124, v154
	v_mad_u32_u24 v123, v196, s19, v123
	v_mul_f32_e32 v114, v118, v114
	s_waitcnt vmcnt(0) lgkmcnt(0)
	s_barrier
	v_mul_f32_e32 v125, 0xbfb8aa3b, v159
	ds_write2_b32 v123, v124, v114 offset1:16
	v_mul_f32_e32 v114, 0xbfb8aa3b, v119
	v_exp_f32_e32 v125, v125
	v_exp_f32_e32 v114, v114
	v_mul_f32_e32 v126, 0xbfb8aa3b, v160
	v_exp_f32_e32 v126, v126
	v_add_f32_e32 v125, 1.0, v125
	v_add_f32_e32 v114, 1.0, v114
	v_rcp_f32_e32 v125, v125
	v_rcp_f32_e32 v114, v114
	v_add_f32_e32 v126, 1.0, v126
	v_rcp_f32_e32 v126, v126
	v_mul_f32_e32 v125, v159, v125
	v_mul_f32_e32 v114, v119, v114
	v_mul_f32_e32 v125, v125, v155
	v_mul_f32_e32 v114, v114, v115
	ds_write2_b32 v123, v125, v114 offset0:68 offset1:84
	v_mul_f32_e32 v114, 0xbfb8aa3b, v120
	v_exp_f32_e32 v114, v114
	v_mul_f32_e32 v126, v160, v126
	v_mul_f32_e32 v126, v126, v156
	v_mul_f32_e32 v127, 0xbfb8aa3b, v161
	v_add_f32_e32 v114, 1.0, v114
	v_rcp_f32_e32 v114, v114
	v_exp_f32_e32 v127, v127
	v_readlane_b32 s22, v254, 46
	v_mul_f32_e32 v114, v120, v114
	v_mul_f32_e32 v114, v114, v116
	ds_write2_b32 v123, v126, v114 offset0:136 offset1:152
	v_mul_f32_e32 v114, 0xbfb8aa3b, v121
	v_exp_f32_e32 v114, v114
	v_add_f32_e32 v127, 1.0, v127
	v_rcp_f32_e32 v127, v127
	v_add_f32_e32 v114, 1.0, v114
	v_rcp_f32_e32 v114, v114
	v_mul_f32_e32 v127, v161, v127
	v_mul_f32_e32 v127, v127, v157
	v_mul_f32_e32 v114, v121, v114
	v_mul_f32_e32 v114, v114, v117
	ds_write2_b32 v123, v127, v114 offset0:204 offset1:220
	v_mul_f32_e32 v114, 0xbfb8aa3b, v110
	v_exp_f32_e32 v114, v114
	s_nop 0
	v_add_f32_e32 v114, 1.0, v114
	v_rcp_f32_e32 v114, v114
	s_nop 0
	v_mul_f32_e32 v110, v110, v114
	v_mul_f32_e32 v106, v110, v106
	v_mul_f32_e32 v110, 0xbfb8aa3b, v111
	v_exp_f32_e32 v110, v110
	s_nop 0
	v_add_f32_e32 v110, 1.0, v110
	v_rcp_f32_e32 v110, v110
	s_nop 0
	v_mul_f32_e32 v110, v111, v110
	v_mul_f32_e32 v107, v110, v107
	v_mul_f32_e32 v110, 0xbfb8aa3b, v112
	v_exp_f32_e32 v110, v110
	s_nop 0
	v_add_f32_e32 v110, 1.0, v110
	v_rcp_f32_e32 v110, v110
	s_nop 0
	v_mul_f32_e32 v110, v112, v110
	v_mul_f32_e32 v108, v110, v108
	v_mul_f32_e32 v110, 0xbfb8aa3b, v113
	v_exp_f32_e32 v110, v110
	s_nop 0
	v_add_f32_e32 v110, 1.0, v110
	v_rcp_f32_e32 v110, v110
	s_nop 0
	v_mul_f32_e32 v110, v113, v110
	v_mul_f32_e32 v109, v110, v109
	v_mul_f32_e32 v110, 0xbfb8aa3b, v102
	v_exp_f32_e32 v110, v110
	s_nop 0
	v_add_f32_e32 v110, 1.0, v110
	v_rcp_f32_e32 v110, v110
	s_nop 0
	v_mul_f32_e32 v102, v102, v110
	v_mul_f32_e32 v98, v102, v98
	ds_write2_b32 v123, v106, v98 offset0:32 offset1:48
	v_mul_f32_e32 v98, 0xbfb8aa3b, v103
	v_exp_f32_e32 v98, v98
	s_nop 0
	v_add_f32_e32 v98, 1.0, v98
	v_rcp_f32_e32 v98, v98
	s_nop 0
	v_mul_f32_e32 v98, v103, v98
	v_mul_f32_e32 v98, v98, v99
	ds_write2_b32 v123, v107, v98 offset0:100 offset1:116
	v_mul_f32_e32 v98, 0xbfb8aa3b, v104
	v_exp_f32_e32 v98, v98
	s_nop 0
	v_add_f32_e32 v98, 1.0, v98
	v_rcp_f32_e32 v98, v98
	s_nop 0
	v_mul_f32_e32 v98, v104, v98
	v_mul_f32_e32 v98, v98, v100
	ds_write2_b32 v123, v108, v98 offset0:168 offset1:184
	v_mul_f32_e32 v98, 0xbfb8aa3b, v105
	v_exp_f32_e32 v98, v98
	s_nop 0
	v_add_f32_e32 v98, 1.0, v98
	v_rcp_f32_e32 v98, v98
	s_nop 0
	v_mul_f32_e32 v98, v105, v98
	v_mul_f32_e32 v98, v98, v101
	ds_write2_b32 v123, v109, v98 offset0:236 offset1:252
	v_mul_f32_e32 v98, 0xbfb8aa3b, v94
	v_exp_f32_e32 v98, v98
	s_nop 0
	v_add_f32_e32 v98, 1.0, v98
	v_rcp_f32_e32 v98, v98
	s_nop 0
	v_mul_f32_e32 v94, v94, v98
	v_mul_f32_e32 v90, v94, v90
	v_mul_f32_e32 v94, 0xbfb8aa3b, v95
	v_exp_f32_e32 v94, v94
	s_nop 0
	v_add_f32_e32 v94, 1.0, v94
	v_rcp_f32_e32 v94, v94
	s_nop 0
	v_mul_f32_e32 v94, v95, v94
	v_mul_f32_e32 v91, v94, v91
	v_mul_f32_e32 v94, 0xbfb8aa3b, v96
	v_exp_f32_e32 v94, v94
	s_nop 0
	v_add_f32_e32 v94, 1.0, v94
	v_rcp_f32_e32 v94, v94
	s_nop 0
	v_mul_f32_e32 v94, v96, v94
	v_mul_f32_e32 v92, v94, v92
	v_mul_f32_e32 v94, 0xbfb8aa3b, v97
	v_exp_f32_e32 v94, v94
	s_nop 0
	v_add_f32_e32 v94, 1.0, v94
	v_rcp_f32_e32 v94, v94
	s_nop 0
	v_mul_f32_e32 v94, v97, v94
	v_mul_f32_e32 v93, v94, v93
	v_mul_f32_e32 v94, 0xbfb8aa3b, v86
	v_exp_f32_e32 v94, v94
	s_nop 0
	v_add_f32_e32 v94, 1.0, v94
	v_rcp_f32_e32 v94, v94
	s_nop 0
	v_mul_f32_e32 v86, v86, v94
	v_mul_f32_e32 v82, v86, v82
	v_add_u32_e32 v86, 0x1000, v123
	ds_write2_b32 v86, v90, v82 offset0:64 offset1:80
	v_mul_f32_e32 v82, 0xbfb8aa3b, v87
	v_exp_f32_e32 v82, v82
	s_nop 0
	v_add_f32_e32 v82, 1.0, v82
	v_rcp_f32_e32 v82, v82
	s_nop 0
	v_mul_f32_e32 v82, v87, v82
	v_mul_f32_e32 v82, v82, v83
	ds_write2_b32 v86, v91, v82 offset0:132 offset1:148
	v_mul_f32_e32 v82, 0xbfb8aa3b, v88
	v_exp_f32_e32 v82, v82
	v_add_u32_e32 v83, 0x1400, v123
	v_add_f32_e32 v82, 1.0, v82
	v_rcp_f32_e32 v82, v82
	s_nop 0
	v_mul_f32_e32 v82, v88, v82
	v_mul_f32_e32 v82, v82, v84
	ds_write2_b32 v86, v92, v82 offset0:200 offset1:216
	v_mul_f32_e32 v82, 0xbfb8aa3b, v89
	v_exp_f32_e32 v82, v82
	s_nop 0
	v_add_f32_e32 v82, 1.0, v82
	v_rcp_f32_e32 v82, v82
	s_nop 0
	v_mul_f32_e32 v82, v89, v82
	v_mul_f32_e32 v82, v82, v85
	ds_write2_b32 v83, v93, v82 offset0:12 offset1:28
	v_mul_f32_e32 v82, 0xbfb8aa3b, v78
	v_exp_f32_e32 v82, v82
	s_nop 0
	v_add_f32_e32 v82, 1.0, v82
	v_rcp_f32_e32 v82, v82
	s_nop 0
	v_mul_f32_e32 v78, v78, v82
	v_mul_f32_e32 v74, v78, v74
	v_mul_f32_e32 v78, 0xbfb8aa3b, v79
	v_exp_f32_e32 v78, v78
	s_nop 0
	v_add_f32_e32 v78, 1.0, v78
	v_rcp_f32_e32 v78, v78
	s_nop 0
	v_mul_f32_e32 v78, v79, v78
	v_mul_f32_e32 v75, v78, v75
	v_mul_f32_e32 v78, 0xbfb8aa3b, v80
	v_exp_f32_e32 v78, v78
	s_nop 0
	v_add_f32_e32 v78, 1.0, v78
	v_rcp_f32_e32 v78, v78
	s_nop 0
	v_mul_f32_e32 v78, v80, v78
	v_mul_f32_e32 v76, v78, v76
	v_mul_f32_e32 v78, 0xbfb8aa3b, v81
	v_exp_f32_e32 v78, v78
	s_nop 0
	v_add_f32_e32 v78, 1.0, v78
	v_rcp_f32_e32 v78, v78
	s_nop 0
	v_mul_f32_e32 v78, v81, v78
	v_mul_f32_e32 v77, v78, v77
	v_mul_f32_e32 v78, 0xbfb8aa3b, v70
	v_exp_f32_e32 v78, v78
	s_nop 0
	v_add_f32_e32 v78, 1.0, v78
	v_rcp_f32_e32 v78, v78
	s_nop 0
	v_mul_f32_e32 v70, v70, v78
	v_mul_f32_e32 v66, v70, v66
	ds_write2_b32 v86, v74, v66 offset0:96 offset1:112
	v_mul_f32_e32 v66, 0xbfb8aa3b, v71
	v_exp_f32_e32 v66, v66
	s_nop 0
	v_add_f32_e32 v66, 1.0, v66
	v_rcp_f32_e32 v66, v66
	s_nop 0
	v_mul_f32_e32 v66, v71, v66
	v_mul_f32_e32 v66, v66, v67
	ds_write2_b32 v86, v75, v66 offset0:164 offset1:180
	v_mul_f32_e32 v66, 0xbfb8aa3b, v72
	v_exp_f32_e32 v66, v66
	s_nop 0
	v_add_f32_e32 v66, 1.0, v66
	v_rcp_f32_e32 v66, v66
	s_nop 0
	v_mul_f32_e32 v66, v72, v66
	v_mul_f32_e32 v66, v66, v68
	ds_write2_b32 v86, v76, v66 offset0:232 offset1:248
	v_mul_f32_e32 v66, 0xbfb8aa3b, v73
	v_exp_f32_e32 v66, v66
	s_nop 0
	v_add_f32_e32 v66, 1.0, v66
	v_rcp_f32_e32 v66, v66
	s_nop 0
	v_mul_f32_e32 v66, v73, v66
	v_mul_f32_e32 v66, v66, v69
	ds_write2_b32 v83, v77, v66 offset0:44 offset1:60
	v_mul_f32_e32 v66, 0xbfb8aa3b, v62
	v_exp_f32_e32 v66, v66
	s_nop 0
	v_add_f32_e32 v66, 1.0, v66
	v_rcp_f32_e32 v66, v66
	s_nop 0
	v_mul_f32_e32 v62, v62, v66
	v_mul_f32_e32 v58, v62, v58
	v_mul_f32_e32 v62, 0xbfb8aa3b, v63
	v_exp_f32_e32 v62, v62
	s_nop 0
	v_add_f32_e32 v62, 1.0, v62
	v_rcp_f32_e32 v62, v62
	s_nop 0
	v_mul_f32_e32 v62, v63, v62
	v_mul_f32_e32 v59, v62, v59
	v_mul_f32_e32 v62, 0xbfb8aa3b, v64
	v_exp_f32_e32 v62, v62
	s_nop 0
	v_add_f32_e32 v62, 1.0, v62
	v_rcp_f32_e32 v62, v62
	s_nop 0
	v_mul_f32_e32 v62, v64, v62
	v_mul_f32_e32 v60, v62, v60
	v_mul_f32_e32 v62, 0xbfb8aa3b, v65
	v_exp_f32_e32 v62, v62
	s_nop 0
	v_add_f32_e32 v62, 1.0, v62
	v_rcp_f32_e32 v62, v62
	s_nop 0
	v_mul_f32_e32 v62, v65, v62
	v_mul_f32_e32 v61, v62, v61
	v_mul_f32_e32 v62, 0xbfb8aa3b, v54
	v_exp_f32_e32 v62, v62
	s_nop 0
	v_add_f32_e32 v62, 1.0, v62
	v_rcp_f32_e32 v62, v62
	s_nop 0
	v_mul_f32_e32 v54, v54, v62
	v_mul_f32_e32 v50, v54, v50
	v_add_u32_e32 v54, 0x2000, v123
	ds_write2_b32 v54, v58, v50 offset0:128 offset1:144
	v_mul_f32_e32 v50, 0xbfb8aa3b, v55
	v_exp_f32_e32 v50, v50
	s_nop 0
	v_add_f32_e32 v50, 1.0, v50
	v_rcp_f32_e32 v50, v50
	s_nop 0
	v_mul_f32_e32 v50, v55, v50
	v_mul_f32_e32 v50, v50, v51
	ds_write2_b32 v54, v59, v50 offset0:196 offset1:212
	v_mul_f32_e32 v50, 0xbfb8aa3b, v56
	v_exp_f32_e32 v50, v50
	v_add_u32_e32 v51, 0x2400, v123
	v_add_f32_e32 v50, 1.0, v50
	v_rcp_f32_e32 v50, v50
	s_nop 0
	v_mul_f32_e32 v50, v56, v50
	v_mul_f32_e32 v50, v50, v52
	ds_write2_b32 v51, v60, v50 offset0:8 offset1:24
	v_mul_f32_e32 v50, 0xbfb8aa3b, v57
	v_exp_f32_e32 v50, v50
	s_nop 0
	v_add_f32_e32 v50, 1.0, v50
	v_rcp_f32_e32 v50, v50
	s_nop 0
	v_mul_f32_e32 v50, v57, v50
	v_mul_f32_e32 v50, v50, v53
	ds_write2_b32 v51, v61, v50 offset0:76 offset1:92
	v_mul_f32_e32 v50, 0xbfb8aa3b, v46
	v_exp_f32_e32 v50, v50
	s_nop 0
	v_add_f32_e32 v50, 1.0, v50
	v_rcp_f32_e32 v50, v50
	s_nop 0
	v_mul_f32_e32 v46, v46, v50
	v_mul_f32_e32 v42, v46, v42
	v_mul_f32_e32 v46, 0xbfb8aa3b, v47
	v_exp_f32_e32 v46, v46
	s_nop 0
	v_add_f32_e32 v46, 1.0, v46
	v_rcp_f32_e32 v46, v46
	s_nop 0
	v_mul_f32_e32 v46, v47, v46
	v_mul_f32_e32 v43, v46, v43
	v_mul_f32_e32 v46, 0xbfb8aa3b, v48
	v_exp_f32_e32 v46, v46
	s_nop 0
	v_add_f32_e32 v46, 1.0, v46
	v_rcp_f32_e32 v46, v46
	s_nop 0
	v_mul_f32_e32 v46, v48, v46
	v_mul_f32_e32 v44, v46, v44
	v_mul_f32_e32 v46, 0xbfb8aa3b, v49
	v_exp_f32_e32 v46, v46
	s_nop 0
	v_add_f32_e32 v46, 1.0, v46
	v_rcp_f32_e32 v46, v46
	s_nop 0
	v_mul_f32_e32 v46, v49, v46
	v_mul_f32_e32 v45, v46, v45
	v_mul_f32_e32 v46, 0xbfb8aa3b, v38
	v_exp_f32_e32 v46, v46
	s_nop 0
	v_add_f32_e32 v46, 1.0, v46
	v_rcp_f32_e32 v46, v46
	s_nop 0
	v_mul_f32_e32 v38, v38, v46
	v_mul_f32_e32 v34, v38, v34
	ds_write2_b32 v54, v42, v34 offset0:160 offset1:176
	v_mul_f32_e32 v34, 0xbfb8aa3b, v39
	v_exp_f32_e32 v34, v34
	s_nop 0
	v_add_f32_e32 v34, 1.0, v34
	v_rcp_f32_e32 v34, v34
	s_nop 0
	v_mul_f32_e32 v34, v39, v34
	v_mul_f32_e32 v34, v34, v35
	ds_write2_b32 v54, v43, v34 offset0:228 offset1:244
	v_mul_f32_e32 v34, 0xbfb8aa3b, v40
	v_exp_f32_e32 v34, v34
	s_nop 0
	v_add_f32_e32 v34, 1.0, v34
	v_rcp_f32_e32 v34, v34
	s_nop 0
	v_mul_f32_e32 v34, v40, v34
	v_mul_f32_e32 v34, v34, v36
	ds_write2_b32 v51, v44, v34 offset0:40 offset1:56
	v_mul_f32_e32 v34, 0xbfb8aa3b, v41
	v_exp_f32_e32 v34, v34
	s_nop 0
	v_add_f32_e32 v34, 1.0, v34
	v_rcp_f32_e32 v34, v34
	s_nop 0
	v_mul_f32_e32 v34, v41, v34
	v_mul_f32_e32 v34, v34, v37
	ds_write2_b32 v51, v45, v34 offset0:108 offset1:124
	v_mul_f32_e32 v34, 0xbfb8aa3b, v30
	v_exp_f32_e32 v34, v34
	s_nop 0
	v_add_f32_e32 v34, 1.0, v34
	v_rcp_f32_e32 v34, v34
	s_nop 0
	v_mul_f32_e32 v30, v30, v34
	v_mul_f32_e32 v26, v30, v26
	v_mul_f32_e32 v30, 0xbfb8aa3b, v31
	v_exp_f32_e32 v30, v30
	s_nop 0
	v_add_f32_e32 v30, 1.0, v30
	v_rcp_f32_e32 v30, v30
	s_nop 0
	v_mul_f32_e32 v30, v31, v30
	v_mul_f32_e32 v27, v30, v27
	v_mul_f32_e32 v30, 0xbfb8aa3b, v32
	v_exp_f32_e32 v30, v30
	s_nop 0
	v_add_f32_e32 v30, 1.0, v30
	v_rcp_f32_e32 v30, v30
	s_nop 0
	v_mul_f32_e32 v30, v32, v30
	v_mul_f32_e32 v28, v30, v28
	v_mul_f32_e32 v30, 0xbfb8aa3b, v33
	v_exp_f32_e32 v30, v30
	s_nop 0
	v_add_f32_e32 v30, 1.0, v30
	v_rcp_f32_e32 v30, v30
	s_nop 0
	v_mul_f32_e32 v30, v33, v30
	v_mul_f32_e32 v29, v30, v29
	v_mul_f32_e32 v30, 0xbfb8aa3b, v22
	v_exp_f32_e32 v30, v30
	s_nop 0
	v_add_f32_e32 v30, 1.0, v30
	v_rcp_f32_e32 v30, v30
	s_nop 0
	v_mul_f32_e32 v22, v22, v30
	v_mul_f32_e32 v18, v22, v18
	v_add_u32_e32 v22, 0x3000, v123
	ds_write2_b32 v22, v26, v18 offset0:192 offset1:208
	v_mul_f32_e32 v18, 0xbfb8aa3b, v23
	v_exp_f32_e32 v18, v18
	s_nop 0
	v_add_f32_e32 v18, 1.0, v18
	v_rcp_f32_e32 v18, v18
	s_nop 0
	v_mul_f32_e32 v18, v23, v18
	v_mul_f32_e32 v18, v18, v19
	v_add_u32_e32 v19, 0x3400, v123
	ds_write2_b32 v19, v27, v18 offset0:4 offset1:20
	v_mul_f32_e32 v18, 0xbfb8aa3b, v24
	v_exp_f32_e32 v18, v18
	s_nop 0
	v_add_f32_e32 v18, 1.0, v18
	v_rcp_f32_e32 v18, v18
	s_nop 0
	v_mul_f32_e32 v18, v24, v18
	v_mul_f32_e32 v18, v18, v20
	ds_write2_b32 v19, v28, v18 offset0:72 offset1:88
	v_mul_f32_e32 v18, 0xbfb8aa3b, v25
	v_exp_f32_e32 v18, v18
	s_nop 0
	v_add_f32_e32 v18, 1.0, v18
	v_rcp_f32_e32 v18, v18
	s_nop 0
	v_mul_f32_e32 v18, v25, v18
	v_mul_f32_e32 v18, v18, v21
	ds_write2_b32 v19, v29, v18 offset0:140 offset1:156
	v_mul_f32_e32 v18, 0xbfb8aa3b, v14
	v_exp_f32_e32 v18, v18
	s_nop 0
	v_add_f32_e32 v18, 1.0, v18
	v_rcp_f32_e32 v18, v18
	s_nop 0
	v_mul_f32_e32 v14, v14, v18
	v_mul_f32_e32 v10, v14, v10
	v_mul_f32_e32 v14, 0xbfb8aa3b, v15
	v_exp_f32_e32 v14, v14
	s_nop 0
	v_add_f32_e32 v14, 1.0, v14
	v_rcp_f32_e32 v14, v14
	s_nop 0
	v_mul_f32_e32 v14, v15, v14
	v_mul_f32_e32 v11, v14, v11
	v_mul_f32_e32 v14, 0xbfb8aa3b, v16
	v_exp_f32_e32 v14, v14
	s_nop 0
	v_add_f32_e32 v14, 1.0, v14
	v_rcp_f32_e32 v14, v14
	s_nop 0
	v_mul_f32_e32 v14, v16, v14
	v_mul_f32_e32 v12, v14, v12
	v_mul_f32_e32 v14, 0xbfb8aa3b, v17
	v_exp_f32_e32 v14, v14
	s_nop 0
	v_add_f32_e32 v14, 1.0, v14
	v_rcp_f32_e32 v14, v14
	s_nop 0
	v_mul_f32_e32 v14, v17, v14
	v_mul_f32_e32 v13, v14, v13
	v_mul_f32_e32 v14, 0xbfb8aa3b, v6
	v_exp_f32_e32 v14, v14
	s_nop 0
	v_add_f32_e32 v14, 1.0, v14
	v_rcp_f32_e32 v14, v14
	s_nop 0
	v_mul_f32_e32 v6, v6, v14
	v_mul_f32_e32 v2, v6, v2
	ds_write2_b32 v22, v10, v2 offset0:224 offset1:240
	v_mul_f32_e32 v2, 0xbfb8aa3b, v7
	v_exp_f32_e32 v2, v2
	s_nop 0
	v_add_f32_e32 v2, 1.0, v2
	v_rcp_f32_e32 v2, v2
	s_nop 0
	v_mul_f32_e32 v2, v7, v2
	v_mul_f32_e32 v2, v2, v3
	ds_write2_b32 v19, v11, v2 offset0:36 offset1:52
	v_mul_f32_e32 v2, 0xbfb8aa3b, v8
	v_exp_f32_e32 v2, v2
	s_nop 0
	v_add_f32_e32 v2, 1.0, v2
	v_rcp_f32_e32 v2, v2
	s_nop 0
	v_mul_f32_e32 v2, v8, v2
	v_mul_f32_e32 v2, v2, v4
	ds_write2_b32 v19, v12, v2 offset0:104 offset1:120
	v_mul_f32_e32 v2, 0xbfb8aa3b, v9
	v_exp_f32_e32 v2, v2
	v_lshl_add_u32 v12, v0, 6, s22
	v_lshl_or_b32 v0, v195, 7, s17
	v_lshlrev_b32_e32 v4, 3, v194
	v_add_f32_e32 v2, 1.0, v2
	v_rcp_f32_e32 v2, v2
	s_add_i32 s17, s8, 32
	s_cmp_gt_u32 s8, 55
	s_mov_b32 s8, s17
	v_mul_f32_e32 v2, v9, v2
	v_mul_f32_e32 v2, v2, v5
	ds_write2_b32 v19, v13, v2 offset0:172 offset1:188
	v_lshl_add_u64 v[2:3], s[46:47], 0, v[0:1]
	v_lshrrev_b32_e32 v0, 3, v194
	v_and_b32_e32 v13, 56, v4
	v_mul_u32_u24_e32 v4, 0x110, v0
	v_lshlrev_b32_e32 v5, 2, v13
	v_add3_u32 v14, v122, v4, v5
	ds_read_b128 v[4:7], v14
	ds_read_b128 v[8:11], v14 offset:16
	v_or_b32_e32 v12, v12, v0
	v_lshlrev_b32_e32 v0, 1, v13
	s_waitcnt lgkmcnt(1)
	v_cvt_pk_bf16_f32 v4, v4, v5
	v_cvt_pk_bf16_f32 v5, v6, v7
	s_waitcnt lgkmcnt(0)
	v_cvt_pk_bf16_f32 v6, v8, v9
	v_mad_i64_i32 v[8:9], s[20:21], v12, s5, v[2:3]
	v_cvt_pk_bf16_f32 v7, v10, v11
	v_lshl_add_u64 v[8:9], v[8:9], 0, v[0:1]
	global_store_dwordx4 v[8:9], v[4:7], off sc1
	ds_read_b128 v[4:7], v14 offset:2176
	ds_read_b128 v[8:11], v14 offset:2192
	s_waitcnt lgkmcnt(1)
	v_cvt_pk_bf16_f32 v4, v4, v5
	v_cvt_pk_bf16_f32 v5, v6, v7
	s_waitcnt lgkmcnt(0)
	v_cvt_pk_bf16_f32 v6, v8, v9
	v_or_b32_e32 v8, 8, v12
	v_mad_i64_i32 v[8:9], s[20:21], v8, s5, v[2:3]
	v_cvt_pk_bf16_f32 v7, v10, v11
	v_lshl_add_u64 v[8:9], v[8:9], 0, v[0:1]
	global_store_dwordx4 v[8:9], v[4:7], off sc1
	ds_read_b128 v[4:7], v14 offset:4352
	ds_read_b128 v[8:11], v14 offset:4368
	s_waitcnt lgkmcnt(1)
	v_cvt_pk_bf16_f32 v4, v4, v5
	v_cvt_pk_bf16_f32 v5, v6, v7
	s_waitcnt lgkmcnt(0)
	v_cvt_pk_bf16_f32 v6, v8, v9
	v_or_b32_e32 v8, 16, v12
	v_mad_i64_i32 v[8:9], s[20:21], v8, s5, v[2:3]
	v_cvt_pk_bf16_f32 v7, v10, v11
	v_lshl_add_u64 v[8:9], v[8:9], 0, v[0:1]
	global_store_dwordx4 v[8:9], v[4:7], off sc1
	ds_read_b128 v[4:7], v14 offset:6528
	ds_read_b128 v[8:11], v14 offset:6544
	s_waitcnt lgkmcnt(1)
	v_cvt_pk_bf16_f32 v4, v4, v5
	v_cvt_pk_bf16_f32 v5, v6, v7
	s_waitcnt lgkmcnt(0)
	v_cvt_pk_bf16_f32 v6, v8, v9
	v_or_b32_e32 v8, 24, v12
	v_mad_i64_i32 v[8:9], s[20:21], v8, s5, v[2:3]
	v_cvt_pk_bf16_f32 v7, v10, v11
	v_lshl_add_u64 v[8:9], v[8:9], 0, v[0:1]
	global_store_dwordx4 v[8:9], v[4:7], off sc1
	ds_read_b128 v[4:7], v14 offset:8704
	ds_read_b128 v[8:11], v14 offset:8720
	s_waitcnt lgkmcnt(1)
	v_cvt_pk_bf16_f32 v4, v4, v5
	v_cvt_pk_bf16_f32 v5, v6, v7
	s_waitcnt lgkmcnt(0)
	v_cvt_pk_bf16_f32 v6, v8, v9
	v_or_b32_e32 v8, 32, v12
	v_mad_i64_i32 v[8:9], s[20:21], v8, s5, v[2:3]
	v_cvt_pk_bf16_f32 v7, v10, v11
	v_lshl_add_u64 v[8:9], v[8:9], 0, v[0:1]
	global_store_dwordx4 v[8:9], v[4:7], off sc1
	ds_read_b128 v[4:7], v14 offset:10880
	ds_read_b128 v[8:11], v14 offset:10896
	s_waitcnt lgkmcnt(1)
	v_cvt_pk_bf16_f32 v4, v4, v5
	v_cvt_pk_bf16_f32 v5, v6, v7
	s_waitcnt lgkmcnt(0)
	v_cvt_pk_bf16_f32 v6, v8, v9
	v_or_b32_e32 v8, 40, v12
	v_mad_i64_i32 v[8:9], s[20:21], v8, s5, v[2:3]
	v_cvt_pk_bf16_f32 v7, v10, v11
	v_lshl_add_u64 v[8:9], v[8:9], 0, v[0:1]
	global_store_dwordx4 v[8:9], v[4:7], off sc1
	ds_read_b128 v[4:7], v14 offset:13056
	ds_read_b128 v[8:11], v14 offset:13072
	s_waitcnt lgkmcnt(1)
	v_cvt_pk_bf16_f32 v4, v4, v5
	v_cvt_pk_bf16_f32 v5, v6, v7
	s_waitcnt lgkmcnt(0)
	v_cvt_pk_bf16_f32 v6, v8, v9
	v_or_b32_e32 v8, 48, v12
	v_mad_i64_i32 v[8:9], s[20:21], v8, s5, v[2:3]
	v_cvt_pk_bf16_f32 v7, v10, v11
	v_lshl_add_u64 v[8:9], v[8:9], 0, v[0:1]
	global_store_dwordx4 v[8:9], v[4:7], off sc1
	ds_read_b128 v[4:7], v14 offset:15232
	ds_read_b128 v[8:11], v14 offset:15248
	s_waitcnt lgkmcnt(1)
	v_cvt_pk_bf16_f32 v4, v4, v5
	v_cvt_pk_bf16_f32 v5, v6, v7
	s_waitcnt lgkmcnt(0)
	v_cvt_pk_bf16_f32 v6, v8, v9
	v_or_b32_e32 v8, 56, v12
	v_mad_i64_i32 v[2:3], s[20:21], v8, s5, v[2:3]
	v_cvt_pk_bf16_f32 v7, v10, v11
	v_lshl_add_u64 v[2:3], v[2:3], 0, v[0:1]
	global_store_dwordx4 v[2:3], v[4:7], off sc1
	s_cbranch_scc1 .LBB0_167

.LBB0_200:
	s_waitcnt vmcnt(1) lgkmcnt(1)
	v_pk_fma_f32 v[6:7], v[14:15], v[6:7], v[18:19]
	v_pk_fma_f32 v[8:9], v[16:17], v[8:9], v[20:21]
	s_waitcnt vmcnt(0) lgkmcnt(0)
	v_pk_fma_f32 v[10:11], v[10:11], v[2:3], v[22:23]
	v_pk_fma_f32 v[12:13], v[12:13], v[4:5], v[24:25]
	v_cvt_pk_bf16_f32 v2, v6, v7
	v_lshl_add_u64 v[6:7], s[66:67], 0, v[30:31]
	s_add_i32 s17, s17, s64
	v_cvt_pk_bf16_f32 v3, v8, v9
	v_cvt_pk_bf16_f32 v4, v10, v11
	v_cvt_pk_bf16_f32 v5, v12, v13
	v_lshl_add_u64 v[6:7], v[26:27], 1, v[6:7]
	s_cmpk_gt_i32 s17, 0xff
	global_store_dwordx4 v[6:7], v[2:5], off sc1
	s_cbranch_scc1 .LBB0_284

.LBB0_229:
	s_waitcnt vmcnt(1) lgkmcnt(1)
	v_pk_fma_f32 v[6:7], v[6:7], v[14:15], v[18:19]
	v_pk_fma_f32 v[8:9], v[8:9], v[16:17], v[20:21]
	s_waitcnt vmcnt(0) lgkmcnt(0)
	v_pk_fma_f32 v[10:11], v[2:3], v[10:11], v[22:23]
	v_pk_fma_f32 v[12:13], v[4:5], v[12:13], v[24:25]
	v_cvt_pk_bf16_f32 v2, v6, v7
	v_lshl_add_u64 v[6:7], s[66:67], 0, v[30:31]
	v_or3_b32 v28, v33, v32, 8
	v_cvt_pk_bf16_f32 v3, v8, v9
	v_cvt_pk_bf16_f32 v4, v10, v11
	v_cvt_pk_bf16_f32 v5, v12, v13
	v_lshl_add_u64 v[6:7], v[26:27], 1, v[6:7]
	v_add_u32_e32 v0, 0xfffff000, v28
	global_store_dwordx4 v[6:7], v[2:5], off sc1
	v_cmp_lt_i32_e64 s[42:43], s1, v28
	v_add_u32_e32 v35, 0x880, v35
	v_lshrrev_b32_e32 v2, 10, v0
	v_cndmask_b32_e64 v2, 4, v2, s[42:43]
	v_add_u32_e32 v4, s8, v2
	v_mov_b64_e32 v[2:3], s[14:15]
	v_mad_i64_i32 v[2:3], s[22:23], v4, s82, v[2:3]
	v_lshl_add_u64 v[2:3], v[26:27], 2, v[2:3]
	s_mov_b64 s[22:23], 0x8602000
	v_lshl_add_u64 v[4:5], v[2:3], 0, s[22:23]
	v_add_co_u32_e32 v2, vcc, 0x8602000, v2
	v_add3_u32 v10, v42, v35, v34
	s_nop 0
	v_addc_co_u32_e32 v3, vcc, 0, v3, vcc
	global_load_dwordx4 v[6:9], v[2:3], off
	s_nop 0
	global_load_dwordx4 v[2:5], v[4:5], off offset:16
	ds_read_b128 v[14:17], v10
	ds_read_b128 v[10:13], v10 offset:16
	v_cndmask_b32_e64 v18, 0, 1, s[44:45]
	v_cmp_ne_u32_e64 s[40:41], 1, v18
	s_andn2_b64 vcc, exec, s[44:45]
	s_mov_b64 s[22:23], -1
	s_cbranch_vccnz .LBB0_231
	v_ashrrev_i32_e32 v29, 31, v28
	v_lshlrev_b64 v[30:31], 11, v[28:29]
	v_lshl_add_u64 v[18:19], s[66:67], 0, v[30:31]
	v_lshl_add_u64 v[18:19], v[26:27], 1, v[18:19]
	global_load_dwordx4 v[22:25], v[18:19], off
	s_mov_b64 s[22:23], 0
	s_waitcnt vmcnt(0)
	v_lshlrev_b32_e32 v18, 16, v22
	v_and_b32_e32 v19, 0xffff0000, v22
	v_lshlrev_b32_e32 v20, 16, v23
	v_and_b32_e32 v21, 0xffff0000, v23
	v_lshlrev_b32_e32 v22, 16, v24
	v_and_b32_e32 v23, 0xffff0000, v24
	v_lshlrev_b32_e32 v24, 16, v25
	v_and_b32_e32 v25, 0xffff0000, v25

.LBB0_237:
	s_waitcnt vmcnt(1) lgkmcnt(1)
	v_pk_fma_f32 v[6:7], v[14:15], v[6:7], v[18:19]
	v_pk_fma_f32 v[8:9], v[16:17], v[8:9], v[20:21]
	s_waitcnt vmcnt(0) lgkmcnt(0)
	v_pk_fma_f32 v[10:11], v[10:11], v[2:3], v[22:23]
	v_pk_fma_f32 v[12:13], v[12:13], v[4:5], v[24:25]
	v_cvt_pk_bf16_f32 v2, v6, v7
	v_lshl_add_u64 v[6:7], s[66:67], 0, v[30:31]
	v_or3_b32 v28, v33, v32, 16
	v_cvt_pk_bf16_f32 v3, v8, v9
	v_cvt_pk_bf16_f32 v4, v10, v11
	v_cvt_pk_bf16_f32 v5, v12, v13
	v_lshl_add_u64 v[6:7], v[26:27], 1, v[6:7]
	v_add_u32_e32 v0, 0xfffff000, v28
	global_store_dwordx4 v[6:7], v[2:5], off sc1
	v_cmp_lt_i32_e64 s[42:43], s1, v28
	v_add_u32_e32 v35, 0x880, v35
	v_lshrrev_b32_e32 v2, 10, v0
	v_cndmask_b32_e64 v2, 4, v2, s[42:43]
	v_add_u32_e32 v4, s8, v2
	v_mov_b64_e32 v[2:3], s[14:15]
	v_mad_i64_i32 v[2:3], s[22:23], v4, s82, v[2:3]
	v_lshl_add_u64 v[2:3], v[26:27], 2, v[2:3]
	s_mov_b64 s[22:23], 0x8602000
	v_lshl_add_u64 v[4:5], v[2:3], 0, s[22:23]
	v_add_co_u32_e32 v2, vcc, 0x8602000, v2
	v_add3_u32 v10, v42, v35, v34
	s_nop 0
	v_addc_co_u32_e32 v3, vcc, 0, v3, vcc
	global_load_dwordx4 v[6:9], v[2:3], off
	s_nop 0
	global_load_dwordx4 v[2:5], v[4:5], off offset:16
	ds_read_b128 v[14:17], v10
	ds_read_b128 v[10:13], v10 offset:16
	s_and_b64 vcc, exec, s[40:41]
	s_mov_b64 s[22:23], -1
	s_cbranch_vccnz .LBB0_239
	v_ashrrev_i32_e32 v29, 31, v28
	v_lshlrev_b64 v[30:31], 11, v[28:29]
	v_lshl_add_u64 v[18:19], s[66:67], 0, v[30:31]
	v_lshl_add_u64 v[18:19], v[26:27], 1, v[18:19]
	global_load_dwordx4 v[22:25], v[18:19], off
	s_mov_b64 s[22:23], 0
	s_waitcnt vmcnt(0)
	v_lshlrev_b32_e32 v18, 16, v22
	v_and_b32_e32 v19, 0xffff0000, v22
	v_lshlrev_b32_e32 v20, 16, v23
	v_and_b32_e32 v21, 0xffff0000, v23
	v_lshlrev_b32_e32 v22, 16, v24
	v_and_b32_e32 v23, 0xffff0000, v24
	v_lshlrev_b32_e32 v24, 16, v25
	v_and_b32_e32 v25, 0xffff0000, v25

.LBB0_245:
	s_waitcnt vmcnt(1) lgkmcnt(1)
	v_pk_fma_f32 v[6:7], v[14:15], v[6:7], v[18:19]
	v_pk_fma_f32 v[8:9], v[16:17], v[8:9], v[20:21]
	s_waitcnt vmcnt(0) lgkmcnt(0)
	v_pk_fma_f32 v[10:11], v[10:11], v[2:3], v[22:23]
	v_pk_fma_f32 v[12:13], v[12:13], v[4:5], v[24:25]
	v_cvt_pk_bf16_f32 v2, v6, v7
	v_lshl_add_u64 v[6:7], s[66:67], 0, v[30:31]
	v_or3_b32 v28, v33, v32, 24
	v_cvt_pk_bf16_f32 v3, v8, v9
	v_cvt_pk_bf16_f32 v4, v10, v11
	v_cvt_pk_bf16_f32 v5, v12, v13
	v_lshl_add_u64 v[6:7], v[26:27], 1, v[6:7]
	v_add_u32_e32 v0, 0xfffff000, v28
	global_store_dwordx4 v[6:7], v[2:5], off sc1
	v_cmp_lt_i32_e64 s[42:43], s1, v28
	v_add_u32_e32 v35, 0x880, v35
	v_lshrrev_b32_e32 v2, 10, v0
	v_cndmask_b32_e64 v2, 4, v2, s[42:43]
	v_add_u32_e32 v4, s8, v2
	v_mov_b64_e32 v[2:3], s[14:15]
	v_mad_i64_i32 v[2:3], s[22:23], v4, s82, v[2:3]
	v_lshl_add_u64 v[2:3], v[26:27], 2, v[2:3]
	s_mov_b64 s[22:23], 0x8602000
	v_lshl_add_u64 v[4:5], v[2:3], 0, s[22:23]
	v_add_co_u32_e32 v2, vcc, 0x8602000, v2
	v_add3_u32 v10, v42, v35, v34
	s_nop 0
	v_addc_co_u32_e32 v3, vcc, 0, v3, vcc
	global_load_dwordx4 v[6:9], v[2:3], off
	s_nop 0
	global_load_dwordx4 v[2:5], v[4:5], off offset:16
	ds_read_b128 v[14:17], v10
	ds_read_b128 v[10:13], v10 offset:16
	s_and_b64 vcc, exec, s[40:41]
	s_mov_b64 s[22:23], -1
	s_cbranch_vccnz .LBB0_247
	v_ashrrev_i32_e32 v29, 31, v28
	v_lshlrev_b64 v[30:31], 11, v[28:29]
	v_lshl_add_u64 v[18:19], s[66:67], 0, v[30:31]
	v_lshl_add_u64 v[18:19], v[26:27], 1, v[18:19]
	global_load_dwordx4 v[22:25], v[18:19], off
	s_mov_b64 s[22:23], 0
	s_waitcnt vmcnt(0)
	v_lshlrev_b32_e32 v18, 16, v22
	v_and_b32_e32 v19, 0xffff0000, v22
	v_lshlrev_b32_e32 v20, 16, v23
	v_and_b32_e32 v21, 0xffff0000, v23
	v_lshlrev_b32_e32 v22, 16, v24
	v_and_b32_e32 v23, 0xffff0000, v24
	v_lshlrev_b32_e32 v24, 16, v25
	v_and_b32_e32 v25, 0xffff0000, v25

.LBB0_253:
	s_waitcnt vmcnt(1) lgkmcnt(1)
	v_pk_fma_f32 v[6:7], v[14:15], v[6:7], v[18:19]
	v_pk_fma_f32 v[8:9], v[16:17], v[8:9], v[20:21]
	s_waitcnt vmcnt(0) lgkmcnt(0)
	v_pk_fma_f32 v[10:11], v[10:11], v[2:3], v[22:23]
	v_pk_fma_f32 v[12:13], v[12:13], v[4:5], v[24:25]
	v_cvt_pk_bf16_f32 v2, v6, v7
	v_lshl_add_u64 v[6:7], s[66:67], 0, v[30:31]
	v_or3_b32 v28, v33, v32, 32
	v_cvt_pk_bf16_f32 v3, v8, v9
	v_cvt_pk_bf16_f32 v4, v10, v11
	v_cvt_pk_bf16_f32 v5, v12, v13
	v_lshl_add_u64 v[6:7], v[26:27], 1, v[6:7]
	v_add_u32_e32 v0, 0xfffff000, v28
	global_store_dwordx4 v[6:7], v[2:5], off sc1
	v_cmp_lt_i32_e64 s[42:43], s1, v28
	v_add_u32_e32 v35, 0x880, v35
	v_lshrrev_b32_e32 v2, 10, v0
	v_cndmask_b32_e64 v2, 4, v2, s[42:43]
	v_add_u32_e32 v4, s8, v2
	v_mov_b64_e32 v[2:3], s[14:15]
	v_mad_i64_i32 v[2:3], s[22:23], v4, s82, v[2:3]
	v_lshl_add_u64 v[2:3], v[26:27], 2, v[2:3]
	s_mov_b64 s[22:23], 0x8602000
	v_lshl_add_u64 v[4:5], v[2:3], 0, s[22:23]
	v_add_co_u32_e32 v2, vcc, 0x8602000, v2
	v_add3_u32 v10, v42, v35, v34
	s_nop 0
	v_addc_co_u32_e32 v3, vcc, 0, v3, vcc
	global_load_dwordx4 v[6:9], v[2:3], off
	s_nop 0
	global_load_dwordx4 v[2:5], v[4:5], off offset:16
	ds_read_b128 v[14:17], v10
	ds_read_b128 v[10:13], v10 offset:16
	s_and_b64 vcc, exec, s[40:41]
	s_mov_b64 s[22:23], -1
	s_cbranch_vccnz .LBB0_255
	v_ashrrev_i32_e32 v29, 31, v28
	v_lshlrev_b64 v[30:31], 11, v[28:29]
	v_lshl_add_u64 v[18:19], s[66:67], 0, v[30:31]
	v_lshl_add_u64 v[18:19], v[26:27], 1, v[18:19]
	global_load_dwordx4 v[22:25], v[18:19], off
	s_mov_b64 s[22:23], 0
	s_waitcnt vmcnt(0)
	v_lshlrev_b32_e32 v18, 16, v22
	v_and_b32_e32 v19, 0xffff0000, v22
	v_lshlrev_b32_e32 v20, 16, v23
	v_and_b32_e32 v21, 0xffff0000, v23
	v_lshlrev_b32_e32 v22, 16, v24
	v_and_b32_e32 v23, 0xffff0000, v24
	v_lshlrev_b32_e32 v24, 16, v25
	v_and_b32_e32 v25, 0xffff0000, v25

.LBB0_261:
	s_waitcnt vmcnt(1) lgkmcnt(1)
	v_pk_fma_f32 v[6:7], v[14:15], v[6:7], v[18:19]
	v_pk_fma_f32 v[8:9], v[16:17], v[8:9], v[20:21]
	s_waitcnt vmcnt(0) lgkmcnt(0)
	v_pk_fma_f32 v[10:11], v[10:11], v[2:3], v[22:23]
	v_pk_fma_f32 v[12:13], v[12:13], v[4:5], v[24:25]
	v_cvt_pk_bf16_f32 v2, v6, v7
	v_lshl_add_u64 v[6:7], s[66:67], 0, v[30:31]
	v_or3_b32 v28, v33, v32, 40
	v_cvt_pk_bf16_f32 v3, v8, v9
	v_cvt_pk_bf16_f32 v4, v10, v11
	v_cvt_pk_bf16_f32 v5, v12, v13
	v_lshl_add_u64 v[6:7], v[26:27], 1, v[6:7]
	v_add_u32_e32 v0, 0xfffff000, v28
	global_store_dwordx4 v[6:7], v[2:5], off sc1
	v_cmp_lt_i32_e64 s[42:43], s1, v28
	v_add_u32_e32 v35, 0x880, v35
	v_lshrrev_b32_e32 v2, 10, v0
	v_cndmask_b32_e64 v2, 4, v2, s[42:43]
	v_add_u32_e32 v4, s8, v2
	v_mov_b64_e32 v[2:3], s[14:15]
	v_mad_i64_i32 v[2:3], s[22:23], v4, s82, v[2:3]
	v_lshl_add_u64 v[2:3], v[26:27], 2, v[2:3]
	s_mov_b64 s[22:23], 0x8602000
	v_lshl_add_u64 v[4:5], v[2:3], 0, s[22:23]
	v_add_co_u32_e32 v2, vcc, 0x8602000, v2
	v_add3_u32 v10, v42, v35, v34
	s_nop 0
	v_addc_co_u32_e32 v3, vcc, 0, v3, vcc
	global_load_dwordx4 v[6:9], v[2:3], off
	s_nop 0
	global_load_dwordx4 v[2:5], v[4:5], off offset:16
	ds_read_b128 v[14:17], v10
	ds_read_b128 v[10:13], v10 offset:16
	s_and_b64 vcc, exec, s[40:41]
	s_mov_b64 s[22:23], -1
	s_cbranch_vccnz .LBB0_263
	v_ashrrev_i32_e32 v29, 31, v28
	v_lshlrev_b64 v[30:31], 11, v[28:29]
	v_lshl_add_u64 v[18:19], s[66:67], 0, v[30:31]
	v_lshl_add_u64 v[18:19], v[26:27], 1, v[18:19]
	global_load_dwordx4 v[22:25], v[18:19], off
	s_mov_b64 s[22:23], 0
	s_waitcnt vmcnt(0)
	v_lshlrev_b32_e32 v18, 16, v22
	v_and_b32_e32 v19, 0xffff0000, v22
	v_lshlrev_b32_e32 v20, 16, v23
	v_and_b32_e32 v21, 0xffff0000, v23
	v_lshlrev_b32_e32 v22, 16, v24
	v_and_b32_e32 v23, 0xffff0000, v24
	v_lshlrev_b32_e32 v24, 16, v25
	v_and_b32_e32 v25, 0xffff0000, v25

.LBB0_269:
	s_waitcnt vmcnt(1) lgkmcnt(1)
	v_pk_fma_f32 v[6:7], v[14:15], v[6:7], v[18:19]
	v_pk_fma_f32 v[8:9], v[16:17], v[8:9], v[20:21]
	s_waitcnt vmcnt(0) lgkmcnt(0)
	v_pk_fma_f32 v[10:11], v[10:11], v[2:3], v[22:23]
	v_pk_fma_f32 v[12:13], v[12:13], v[4:5], v[24:25]
	v_cvt_pk_bf16_f32 v2, v6, v7
	v_lshl_add_u64 v[6:7], s[66:67], 0, v[30:31]
	v_or3_b32 v28, v33, v32, 48
	v_cvt_pk_bf16_f32 v3, v8, v9
	v_cvt_pk_bf16_f32 v4, v10, v11
	v_cvt_pk_bf16_f32 v5, v12, v13
	v_lshl_add_u64 v[6:7], v[26:27], 1, v[6:7]
	v_add_u32_e32 v0, 0xfffff000, v28
	global_store_dwordx4 v[6:7], v[2:5], off sc1
	v_cmp_lt_i32_e64 s[42:43], s1, v28
	v_add_u32_e32 v10, 0x880, v35
	v_lshrrev_b32_e32 v2, 10, v0
	v_cndmask_b32_e64 v2, 4, v2, s[42:43]
	v_add_u32_e32 v4, s8, v2
	v_mov_b64_e32 v[2:3], s[14:15]
	v_mad_i64_i32 v[2:3], s[22:23], v4, s82, v[2:3]
	v_lshl_add_u64 v[2:3], v[26:27], 2, v[2:3]
	s_mov_b64 s[22:23], 0x8602000
	v_lshl_add_u64 v[4:5], v[2:3], 0, s[22:23]
	v_add_co_u32_e32 v2, vcc, 0x8602000, v2
	v_add3_u32 v34, v42, v10, v34
	s_nop 0
	v_addc_co_u32_e32 v3, vcc, 0, v3, vcc
	global_load_dwordx4 v[6:9], v[2:3], off
	s_nop 0
	global_load_dwordx4 v[2:5], v[4:5], off offset:16
	ds_read_b128 v[14:17], v34
	ds_read_b128 v[10:13], v34 offset:16
	s_and_b64 vcc, exec, s[40:41]
	s_mov_b64 s[22:23], -1
	s_cbranch_vccnz .LBB0_271
	v_ashrrev_i32_e32 v29, 31, v28
	v_lshlrev_b64 v[30:31], 11, v[28:29]
	v_lshl_add_u64 v[18:19], s[66:67], 0, v[30:31]
	v_lshl_add_u64 v[18:19], v[26:27], 1, v[18:19]
	global_load_dwordx4 v[22:25], v[18:19], off
	s_mov_b64 s[22:23], 0
	s_waitcnt vmcnt(0)
	v_lshlrev_b32_e32 v18, 16, v22
	v_and_b32_e32 v19, 0xffff0000, v22
	v_lshlrev_b32_e32 v20, 16, v23
	v_and_b32_e32 v21, 0xffff0000, v23
	v_lshlrev_b32_e32 v22, 16, v24
	v_and_b32_e32 v23, 0xffff0000, v24
	v_lshlrev_b32_e32 v24, 16, v25
	v_and_b32_e32 v25, 0xffff0000, v25

.LBB0_277:
	s_waitcnt vmcnt(1) lgkmcnt(1)
	v_pk_fma_f32 v[6:7], v[14:15], v[6:7], v[18:19]
	v_pk_fma_f32 v[8:9], v[16:17], v[8:9], v[20:21]
	s_waitcnt vmcnt(0) lgkmcnt(0)
	v_pk_fma_f32 v[10:11], v[10:11], v[2:3], v[22:23]
	v_pk_fma_f32 v[12:13], v[12:13], v[4:5], v[24:25]
	v_cvt_pk_bf16_f32 v2, v6, v7
	v_lshl_add_u64 v[6:7], s[66:67], 0, v[30:31]
	v_or3_b32 v28, v33, v32, 56
	v_cvt_pk_bf16_f32 v3, v8, v9
	v_cvt_pk_bf16_f32 v4, v10, v11
	v_cvt_pk_bf16_f32 v5, v12, v13
	v_lshl_add_u64 v[6:7], v[26:27], 1, v[6:7]
	v_add_u32_e32 v0, 0xfffff000, v28
	global_store_dwordx4 v[6:7], v[2:5], off sc1
	v_cmp_lt_i32_e64 s[42:43], s1, v28
	s_nop 0
	v_lshrrev_b32_e32 v2, 10, v0
	v_cndmask_b32_e64 v2, 4, v2, s[42:43]
	v_add_u32_e32 v4, s8, v2
	v_mov_b64_e32 v[2:3], s[14:15]
	v_mad_i64_i32 v[2:3], s[22:23], v4, s82, v[2:3]
	v_lshl_add_u64 v[2:3], v[26:27], 2, v[2:3]
	s_mov_b64 s[22:23], 0x8602000
	v_lshl_add_u64 v[4:5], v[2:3], 0, s[22:23]
	v_add_co_u32_e32 v2, vcc, 0x8602000, v2
	s_mov_b64 s[22:23], -1
	s_nop 0
	v_addc_co_u32_e32 v3, vcc, 0, v3, vcc
	global_load_dwordx4 v[6:9], v[2:3], off
	s_nop 0
	global_load_dwordx4 v[2:5], v[4:5], off offset:16
	ds_read_b128 v[14:17], v34 offset:2176
	ds_read_b128 v[10:13], v34 offset:2192
	s_and_b64 vcc, exec, s[40:41]
	s_cbranch_vccnz .LBB0_279
	v_ashrrev_i32_e32 v29, 31, v28
	v_lshlrev_b64 v[30:31], 11, v[28:29]
	v_lshl_add_u64 v[18:19], s[66:67], 0, v[30:31]
	v_lshl_add_u64 v[18:19], v[26:27], 1, v[18:19]
	global_load_dwordx4 v[22:25], v[18:19], off
	s_mov_b64 s[22:23], 0
	s_waitcnt vmcnt(0)
	v_lshlrev_b32_e32 v18, 16, v22
	v_and_b32_e32 v19, 0xffff0000, v22
	v_lshlrev_b32_e32 v20, 16, v23
	v_and_b32_e32 v21, 0xffff0000, v23
	v_lshlrev_b32_e32 v22, 16, v24
	v_and_b32_e32 v23, 0xffff0000, v24
	v_lshlrev_b32_e32 v24, 16, v25
	v_and_b32_e32 v25, 0xffff0000, v25

.LBB0_307:
	s_or_b64 exec, exec, s[20:21]
	s_add_i32 s8, s16, 6
	s_cmp_gt_u32 s8, 14
	s_movk_i32 s8, 0x4400
	v_mul_lo_u32 v42, v136, s8
	v_lshl_or_b32 v3, v138, 2, v42
	s_movk_i32 s8, 0x440
	v_mad_u32_u24 v3, v135, s8, v3
	v_add_u32_e32 v4, 0x1000, v3
	v_add_u32_e32 v5, 0x1400, v3
	s_waitcnt vmcnt(0) lgkmcnt(0)
	s_barrier
	ds_write2_b32 v3, v102, v90 offset1:16
	ds_write2_b32 v3, v103, v91 offset0:68 offset1:84
	ds_write2_b32 v3, v104, v92 offset0:136 offset1:152
	ds_write2_b32 v3, v105, v93 offset0:204 offset1:220
	ds_write2_b32 v3, v74, v94 offset0:32 offset1:48
	ds_write2_b32 v3, v75, v95 offset0:100 offset1:116
	ds_write2_b32 v3, v76, v96 offset0:168 offset1:184
	ds_write2_b32 v3, v77, v97 offset0:236 offset1:252
	ds_write2_b32 v4, v98, v78 offset0:64 offset1:80
	ds_write2_b32 v4, v99, v79 offset0:132 offset1:148
	ds_write2_b32 v4, v100, v80 offset0:200 offset1:216
	ds_write2_b32 v5, v101, v81 offset0:12 offset1:28
	ds_write2_b32 v4, v58, v82 offset0:96 offset1:112
	ds_write2_b32 v4, v59, v83 offset0:164 offset1:180
	ds_write2_b32 v4, v60, v84 offset0:232 offset1:248
	ds_write2_b32 v5, v61, v85 offset0:44 offset1:60
	v_add_u32_e32 v4, 0x2000, v3
	v_add_u32_e32 v5, 0x2400, v3
	ds_write2_b32 v4, v86, v62 offset0:128 offset1:144
	ds_write2_b32 v4, v87, v63 offset0:196 offset1:212
	ds_write2_b32 v5, v88, v64 offset0:8 offset1:24
	ds_write2_b32 v5, v89, v65 offset0:76 offset1:92
	ds_write2_b32 v4, v38, v66 offset0:160 offset1:176
	ds_write2_b32 v4, v39, v67 offset0:228 offset1:244
	ds_write2_b32 v5, v40, v68 offset0:40 offset1:56
	ds_write2_b32 v5, v41, v69 offset0:108 offset1:124
	v_add_u32_e32 v4, 0x3000, v3
	v_add_u32_e32 v3, 0x3400, v3
	v_readlane_b32 s8, v254, 46
	ds_write2_b32 v4, v70, v46 offset0:192 offset1:208
	ds_write2_b32 v3, v71, v47 offset0:4 offset1:20
	ds_write2_b32 v3, v72, v48 offset0:72 offset1:88
	ds_write2_b32 v3, v73, v49 offset0:140 offset1:156
	ds_write2_b32 v4, v30, v34 offset0:224 offset1:240
	ds_write2_b32 v3, v31, v35 offset0:36 offset1:52
	ds_write2_b32 v3, v32, v36 offset0:104 offset1:120
	ds_write2_b32 v3, v33, v37 offset0:172 offset1:188
	v_lshl_add_u32 v34, v0, 6, s8
	v_lshrrev_b32_e32 v35, 3, v134
	v_lshlrev_b32_e32 v0, 3, v134
	v_or_b32_e32 v28, v34, v35
	v_lshlrev_b32_e32 v2, 6, v139
	v_and_b32_e32 v0, 56, v0
	v_readlane_b32 s8, v254, 47
	v_add_u32_e32 v30, 0xfffff000, v28
	v_cmp_lt_i32_e64 s[40:41], s1, v28
	v_or3_b32 v18, v2, s8, v0
	v_lshrrev_b32_e32 v2, 10, v30
	v_cndmask_b32_e64 v2, 4, v2, s[40:41]
	s_mul_i32 s8, s18, 5
	v_add_u32_e32 v4, s8, v2
	s_cselect_b64 s[20:21], -1, 0
	v_mov_b64_e32 v[2:3], s[14:15]
	v_mad_i64_i32 v[2:3], s[22:23], v4, s82, v[2:3]
	v_lshlrev_b32_e32 v26, 2, v18
	v_mov_b32_e32 v27, v1
	v_lshl_add_u64 v[10:11], v[2:3], 0, v[26:27]
	s_mov_b64 s[22:23], 0x8602000
	v_lshl_add_u64 v[10:11], v[10:11], 0, s[22:23]
	global_load_dwordx4 v[108:111], v[10:11], off
	global_load_dwordx4 v[112:115], v[10:11], off offset:16
	v_mul_u32_u24_e32 v37, 0x110, v35
	v_lshlrev_b32_e32 v36, 2, v0
	v_add3_u32 v8, v42, v37, v36
	v_lshlrev_b32_e32 v0, 1, v18
	v_mov_b32_e32 v10, v28
	v_ashrrev_i32_e32 v11, 31, v10
	v_lshlrev_b64 v[10:11], 11, v[10:11]
	v_lshl_add_u64 v[10:11], s[66:67], 0, v[10:11]
	v_lshl_add_u64 v[116:117], v[10:11], 0, v[0:1]
	v_or3_b32 v10, v35, v34, 8
	v_ashrrev_i32_e32 v11, 31, v10
	v_lshlrev_b64 v[10:11], 11, v[10:11]
	v_lshl_add_u64 v[10:11], s[66:67], 0, v[10:11]
	v_lshl_add_u64 v[118:119], v[10:11], 0, v[0:1]
	v_or3_b32 v10, v35, v34, 16
	v_ashrrev_i32_e32 v11, 31, v10
	v_lshlrev_b64 v[10:11], 11, v[10:11]
	v_lshl_add_u64 v[10:11], s[66:67], 0, v[10:11]
	v_lshl_add_u64 v[120:121], v[10:11], 0, v[0:1]
	v_or3_b32 v10, v35, v34, 24
	v_ashrrev_i32_e32 v11, 31, v10
	v_lshlrev_b64 v[10:11], 11, v[10:11]
	v_lshl_add_u64 v[10:11], s[66:67], 0, v[10:11]
	v_lshl_add_u64 v[122:123], v[10:11], 0, v[0:1]
	v_or3_b32 v10, v35, v34, 32
	v_ashrrev_i32_e32 v11, 31, v10
	v_lshlrev_b64 v[10:11], 11, v[10:11]
	v_lshl_add_u64 v[10:11], s[66:67], 0, v[10:11]
	v_lshl_add_u64 v[124:125], v[10:11], 0, v[0:1]
	v_or3_b32 v10, v35, v34, 40
	v_ashrrev_i32_e32 v11, 31, v10
	v_lshlrev_b64 v[10:11], 11, v[10:11]
	v_lshl_add_u64 v[10:11], s[66:67], 0, v[10:11]
	v_lshl_add_u64 v[126:127], v[10:11], 0, v[0:1]
	v_or3_b32 v10, v35, v34, 48
	v_ashrrev_i32_e32 v11, 31, v10
	v_lshlrev_b64 v[10:11], 11, v[10:11]
	v_lshl_add_u64 v[10:11], s[66:67], 0, v[10:11]
	v_lshl_add_u64 v[128:129], v[10:11], 0, v[0:1]
	v_or3_b32 v10, v35, v34, 56
	v_ashrrev_i32_e32 v11, 31, v10
	v_lshlrev_b64 v[10:11], 11, v[10:11]
	v_lshl_add_u64 v[10:11], s[66:67], 0, v[10:11]
	v_lshl_add_u64 v[130:131], v[10:11], 0, v[0:1]
	s_and_b64 vcc, exec, s[20:21]
	s_cbranch_vccz .Lg3_from_input
	global_load_dwordx4 v[44:47], v[116:117], off
	global_load_dwordx4 v[48:51], v[118:119], off
	global_load_dwordx4 v[52:55], v[120:121], off
	global_load_dwordx4 v[56:59], v[122:123], off
	global_load_dwordx4 v[60:63], v[124:125], off
	global_load_dwordx4 v[64:67], v[126:127], off
	global_load_dwordx4 v[68:71], v[128:129], off
	global_load_dwordx4 v[72:75], v[130:131], off
	ds_read_b128 v[132:135], v8
	ds_read_b128 v[136:139], v8 offset:16
	ds_read_b128 v[140:143], v8 offset:2176
	ds_read_b128 v[144:147], v8 offset:2192
	s_waitcnt vmcnt(7)
	v_lshlrev_b32_e32 v148, 16, v44
	v_and_b32_e32 v149, 0xffff0000, v44
	v_lshlrev_b32_e32 v150, 16, v45
	v_and_b32_e32 v151, 0xffff0000, v45
	v_lshlrev_b32_e32 v152, 16, v46
	v_and_b32_e32 v153, 0xffff0000, v46
	v_lshlrev_b32_e32 v154, 16, v47
	v_and_b32_e32 v155, 0xffff0000, v47
	s_waitcnt lgkmcnt(2)
	v_pk_fma_f32 v[148:149], v[132:133], v[108:109], v[148:149]
	v_pk_fma_f32 v[150:151], v[134:135], v[110:111], v[150:151]
	v_pk_fma_f32 v[152:153], v[136:137], v[112:113], v[152:153]
	v_pk_fma_f32 v[154:155], v[138:139], v[114:115], v[154:155]
	v_cvt_pk_bf16_f32 v164, v148, v149
	v_cvt_pk_bf16_f32 v165, v150, v151
	v_cvt_pk_bf16_f32 v166, v152, v153
	v_cvt_pk_bf16_f32 v167, v154, v155
	global_store_dwordx4 v[116:117], v[164:167], off sc1
	ds_read_b128 v[132:135], v8 offset:4352
	ds_read_b128 v[136:139], v8 offset:4368
	s_waitcnt vmcnt(7)
	v_lshlrev_b32_e32 v156, 16, v48
	v_and_b32_e32 v157, 0xffff0000, v48
	v_lshlrev_b32_e32 v158, 16, v49
	v_and_b32_e32 v159, 0xffff0000, v49
	v_lshlrev_b32_e32 v160, 16, v50
	v_and_b32_e32 v161, 0xffff0000, v50
	v_lshlrev_b32_e32 v162, 16, v51
	v_and_b32_e32 v163, 0xffff0000, v51
	s_waitcnt lgkmcnt(2)
	v_pk_fma_f32 v[156:157], v[140:141], v[108:109], v[156:157]
	v_pk_fma_f32 v[158:159], v[142:143], v[110:111], v[158:159]
	v_pk_fma_f32 v[160:161], v[144:145], v[112:113], v[160:161]
	v_pk_fma_f32 v[162:163], v[146:147], v[114:115], v[162:163]
	v_cvt_pk_bf16_f32 v168, v156, v157
	v_cvt_pk_bf16_f32 v169, v158, v159
	v_cvt_pk_bf16_f32 v170, v160, v161
	v_cvt_pk_bf16_f32 v171, v162, v163
	global_store_dwordx4 v[118:119], v[168:171], off sc1
	ds_read_b128 v[140:143], v8 offset:6528
	ds_read_b128 v[144:147], v8 offset:6544
	s_waitcnt vmcnt(7)
	v_lshlrev_b32_e32 v148, 16, v52
	v_and_b32_e32 v149, 0xffff0000, v52
	v_lshlrev_b32_e32 v150, 16, v53
	v_and_b32_e32 v151, 0xffff0000, v53
	v_lshlrev_b32_e32 v152, 16, v54
	v_and_b32_e32 v153, 0xffff0000, v54
	v_lshlrev_b32_e32 v154, 16, v55
	v_and_b32_e32 v155, 0xffff0000, v55
	s_waitcnt lgkmcnt(2)
	v_pk_fma_f32 v[148:149], v[132:133], v[108:109], v[148:149]
	v_pk_fma_f32 v[150:151], v[134:135], v[110:111], v[150:151]
	v_pk_fma_f32 v[152:153], v[136:137], v[112:113], v[152:153]
	v_pk_fma_f32 v[154:155], v[138:139], v[114:115], v[154:155]
	v_cvt_pk_bf16_f32 v164, v148, v149
	v_cvt_pk_bf16_f32 v165, v150, v151
	v_cvt_pk_bf16_f32 v166, v152, v153
	v_cvt_pk_bf16_f32 v167, v154, v155
	global_store_dwordx4 v[120:121], v[164:167], off sc1
	ds_read_b128 v[132:135], v8 offset:8704
	ds_read_b128 v[136:139], v8 offset:8720
	s_waitcnt vmcnt(7)
	v_lshlrev_b32_e32 v156, 16, v56
	v_and_b32_e32 v157, 0xffff0000, v56
	v_lshlrev_b32_e32 v158, 16, v57
	v_and_b32_e32 v159, 0xffff0000, v57
	v_lshlrev_b32_e32 v160, 16, v58
	v_and_b32_e32 v161, 0xffff0000, v58
	v_lshlrev_b32_e32 v162, 16, v59
	v_and_b32_e32 v163, 0xffff0000, v59
	s_waitcnt lgkmcnt(2)
	v_pk_fma_f32 v[156:157], v[140:141], v[108:109], v[156:157]
	v_pk_fma_f32 v[158:159], v[142:143], v[110:111], v[158:159]
	v_pk_fma_f32 v[160:161], v[144:145], v[112:113], v[160:161]
	v_pk_fma_f32 v[162:163], v[146:147], v[114:115], v[162:163]
	v_cvt_pk_bf16_f32 v168, v156, v157
	v_cvt_pk_bf16_f32 v169, v158, v159
	v_cvt_pk_bf16_f32 v170, v160, v161
	v_cvt_pk_bf16_f32 v171, v162, v163
	global_store_dwordx4 v[122:123], v[168:171], off sc1
	ds_read_b128 v[140:143], v8 offset:10880
	ds_read_b128 v[144:147], v8 offset:10896
	s_waitcnt vmcnt(7)
	v_lshlrev_b32_e32 v148, 16, v60
	v_and_b32_e32 v149, 0xffff0000, v60
	v_lshlrev_b32_e32 v150, 16, v61
	v_and_b32_e32 v151, 0xffff0000, v61
	v_lshlrev_b32_e32 v152, 16, v62
	v_and_b32_e32 v153, 0xffff0000, v62
	v_lshlrev_b32_e32 v154, 16, v63
	v_and_b32_e32 v155, 0xffff0000, v63
	s_waitcnt lgkmcnt(2)
	v_pk_fma_f32 v[148:149], v[132:133], v[108:109], v[148:149]
	v_pk_fma_f32 v[150:151], v[134:135], v[110:111], v[150:151]
	v_pk_fma_f32 v[152:153], v[136:137], v[112:113], v[152:153]
	v_pk_fma_f32 v[154:155], v[138:139], v[114:115], v[154:155]
	v_cvt_pk_bf16_f32 v164, v148, v149
	v_cvt_pk_bf16_f32 v165, v150, v151
	v_cvt_pk_bf16_f32 v166, v152, v153
	v_cvt_pk_bf16_f32 v167, v154, v155
	global_store_dwordx4 v[124:125], v[164:167], off sc1
	ds_read_b128 v[132:135], v8 offset:13056
	ds_read_b128 v[136:139], v8 offset:13072
	s_waitcnt vmcnt(7)
	v_lshlrev_b32_e32 v156, 16, v64
	v_and_b32_e32 v157, 0xffff0000, v64
	v_lshlrev_b32_e32 v158, 16, v65
	v_and_b32_e32 v159, 0xffff0000, v65
	v_lshlrev_b32_e32 v160, 16, v66
	v_and_b32_e32 v161, 0xffff0000, v66
	v_lshlrev_b32_e32 v162, 16, v67
	v_and_b32_e32 v163, 0xffff0000, v67
	s_waitcnt lgkmcnt(2)
	v_pk_fma_f32 v[156:157], v[140:141], v[108:109], v[156:157]
	v_pk_fma_f32 v[158:159], v[142:143], v[110:111], v[158:159]
	v_pk_fma_f32 v[160:161], v[144:145], v[112:113], v[160:161]
	v_pk_fma_f32 v[162:163], v[146:147], v[114:115], v[162:163]
	v_cvt_pk_bf16_f32 v168, v156, v157
	v_cvt_pk_bf16_f32 v169, v158, v159
	v_cvt_pk_bf16_f32 v170, v160, v161
	v_cvt_pk_bf16_f32 v171, v162, v163
	global_store_dwordx4 v[126:127], v[168:171], off sc1
	ds_read_b128 v[140:143], v8 offset:15232
	ds_read_b128 v[144:147], v8 offset:15248
	s_waitcnt vmcnt(7)
	v_lshlrev_b32_e32 v148, 16, v68
	v_and_b32_e32 v149, 0xffff0000, v68
	v_lshlrev_b32_e32 v150, 16, v69
	v_and_b32_e32 v151, 0xffff0000, v69
	v_lshlrev_b32_e32 v152, 16, v70
	v_and_b32_e32 v153, 0xffff0000, v70
	v_lshlrev_b32_e32 v154, 16, v71
	v_and_b32_e32 v155, 0xffff0000, v71
	s_waitcnt lgkmcnt(2)
	v_pk_fma_f32 v[148:149], v[132:133], v[108:109], v[148:149]
	v_pk_fma_f32 v[150:151], v[134:135], v[110:111], v[150:151]
	v_pk_fma_f32 v[152:153], v[136:137], v[112:113], v[152:153]
	v_pk_fma_f32 v[154:155], v[138:139], v[114:115], v[154:155]
	v_cvt_pk_bf16_f32 v164, v148, v149
	v_cvt_pk_bf16_f32 v165, v150, v151
	v_cvt_pk_bf16_f32 v166, v152, v153
	v_cvt_pk_bf16_f32 v167, v154, v155
	global_store_dwordx4 v[128:129], v[164:167], off sc1
	s_waitcnt vmcnt(7)
	v_lshlrev_b32_e32 v156, 16, v72
	v_and_b32_e32 v157, 0xffff0000, v72
	v_lshlrev_b32_e32 v158, 16, v73
	v_and_b32_e32 v159, 0xffff0000, v73
	v_lshlrev_b32_e32 v160, 16, v74
	v_and_b32_e32 v161, 0xffff0000, v74
	v_lshlrev_b32_e32 v162, 16, v75
	v_and_b32_e32 v163, 0xffff0000, v75
	s_waitcnt lgkmcnt(0)
	v_pk_fma_f32 v[156:157], v[140:141], v[108:109], v[156:157]
	v_pk_fma_f32 v[158:159], v[142:143], v[110:111], v[158:159]
	v_pk_fma_f32 v[160:161], v[144:145], v[112:113], v[160:161]
	v_pk_fma_f32 v[162:163], v[146:147], v[114:115], v[162:163]
	v_cvt_pk_bf16_f32 v168, v156, v157
	v_cvt_pk_bf16_f32 v169, v158, v159
	v_cvt_pk_bf16_f32 v170, v160, v161
	v_cvt_pk_bf16_f32 v171, v162, v163
	global_store_dwordx4 v[130:131], v[168:171], off sc1
	s_branch .LBB0_372
.Lg3_from_input:
	v_readlane_b32 s36, v254, 32
	v_readlane_b32 s37, v254, 33
	v_readlane_b32 s38, v254, 34
	v_readlane_b32 s39, v254, 35
	s_nop 3
	v_mov_b32_e32 v12, s36
	v_mov_b32_e32 v13, s37
	v_mov_b32_e32 v14, s38
	v_mov_b32_e32 v15, s39
	v_cndmask_b32_e64 v12, v12, v14, s[40:41]
	v_cndmask_b32_e64 v13, v13, v15, s[40:41]
	v_mov_b32_e32 v10, v28
	v_add_u32_e32 v11, 0xfffff000, v10
	v_cndmask_b32_e64 v10, v10, v11, s[40:41]
	v_mov_b32_e32 v11, v1
	v_lshlrev_b64 v[10:11], 12, v[10:11]
	v_lshl_add_u64 v[10:11], v[12:13], 0, v[10:11]
	v_lshl_add_u64 v[10:11], v[10:11], 0, v[26:27]
	global_load_dwordx4 v[44:47], v[10:11], off nt
	global_load_dwordx4 v[48:51], v[10:11], off offset:16 nt
	v_or3_b32 v10, v35, v34, 8
	v_add_u32_e32 v11, 0xfffff000, v10
	v_cndmask_b32_e64 v10, v10, v11, s[40:41]
	v_mov_b32_e32 v11, v1
	v_lshlrev_b64 v[10:11], 12, v[10:11]
	v_lshl_add_u64 v[10:11], v[12:13], 0, v[10:11]
	v_lshl_add_u64 v[10:11], v[10:11], 0, v[26:27]
	global_load_dwordx4 v[52:55], v[10:11], off nt
	global_load_dwordx4 v[56:59], v[10:11], off offset:16 nt
	v_or3_b32 v10, v35, v34, 16
	v_add_u32_e32 v11, 0xfffff000, v10
	v_cndmask_b32_e64 v10, v10, v11, s[40:41]
	v_mov_b32_e32 v11, v1
	v_lshlrev_b64 v[10:11], 12, v[10:11]
	v_lshl_add_u64 v[10:11], v[12:13], 0, v[10:11]
	v_lshl_add_u64 v[10:11], v[10:11], 0, v[26:27]
	global_load_dwordx4 v[60:63], v[10:11], off nt
	global_load_dwordx4 v[64:67], v[10:11], off offset:16 nt
	v_or3_b32 v10, v35, v34, 24
	v_add_u32_e32 v11, 0xfffff000, v10
	v_cndmask_b32_e64 v10, v10, v11, s[40:41]
	v_mov_b32_e32 v11, v1
	v_lshlrev_b64 v[10:11], 12, v[10:11]
	v_lshl_add_u64 v[10:11], v[12:13], 0, v[10:11]
	v_lshl_add_u64 v[10:11], v[10:11], 0, v[26:27]
	global_load_dwordx4 v[68:71], v[10:11], off nt
	global_load_dwordx4 v[72:75], v[10:11], off offset:16 nt
	v_or3_b32 v10, v35, v34, 32
	v_add_u32_e32 v11, 0xfffff000, v10
	v_cndmask_b32_e64 v10, v10, v11, s[40:41]
	v_mov_b32_e32 v11, v1
	v_lshlrev_b64 v[10:11], 12, v[10:11]
	v_lshl_add_u64 v[10:11], v[12:13], 0, v[10:11]
	v_lshl_add_u64 v[10:11], v[10:11], 0, v[26:27]
	global_load_dwordx4 v[76:79], v[10:11], off nt
	global_load_dwordx4 v[80:83], v[10:11], off offset:16 nt
	v_or3_b32 v10, v35, v34, 40
	v_add_u32_e32 v11, 0xfffff000, v10
	v_cndmask_b32_e64 v10, v10, v11, s[40:41]
	v_mov_b32_e32 v11, v1
	v_lshlrev_b64 v[10:11], 12, v[10:11]
	v_lshl_add_u64 v[10:11], v[12:13], 0, v[10:11]
	v_lshl_add_u64 v[10:11], v[10:11], 0, v[26:27]
	global_load_dwordx4 v[84:87], v[10:11], off nt
	global_load_dwordx4 v[88:91], v[10:11], off offset:16 nt
	v_or3_b32 v10, v35, v34, 48
	v_add_u32_e32 v11, 0xfffff000, v10
	v_cndmask_b32_e64 v10, v10, v11, s[40:41]
	v_mov_b32_e32 v11, v1
	v_lshlrev_b64 v[10:11], 12, v[10:11]
	v_lshl_add_u64 v[10:11], v[12:13], 0, v[10:11]
	v_lshl_add_u64 v[10:11], v[10:11], 0, v[26:27]
	global_load_dwordx4 v[92:95], v[10:11], off nt
	global_load_dwordx4 v[96:99], v[10:11], off offset:16 nt
	v_or3_b32 v10, v35, v34, 56
	v_add_u32_e32 v11, 0xfffff000, v10
	v_cndmask_b32_e64 v10, v10, v11, s[40:41]
	v_mov_b32_e32 v11, v1
	v_lshlrev_b64 v[10:11], 12, v[10:11]
	v_lshl_add_u64 v[10:11], v[12:13], 0, v[10:11]
	v_lshl_add_u64 v[10:11], v[10:11], 0, v[26:27]
	global_load_dwordx4 v[100:103], v[10:11], off nt
	global_load_dwordx4 v[104:107], v[10:11], off offset:16 nt
	ds_read_b128 v[132:135], v8
	ds_read_b128 v[136:139], v8 offset:16
	ds_read_b128 v[140:143], v8 offset:2176
	ds_read_b128 v[144:147], v8 offset:2192
	s_waitcnt vmcnt(14)
	s_waitcnt lgkmcnt(2)
	v_pk_fma_f32 v[148:149], v[132:133], v[108:109], v[44:45]
	v_pk_fma_f32 v[150:151], v[134:135], v[110:111], v[46:47]
	v_pk_fma_f32 v[152:153], v[136:137], v[112:113], v[48:49]
	v_pk_fma_f32 v[154:155], v[138:139], v[114:115], v[50:51]
	v_cvt_pk_bf16_f32 v164, v148, v149
	v_cvt_pk_bf16_f32 v165, v150, v151
	v_cvt_pk_bf16_f32 v166, v152, v153
	v_cvt_pk_bf16_f32 v167, v154, v155
	global_store_dwordx4 v[116:117], v[164:167], off sc1
	ds_read_b128 v[132:135], v8 offset:4352
	ds_read_b128 v[136:139], v8 offset:4368
	s_waitcnt vmcnt(13)
	s_waitcnt lgkmcnt(2)
	v_pk_fma_f32 v[156:157], v[140:141], v[108:109], v[52:53]
	v_pk_fma_f32 v[158:159], v[142:143], v[110:111], v[54:55]
	v_pk_fma_f32 v[160:161], v[144:145], v[112:113], v[56:57]
	v_pk_fma_f32 v[162:163], v[146:147], v[114:115], v[58:59]
	v_cvt_pk_bf16_f32 v168, v156, v157
	v_cvt_pk_bf16_f32 v169, v158, v159
	v_cvt_pk_bf16_f32 v170, v160, v161
	v_cvt_pk_bf16_f32 v171, v162, v163
	global_store_dwordx4 v[118:119], v[168:171], off sc1
	ds_read_b128 v[140:143], v8 offset:6528
	ds_read_b128 v[144:147], v8 offset:6544
	s_waitcnt vmcnt(12)
	s_waitcnt lgkmcnt(2)
	v_pk_fma_f32 v[148:149], v[132:133], v[108:109], v[60:61]
	v_pk_fma_f32 v[150:151], v[134:135], v[110:111], v[62:63]
	v_pk_fma_f32 v[152:153], v[136:137], v[112:113], v[64:65]
	v_pk_fma_f32 v[154:155], v[138:139], v[114:115], v[66:67]
	v_cvt_pk_bf16_f32 v164, v148, v149
	v_cvt_pk_bf16_f32 v165, v150, v151
	v_cvt_pk_bf16_f32 v166, v152, v153
	v_cvt_pk_bf16_f32 v167, v154, v155
	global_store_dwordx4 v[120:121], v[164:167], off sc1
	ds_read_b128 v[132:135], v8 offset:8704
	ds_read_b128 v[136:139], v8 offset:8720
	s_waitcnt vmcnt(11)
	s_waitcnt lgkmcnt(2)
	v_pk_fma_f32 v[156:157], v[140:141], v[108:109], v[68:69]
	v_pk_fma_f32 v[158:159], v[142:143], v[110:111], v[70:71]
	v_pk_fma_f32 v[160:161], v[144:145], v[112:113], v[72:73]
	v_pk_fma_f32 v[162:163], v[146:147], v[114:115], v[74:75]
	v_cvt_pk_bf16_f32 v168, v156, v157
	v_cvt_pk_bf16_f32 v169, v158, v159
	v_cvt_pk_bf16_f32 v170, v160, v161
	v_cvt_pk_bf16_f32 v171, v162, v163
	global_store_dwordx4 v[122:123], v[168:171], off sc1
	ds_read_b128 v[140:143], v8 offset:10880
	ds_read_b128 v[144:147], v8 offset:10896
	s_waitcnt vmcnt(10)
	s_waitcnt lgkmcnt(2)
	v_pk_fma_f32 v[148:149], v[132:133], v[108:109], v[76:77]
	v_pk_fma_f32 v[150:151], v[134:135], v[110:111], v[78:79]
	v_pk_fma_f32 v[152:153], v[136:137], v[112:113], v[80:81]
	v_pk_fma_f32 v[154:155], v[138:139], v[114:115], v[82:83]
	v_cvt_pk_bf16_f32 v164, v148, v149
	v_cvt_pk_bf16_f32 v165, v150, v151
	v_cvt_pk_bf16_f32 v166, v152, v153
	v_cvt_pk_bf16_f32 v167, v154, v155
	global_store_dwordx4 v[124:125], v[164:167], off sc1
	ds_read_b128 v[132:135], v8 offset:13056
	ds_read_b128 v[136:139], v8 offset:13072
	s_waitcnt vmcnt(9)
	s_waitcnt lgkmcnt(2)
	v_pk_fma_f32 v[156:157], v[140:141], v[108:109], v[84:85]
	v_pk_fma_f32 v[158:159], v[142:143], v[110:111], v[86:87]
	v_pk_fma_f32 v[160:161], v[144:145], v[112:113], v[88:89]
	v_pk_fma_f32 v[162:163], v[146:147], v[114:115], v[90:91]
	v_cvt_pk_bf16_f32 v168, v156, v157
	v_cvt_pk_bf16_f32 v169, v158, v159
	v_cvt_pk_bf16_f32 v170, v160, v161
	v_cvt_pk_bf16_f32 v171, v162, v163
	global_store_dwordx4 v[126:127], v[168:171], off sc1
	ds_read_b128 v[140:143], v8 offset:15232
	ds_read_b128 v[144:147], v8 offset:15248
	s_waitcnt vmcnt(8)
	s_waitcnt lgkmcnt(2)
	v_pk_fma_f32 v[148:149], v[132:133], v[108:109], v[92:93]
	v_pk_fma_f32 v[150:151], v[134:135], v[110:111], v[94:95]
	v_pk_fma_f32 v[152:153], v[136:137], v[112:113], v[96:97]
	v_pk_fma_f32 v[154:155], v[138:139], v[114:115], v[98:99]
	v_cvt_pk_bf16_f32 v164, v148, v149
	v_cvt_pk_bf16_f32 v165, v150, v151
	v_cvt_pk_bf16_f32 v166, v152, v153
	v_cvt_pk_bf16_f32 v167, v154, v155
	global_store_dwordx4 v[128:129], v[164:167], off sc1
	s_waitcnt vmcnt(7)
	s_waitcnt lgkmcnt(0)
	v_pk_fma_f32 v[156:157], v[140:141], v[108:109], v[100:101]
	v_pk_fma_f32 v[158:159], v[142:143], v[110:111], v[102:103]
	v_pk_fma_f32 v[160:161], v[144:145], v[112:113], v[104:105]
	v_pk_fma_f32 v[162:163], v[146:147], v[114:115], v[106:107]
	v_cvt_pk_bf16_f32 v168, v156, v157
	v_cvt_pk_bf16_f32 v169, v158, v159
	v_cvt_pk_bf16_f32 v170, v160, v161
	v_cvt_pk_bf16_f32 v171, v162, v163
	global_store_dwordx4 v[130:131], v[168:171], off sc1

.LBB0_379:
	s_or_b64 exec, exec, s[22:23]
	s_movk_i32 s17, 0x4400
	v_mul_lo_u32 v2, v231, s17
	v_lshl_or_b32 v3, v234, 2, v2
	s_movk_i32 s17, 0x440
	v_mad_u32_u24 v3, v230, s17, v3
	v_add_u32_e32 v4, 0x1000, v3
	v_add_u32_e32 v5, 0x1400, v3
	s_waitcnt vmcnt(0) lgkmcnt(0)
	s_barrier
	ds_write2_b32 v3, v198, v194 offset1:16
	ds_write2_b32 v3, v199, v195 offset0:68 offset1:84
	ds_write2_b32 v3, v196, v192 offset0:136 offset1:152
	ds_write2_b32 v3, v197, v193 offset0:204 offset1:220
	ds_write2_b32 v3, v190, v186 offset0:32 offset1:48
	ds_write2_b32 v3, v191, v187 offset0:100 offset1:116
	ds_write2_b32 v3, v188, v184 offset0:168 offset1:184
	ds_write2_b32 v3, v189, v185 offset0:236 offset1:252
	ds_write2_b32 v4, v182, v178 offset0:64 offset1:80
	ds_write2_b32 v4, v183, v179 offset0:132 offset1:148
	ds_write2_b32 v4, v180, v176 offset0:200 offset1:216
	ds_write2_b32 v5, v181, v177 offset0:12 offset1:28
	ds_write2_b32 v4, v174, v170 offset0:96 offset1:112
	ds_write2_b32 v4, v175, v171 offset0:164 offset1:180
	ds_write2_b32 v4, v172, v168 offset0:232 offset1:248
	ds_write2_b32 v5, v173, v169 offset0:44 offset1:60
	v_add_u32_e32 v4, 0x2000, v3
	v_add_u32_e32 v5, 0x2400, v3
	ds_write2_b32 v4, v166, v162 offset0:128 offset1:144
	ds_write2_b32 v4, v167, v163 offset0:196 offset1:212
	ds_write2_b32 v5, v164, v160 offset0:8 offset1:24
	ds_write2_b32 v5, v165, v161 offset0:76 offset1:92
	ds_write2_b32 v4, v158, v154 offset0:160 offset1:176
	ds_write2_b32 v4, v159, v155 offset0:228 offset1:244
	ds_write2_b32 v5, v156, v152 offset0:40 offset1:56
	ds_write2_b32 v5, v157, v153 offset0:108 offset1:124
	v_add_u32_e32 v4, 0x3000, v3
	v_add_u32_e32 v3, 0x3400, v3
	v_lshrrev_b32_e32 v10, 3, v133
	v_and_b32_e32 v0, 56, v0
	ds_write2_b32 v4, v150, v146 offset0:192 offset1:208
	ds_write2_b32 v3, v151, v147 offset0:4 offset1:20
	ds_write2_b32 v3, v148, v144 offset0:72 offset1:88
	ds_write2_b32 v3, v149, v145 offset0:140 offset1:156
	ds_write2_b32 v4, v142, v138 offset0:224 offset1:240
	ds_write2_b32 v3, v143, v139 offset0:36 offset1:52
	ds_write2_b32 v3, v140, v136 offset0:104 offset1:120
	ds_write2_b32 v3, v141, v137 offset0:172 offset1:188
	v_mul_u32_u24_e32 v3, 0x110, v10
	v_lshlrev_b32_e32 v4, 2, v0
	v_add3_u32 v20, v2, v3, v4
	ds_read_b128 v[2:5], v20
	ds_read_b128 v[6:9], v20 offset:16
	v_readlane_b32 s22, v254, 49
	v_or_b32_e32 v16, v233, v10
	v_ashrrev_i32_e32 v133, 31, v132
	v_readlane_b32 s23, v254, 50
	v_ashrrev_i32_e32 v17, 31, v16
	s_waitcnt lgkmcnt(1)
	v_cvt_pk_bf16_f32 v2, v2, v3
	v_lshl_add_u64 v[14:15], v[132:133], 1, s[22:23]
	v_cvt_pk_bf16_f32 v3, v4, v5
	s_waitcnt lgkmcnt(0)
	v_cvt_pk_bf16_f32 v4, v6, v7
	v_lshlrev_b64 v[6:7], 11, v[16:17]
	v_cvt_pk_bf16_f32 v5, v8, v9
	v_lshl_add_u64 v[18:19], v[14:15], 0, v[6:7]
	ds_read_b128 v[6:9], v20 offset:2176
	ds_read_b128 v[10:13], v20 offset:2192
	v_lshlrev_b32_e32 v0, 1, v0
	v_lshl_add_u64 v[18:19], v[18:19], 0, v[0:1]
	global_store_dwordx4 v[18:19], v[2:5], off sc1
	s_add_i32 s8, s8, s64
	s_cmpk_gt_i32 s8, 0xff
	s_waitcnt lgkmcnt(1)
	v_cvt_pk_bf16_f32 v2, v6, v7
	v_or_b32_e32 v6, 8, v16
	v_ashrrev_i32_e32 v7, 31, v6
	v_cvt_pk_bf16_f32 v3, v8, v9
	s_waitcnt lgkmcnt(0)
	v_cvt_pk_bf16_f32 v4, v10, v11
	v_lshlrev_b64 v[10:11], 11, v[6:7]
	ds_read_b128 v[6:9], v20 offset:4352
	v_cvt_pk_bf16_f32 v5, v12, v13
	v_lshl_add_u64 v[18:19], v[14:15], 0, v[10:11]
	ds_read_b128 v[10:13], v20 offset:4368
	v_lshl_add_u64 v[18:19], v[18:19], 0, v[0:1]
	global_store_dwordx4 v[18:19], v[2:5], off sc1
	s_waitcnt lgkmcnt(1)
	s_nop 0
	v_cvt_pk_bf16_f32 v2, v6, v7
	v_or_b32_e32 v6, 16, v16
	v_ashrrev_i32_e32 v7, 31, v6
	v_cvt_pk_bf16_f32 v3, v8, v9
	s_waitcnt lgkmcnt(0)
	v_cvt_pk_bf16_f32 v4, v10, v11
	v_lshlrev_b64 v[10:11], 11, v[6:7]
	ds_read_b128 v[6:9], v20 offset:6528
	v_cvt_pk_bf16_f32 v5, v12, v13
	v_lshl_add_u64 v[18:19], v[14:15], 0, v[10:11]
	ds_read_b128 v[10:13], v20 offset:6544
	v_lshl_add_u64 v[18:19], v[18:19], 0, v[0:1]
	global_store_dwordx4 v[18:19], v[2:5], off sc1
	s_waitcnt lgkmcnt(1)
	s_nop 0
	v_cvt_pk_bf16_f32 v2, v6, v7
	v_or_b32_e32 v6, 24, v16
	v_ashrrev_i32_e32 v7, 31, v6
	v_cvt_pk_bf16_f32 v3, v8, v9
	s_waitcnt lgkmcnt(0)
	v_cvt_pk_bf16_f32 v4, v10, v11
	v_lshlrev_b64 v[10:11], 11, v[6:7]
	ds_read_b128 v[6:9], v20 offset:8704
	v_cvt_pk_bf16_f32 v5, v12, v13
	v_lshl_add_u64 v[18:19], v[14:15], 0, v[10:11]
	ds_read_b128 v[10:13], v20 offset:8720
	v_lshl_add_u64 v[18:19], v[18:19], 0, v[0:1]
	global_store_dwordx4 v[18:19], v[2:5], off sc1
	s_waitcnt lgkmcnt(1)
	s_nop 0
	v_cvt_pk_bf16_f32 v2, v6, v7
	v_or_b32_e32 v6, 32, v16
	v_ashrrev_i32_e32 v7, 31, v6
	v_cvt_pk_bf16_f32 v3, v8, v9
	s_waitcnt lgkmcnt(0)
	v_cvt_pk_bf16_f32 v4, v10, v11
	v_lshlrev_b64 v[10:11], 11, v[6:7]
	ds_read_b128 v[6:9], v20 offset:10880
	v_cvt_pk_bf16_f32 v5, v12, v13
	v_lshl_add_u64 v[18:19], v[14:15], 0, v[10:11]
	ds_read_b128 v[10:13], v20 offset:10896
	v_lshl_add_u64 v[18:19], v[18:19], 0, v[0:1]
	global_store_dwordx4 v[18:19], v[2:5], off sc1
	s_waitcnt lgkmcnt(1)
	s_nop 0
	v_cvt_pk_bf16_f32 v2, v6, v7
	v_or_b32_e32 v6, 40, v16
	v_ashrrev_i32_e32 v7, 31, v6
	v_cvt_pk_bf16_f32 v3, v8, v9
	s_waitcnt lgkmcnt(0)
	v_cvt_pk_bf16_f32 v4, v10, v11
	v_lshlrev_b64 v[10:11], 11, v[6:7]
	ds_read_b128 v[6:9], v20 offset:13056
	v_cvt_pk_bf16_f32 v5, v12, v13
	v_lshl_add_u64 v[18:19], v[14:15], 0, v[10:11]
	ds_read_b128 v[10:13], v20 offset:13072
	v_lshl_add_u64 v[18:19], v[18:19], 0, v[0:1]
	global_store_dwordx4 v[18:19], v[2:5], off sc1
	s_waitcnt lgkmcnt(1)
	s_nop 0
	v_cvt_pk_bf16_f32 v2, v6, v7
	v_or_b32_e32 v6, 48, v16
	v_ashrrev_i32_e32 v7, 31, v6
	v_cvt_pk_bf16_f32 v3, v8, v9
	s_waitcnt lgkmcnt(0)
	v_cvt_pk_bf16_f32 v4, v10, v11
	v_lshlrev_b64 v[10:11], 11, v[6:7]
	ds_read_b128 v[6:9], v20 offset:15232
	v_lshl_add_u64 v[18:19], v[14:15], 0, v[10:11]
	v_cvt_pk_bf16_f32 v5, v12, v13
	ds_read_b128 v[10:13], v20 offset:15248
	v_lshl_add_u64 v[18:19], v[18:19], 0, v[0:1]
	global_store_dwordx4 v[18:19], v[2:5], off sc1
	s_waitcnt lgkmcnt(1)
	s_nop 0
	v_cvt_pk_bf16_f32 v2, v6, v7
	v_or_b32_e32 v6, 56, v16
	v_ashrrev_i32_e32 v7, 31, v6
	v_lshlrev_b64 v[6:7], 11, v[6:7]
	v_lshl_add_u64 v[6:7], v[14:15], 0, v[6:7]
	v_cvt_pk_bf16_f32 v3, v8, v9
	s_waitcnt lgkmcnt(0)
	v_cvt_pk_bf16_f32 v4, v10, v11
	v_cvt_pk_bf16_f32 v5, v12, v13
	v_lshl_add_u64 v[6:7], v[6:7], 0, v[0:1]
	global_store_dwordx4 v[6:7], v[2:5], off sc1
	s_cbranch_scc1 .LBB0_402

.LBB0_427:
	s_or_b64 exec, exec, s[20:21]
	s_movk_i32 s8, 0x4400
	v_mul_lo_u32 v2, v230, s8
	v_lshl_or_b32 v3, v234, 2, v2
	s_movk_i32 s8, 0x440
	v_mad_u32_u24 v3, v201, s8, v3
	v_add_u32_e32 v4, 0x1000, v3
	v_add_u32_e32 v5, 0x1400, v3
	s_waitcnt vmcnt(0) lgkmcnt(0)
	s_barrier
	ds_write2_b32 v3, v196, v192 offset1:16
	ds_write2_b32 v3, v197, v193 offset0:68 offset1:84
	ds_write2_b32 v3, v194, v190 offset0:136 offset1:152
	ds_write2_b32 v3, v195, v191 offset0:204 offset1:220
	ds_write2_b32 v3, v188, v184 offset0:32 offset1:48
	ds_write2_b32 v3, v189, v185 offset0:100 offset1:116
	ds_write2_b32 v3, v186, v182 offset0:168 offset1:184
	ds_write2_b32 v3, v187, v183 offset0:236 offset1:252
	ds_write2_b32 v4, v180, v176 offset0:64 offset1:80
	ds_write2_b32 v4, v181, v177 offset0:132 offset1:148
	ds_write2_b32 v4, v178, v174 offset0:200 offset1:216
	ds_write2_b32 v5, v179, v175 offset0:12 offset1:28
	ds_write2_b32 v4, v172, v168 offset0:96 offset1:112
	ds_write2_b32 v4, v173, v169 offset0:164 offset1:180
	ds_write2_b32 v4, v170, v166 offset0:232 offset1:248
	ds_write2_b32 v5, v171, v167 offset0:44 offset1:60
	v_add_u32_e32 v4, 0x2000, v3
	v_add_u32_e32 v5, 0x2400, v3
	ds_write2_b32 v4, v164, v160 offset0:128 offset1:144
	ds_write2_b32 v4, v165, v161 offset0:196 offset1:212
	ds_write2_b32 v5, v162, v158 offset0:8 offset1:24
	ds_write2_b32 v5, v163, v159 offset0:76 offset1:92
	ds_write2_b32 v4, v156, v152 offset0:160 offset1:176
	ds_write2_b32 v4, v157, v153 offset0:228 offset1:244
	ds_write2_b32 v5, v154, v150 offset0:40 offset1:56
	ds_write2_b32 v5, v155, v151 offset0:108 offset1:124
	v_add_u32_e32 v4, 0x3000, v3
	v_add_u32_e32 v3, 0x3400, v3
	v_lshrrev_b32_e32 v12, 3, v200
	v_and_b32_e32 v0, 56, v0
	ds_write2_b32 v4, v148, v144 offset0:192 offset1:208
	ds_write2_b32 v3, v149, v145 offset0:4 offset1:20
	ds_write2_b32 v3, v146, v142 offset0:72 offset1:88
	ds_write2_b32 v3, v147, v143 offset0:140 offset1:156
	ds_write2_b32 v4, v140, v136 offset0:224 offset1:240
	ds_write2_b32 v3, v141, v137 offset0:36 offset1:52
	ds_write2_b32 v3, v138, v134 offset0:104 offset1:120
	ds_write2_b32 v3, v139, v135 offset0:172 offset1:188
	v_mul_u32_u24_e32 v3, 0x110, v12
	v_lshlrev_b32_e32 v4, 2, v0
	v_add3_u32 v20, v2, v3, v4
	ds_read_b128 v[2:5], v20
	ds_read_b128 v[6:9], v20 offset:16
	v_readlane_b32 s8, v254, 47
	s_lshl_b32 s8, s8, 1
	v_readlane_b32 s20, v254, 49
	v_or_b32_e32 v16, v233, v12
	v_lshl_or_b32 v10, v231, 7, s8
	v_mov_b32_e32 v11, v1
	v_readlane_b32 s21, v254, 50
	v_ashrrev_i32_e32 v17, 31, v16
	s_waitcnt lgkmcnt(1)
	v_cvt_pk_bf16_f32 v2, v2, v3
	v_lshl_add_u64 v[14:15], s[20:21], 0, v[10:11]
	v_cvt_pk_bf16_f32 v3, v4, v5
	s_waitcnt lgkmcnt(0)
	v_cvt_pk_bf16_f32 v4, v6, v7
	v_lshlrev_b64 v[6:7], 11, v[16:17]
	v_cvt_pk_bf16_f32 v5, v8, v9
	v_lshl_add_u64 v[18:19], v[14:15], 0, v[6:7]
	ds_read_b128 v[6:9], v20 offset:2176
	ds_read_b128 v[10:13], v20 offset:2192
	v_lshlrev_b32_e32 v0, 1, v0
	v_lshl_add_u64 v[18:19], v[18:19], 0, v[0:1]
	global_store_dwordx4 v[18:19], v[2:5], off sc1
	s_waitcnt lgkmcnt(1)
	s_nop 0
	v_cvt_pk_bf16_f32 v2, v6, v7
	v_or_b32_e32 v6, 8, v16
	v_ashrrev_i32_e32 v7, 31, v6
	v_cvt_pk_bf16_f32 v3, v8, v9
	s_waitcnt lgkmcnt(0)
	v_cvt_pk_bf16_f32 v4, v10, v11
	v_lshlrev_b64 v[10:11], 11, v[6:7]
	ds_read_b128 v[6:9], v20 offset:4352
	v_cvt_pk_bf16_f32 v5, v12, v13
	v_lshl_add_u64 v[18:19], v[14:15], 0, v[10:11]
	ds_read_b128 v[10:13], v20 offset:4368
	v_lshl_add_u64 v[18:19], v[18:19], 0, v[0:1]
	global_store_dwordx4 v[18:19], v[2:5], off sc1
	s_waitcnt lgkmcnt(1)
	s_nop 0
	v_cvt_pk_bf16_f32 v2, v6, v7
	v_or_b32_e32 v6, 16, v16
	v_ashrrev_i32_e32 v7, 31, v6
	v_cvt_pk_bf16_f32 v3, v8, v9
	s_waitcnt lgkmcnt(0)
	v_cvt_pk_bf16_f32 v4, v10, v11
	v_lshlrev_b64 v[10:11], 11, v[6:7]
	ds_read_b128 v[6:9], v20 offset:6528
	v_cvt_pk_bf16_f32 v5, v12, v13
	v_lshl_add_u64 v[18:19], v[14:15], 0, v[10:11]
	ds_read_b128 v[10:13], v20 offset:6544
	v_lshl_add_u64 v[18:19], v[18:19], 0, v[0:1]
	global_store_dwordx4 v[18:19], v[2:5], off sc1
	s_waitcnt lgkmcnt(1)
	s_nop 0
	v_cvt_pk_bf16_f32 v2, v6, v7
	v_or_b32_e32 v6, 24, v16
	v_ashrrev_i32_e32 v7, 31, v6
	v_cvt_pk_bf16_f32 v3, v8, v9
	s_waitcnt lgkmcnt(0)
	v_cvt_pk_bf16_f32 v4, v10, v11
	v_lshlrev_b64 v[10:11], 11, v[6:7]
	ds_read_b128 v[6:9], v20 offset:8704
	v_cvt_pk_bf16_f32 v5, v12, v13
	v_lshl_add_u64 v[18:19], v[14:15], 0, v[10:11]
	ds_read_b128 v[10:13], v20 offset:8720
	v_lshl_add_u64 v[18:19], v[18:19], 0, v[0:1]
	global_store_dwordx4 v[18:19], v[2:5], off sc1
	s_waitcnt lgkmcnt(1)
	s_nop 0
	v_cvt_pk_bf16_f32 v2, v6, v7
	v_or_b32_e32 v6, 32, v16
	v_ashrrev_i32_e32 v7, 31, v6
	v_cvt_pk_bf16_f32 v3, v8, v9
	s_waitcnt lgkmcnt(0)
	v_cvt_pk_bf16_f32 v4, v10, v11
	v_lshlrev_b64 v[10:11], 11, v[6:7]
	ds_read_b128 v[6:9], v20 offset:10880
	v_cvt_pk_bf16_f32 v5, v12, v13
	v_lshl_add_u64 v[18:19], v[14:15], 0, v[10:11]
	ds_read_b128 v[10:13], v20 offset:10896
	v_lshl_add_u64 v[18:19], v[18:19], 0, v[0:1]
	global_store_dwordx4 v[18:19], v[2:5], off sc1
	s_waitcnt lgkmcnt(1)
	s_nop 0
	v_cvt_pk_bf16_f32 v2, v6, v7
	v_or_b32_e32 v6, 40, v16
	v_ashrrev_i32_e32 v7, 31, v6
	v_cvt_pk_bf16_f32 v3, v8, v9
	s_waitcnt lgkmcnt(0)
	v_cvt_pk_bf16_f32 v4, v10, v11
	v_lshlrev_b64 v[10:11], 11, v[6:7]
	ds_read_b128 v[6:9], v20 offset:13056
	v_cvt_pk_bf16_f32 v5, v12, v13
	v_lshl_add_u64 v[18:19], v[14:15], 0, v[10:11]
	ds_read_b128 v[10:13], v20 offset:13072
	v_lshl_add_u64 v[18:19], v[18:19], 0, v[0:1]
	global_store_dwordx4 v[18:19], v[2:5], off sc1
	s_waitcnt lgkmcnt(1)
	s_nop 0
	v_cvt_pk_bf16_f32 v2, v6, v7
	v_or_b32_e32 v6, 48, v16
	v_ashrrev_i32_e32 v7, 31, v6
	v_cvt_pk_bf16_f32 v3, v8, v9
	s_waitcnt lgkmcnt(0)
	v_cvt_pk_bf16_f32 v4, v10, v11
	v_lshlrev_b64 v[10:11], 11, v[6:7]
	ds_read_b128 v[6:9], v20 offset:15232
	v_lshl_add_u64 v[18:19], v[14:15], 0, v[10:11]
	v_cvt_pk_bf16_f32 v5, v12, v13
	ds_read_b128 v[10:13], v20 offset:15248
	v_lshl_add_u64 v[18:19], v[18:19], 0, v[0:1]
	global_store_dwordx4 v[18:19], v[2:5], off sc1
	s_waitcnt lgkmcnt(1)
	s_nop 0
	v_cvt_pk_bf16_f32 v2, v6, v7
	v_or_b32_e32 v6, 56, v16
	v_ashrrev_i32_e32 v7, 31, v6
	v_lshlrev_b64 v[6:7], 11, v[6:7]
	v_lshl_add_u64 v[6:7], v[14:15], 0, v[6:7]
	v_cvt_pk_bf16_f32 v3, v8, v9
	s_waitcnt lgkmcnt(0)
	v_cvt_pk_bf16_f32 v4, v10, v11
	v_cvt_pk_bf16_f32 v5, v12, v13
	v_lshl_add_u64 v[6:7], v[6:7], 0, v[0:1]
	global_store_dwordx4 v[6:7], v[2:5], off sc1

.Lat_pfb_skip:
	ds_bpermute_b32 v0, v166, v114
	s_ashr_i32 s23, s22, 31
	v_mov_b32_e32 v147, v1
	v_mov_b32_e32 v149, v1
	v_readlane_b32 s80, v255, 34
	s_waitcnt lgkmcnt(0)
	v_add_f32_e32 v0, v114, v0
	v_div_scale_f32 v34, s[24:25], v0, v0, 1.0
	v_rcp_f32_e32 v35, v34
	v_div_scale_f32 v36, vcc, 1.0, v0, 1.0
	v_readlane_b32 s24, v254, 55
	v_fma_f32 v37, -v34, v35, 1.0
	v_fmac_f32_e32 v35, v37, v35
	v_mul_f32_e32 v37, v36, v35
	v_fma_f32 v38, -v34, v37, v36
	v_fmac_f32_e32 v37, v38, v35
	v_fma_f32 v34, -v34, v37, v36
	v_div_fmas_f32 v34, v34, v35, v37
	v_div_fixup_f32 v0, v34, v0, 1.0
	v_pk_mul_f32 v[2:3], v[2:3], v[0:1] op_sel_hi:[1,0]
	v_pk_mul_f32 v[4:5], v[4:5], v[0:1] op_sel_hi:[1,0]
	v_pk_mul_f32 v[6:7], v[6:7], v[0:1] op_sel_hi:[1,0]
	v_pk_mul_f32 v[8:9], v[8:9], v[0:1] op_sel_hi:[1,0]
	v_pk_mul_f32 v[10:11], v[10:11], v[0:1] op_sel_hi:[1,0]
	v_pk_mul_f32 v[12:13], v[12:13], v[0:1] op_sel_hi:[1,0]
	v_pk_mul_f32 v[14:15], v[14:15], v[0:1] op_sel_hi:[1,0]
	v_pk_mul_f32 v[16:17], v[16:17], v[0:1] op_sel_hi:[1,0]
	v_cvt_pk_bf16_f32 v2, v2, v3
	v_cvt_pk_bf16_f32 v3, v4, v5
	v_cvt_pk_bf16_f32 v4, v6, v7
	v_cvt_pk_bf16_f32 v5, v8, v9
	v_pk_mul_f32 v[18:19], v[18:19], v[0:1] op_sel_hi:[1,0]
	v_pk_mul_f32 v[20:21], v[20:21], v[0:1] op_sel_hi:[1,0]
	v_pk_mul_f32 v[22:23], v[22:23], v[0:1] op_sel_hi:[1,0]
	v_pk_mul_f32 v[24:25], v[24:25], v[0:1] op_sel_hi:[1,0]
	ds_write2_b64 v185, v[2:3], v[4:5] offset1:2
	v_cvt_pk_bf16_f32 v2, v10, v11
	v_cvt_pk_bf16_f32 v3, v12, v13
	v_cvt_pk_bf16_f32 v4, v14, v15
	v_cvt_pk_bf16_f32 v5, v16, v17
	v_pk_mul_f32 v[26:27], v[26:27], v[0:1] op_sel_hi:[1,0]
	v_pk_mul_f32 v[28:29], v[28:29], v[0:1] op_sel_hi:[1,0]
	v_pk_mul_f32 v[30:31], v[30:31], v[0:1] op_sel_hi:[1,0]
	v_pk_mul_f32 v[32:33], v[32:33], v[0:1] op_sel_hi:[1,0]
	ds_write2_b64 v185, v[2:3], v[4:5] offset0:4 offset1:6
	v_cvt_pk_bf16_f32 v2, v18, v19
	v_cvt_pk_bf16_f32 v3, v20, v21
	v_cvt_pk_bf16_f32 v4, v22, v23
	v_cvt_pk_bf16_f32 v5, v24, v25
	ds_write2_b64 v185, v[2:3], v[4:5] offset0:8 offset1:10
	v_cvt_pk_bf16_f32 v2, v26, v27
	v_cvt_pk_bf16_f32 v3, v28, v29
	v_cvt_pk_bf16_f32 v4, v30, v31
	v_cvt_pk_bf16_f32 v5, v32, v33
	v_readlane_b32 s25, v254, 56
	ds_write2_b64 v185, v[2:3], v[4:5] offset0:12 offset1:14
	v_lshlrev_b32_e32 v0, 1, v112
	v_mov_b64_e32 v[2:3], s[24:25]
	v_mad_i64_i32 v[2:3], s[24:25], v113, s84, v[2:3]
	v_lshl_add_u64 v[2:3], s[22:23], 1, v[2:3]
	v_lshl_add_u64 v[6:7], v[2:3], 0, v[0:1]
	ds_read_b128 v[2:5], v175
	v_lshl_add_u64 v[6:7], v[6:7], 0, v[146:147]
	v_lshl_add_u64 v[10:11], v[6:7], 0, v[148:149]
	ds_read_b128 v[6:9], v176
	v_readlane_b32 s68, v255, 33
	s_waitcnt lgkmcnt(1)
	global_store_dwordx4 v[10:11], v[2:5], off sc1
	v_readlane_b32 s81, v255, 35
	s_nop 0
	v_add_co_u32_e32 v2, vcc, s82, v10
	s_nop 1
	v_addc_co_u32_e32 v3, vcc, 0, v11, vcc
	s_waitcnt lgkmcnt(0)
	global_store_dwordx4 v[2:3], v[6:9], off sc1
	ds_read_b128 v[2:5], v177
	ds_read_b128 v[6:9], v178
	v_add_co_u32_e32 v12, vcc, 0xc000, v10
	s_nop 1
	v_addc_co_u32_e32 v13, vcc, 0, v11, vcc
	s_waitcnt lgkmcnt(1)
	global_store_dwordx4 v[12:13], v[2:5], off sc1
	s_nop 1
	v_add_co_u32_e32 v2, vcc, 0x12000, v10
	s_nop 1
	v_addc_co_u32_e32 v3, vcc, 0, v11, vcc
	s_waitcnt lgkmcnt(0)
	global_store_dwordx4 v[2:3], v[6:9], off sc1
	s_branch .LBB0_432

.LBB0_476:
	s_or_b64 exec, exec, s[20:21]
	s_waitcnt lgkmcnt(0)
	s_barrier
	s_and_saveexec_b64 s[20:21], s[44:45]
	s_xor_b64 s[20:21], exec, s[20:21]
	s_cbranch_execz .LBB0_431
	ds_read2st64_b32 v[20:21], v173 offset1:1
	ds_read2st64_b32 v[22:23], v173 offset0:2 offset1:3
	ds_read2st64_b32 v[24:25], v173 offset0:4 offset1:5
	ds_read2st64_b32 v[26:27], v173 offset0:6 offset1:7
	ds_read2st64_b32 v[28:29], v173 offset0:8 offset1:9
	ds_read2st64_b32 v[34:35], v173 offset0:10 offset1:11
	ds_read2st64_b32 v[36:37], v173 offset0:12 offset1:13
	ds_read2st64_b32 v[40:41], v173 offset0:14 offset1:15
	ds_read2st64_b32 v[46:47], v173 offset0:16 offset1:17
	ds_read2st64_b32 v[58:59], v173 offset0:18 offset1:19
	ds_read2st64_b32 v[62:63], v173 offset0:20 offset1:21
	ds_read2st64_b32 v[96:97], v173 offset0:22 offset1:23
	ds_read2st64_b32 v[98:99], v173 offset0:24 offset1:25
	ds_read2st64_b32 v[100:101], v173 offset0:26 offset1:27
	ds_read2st64_b32 v[102:103], v173 offset0:28 offset1:29
	ds_read2st64_b32 v[104:105], v173 offset0:30 offset1:31
	ds_read2st64_b32 v[106:107], v173 offset0:32 offset1:33
	ds_read2st64_b32 v[108:109], v173 offset0:34 offset1:35
	ds_read2st64_b32 v[110:111], v173 offset0:36 offset1:37
	ds_read2st64_b32 v[112:113], v173 offset0:38 offset1:39
	ds_read2st64_b32 v[114:115], v173 offset0:40 offset1:41
	ds_read2st64_b32 v[116:117], v173 offset0:42 offset1:43
	ds_read2st64_b32 v[118:119], v173 offset0:44 offset1:45
	ds_read2st64_b32 v[120:121], v173 offset0:46 offset1:47
	ds_read2st64_b32 v[122:123], v173 offset0:56 offset1:57
	ds_read2st64_b32 v[124:125], v173 offset0:58 offset1:59
	ds_read2st64_b32 v[30:31], v173 offset0:60 offset1:61
	ds_read2st64_b32 v[32:33], v173 offset0:62 offset1:63
	ds_read2st64_b32 v[126:127], v173 offset0:48 offset1:49
	ds_read2st64_b32 v[128:129], v173 offset0:50 offset1:51
	ds_read2st64_b32 v[130:131], v173 offset0:52 offset1:53
	ds_read2st64_b32 v[158:159], v173 offset0:54 offset1:55
	s_waitcnt lgkmcnt(14)
	v_pk_fma_f32 v[188:189], v[132:133], v[20:21], v[88:89] neg_lo:[1,0,0] neg_hi:[1,0,0]
	v_pk_fma_f32 v[164:165], v[132:133], v[22:23], v[92:93] neg_lo:[1,0,0] neg_hi:[1,0,0]
	v_pk_mul_f32 v[190:191], v[188:189], v[188:189]
	v_pk_mul_f32 v[186:187], v[164:165], v[164:165]
	v_add_f32_e32 v0, v190, v191
	v_pk_fma_f32 v[192:193], v[132:133], v[26:27], v[90:91] neg_lo:[1,0,0] neg_hi:[1,0,0]
	global_load_dwordx4 v[88:91], v[144:145], off
	global_load_dwordx4 v[92:95], v[144:145], off offset:32
	v_pk_fma_f32 v[196:197], v[132:133], v[24:25], v[4:5] neg_lo:[1,0,0] neg_hi:[1,0,0]
	v_add_f32_e32 v0, v0, v186
	v_pk_mul_f32 v[198:199], v[196:197], v[196:197]
	v_add_f32_e32 v0, v0, v187
	v_add_f32_e32 v0, v0, v198
	v_pk_mul_f32 v[194:195], v[192:193], v[192:193]
	v_add_f32_e32 v0, v0, v199
	v_pk_fma_f32 v[232:233], v[132:133], v[28:29], v[2:3] neg_lo:[1,0,0] neg_hi:[1,0,0]
	v_add_f32_e32 v0, v0, v194
	v_pk_mul_f32 v[234:235], v[232:233], v[232:233]
	v_add_f32_e32 v0, v0, v195
	v_pk_fma_f32 v[200:201], v[132:133], v[34:35], v[86:87] neg_lo:[1,0,0] neg_hi:[1,0,0]
	v_pk_fma_f32 v[34:35], v[132:133], v[40:41], v[84:85] neg_lo:[1,0,0] neg_hi:[1,0,0]
	global_load_dwordx4 v[84:87], v[144:145], off offset:64
	global_load_dwordx4 v[2:5], v[144:145], off offset:96
	v_add_f32_e32 v0, v0, v234
	v_pk_mul_f32 v[230:231], v[200:201], v[200:201]
	v_add_f32_e32 v0, v0, v235
	v_pk_fma_f32 v[44:45], v[132:133], v[36:37], v[10:11] neg_lo:[1,0,0] neg_hi:[1,0,0]
	v_add_f32_e32 v0, v0, v230
	v_pk_mul_f32 v[238:239], v[44:45], v[44:45]
	v_add_f32_e32 v0, v0, v231
	v_add_f32_e32 v0, v0, v238
	v_pk_mul_f32 v[236:237], v[34:35], v[34:35]
	v_add_f32_e32 v0, v0, v239
	v_pk_fma_f32 v[46:47], v[132:133], v[46:47], v[6:7] neg_lo:[1,0,0] neg_hi:[1,0,0]
	v_add_f32_e32 v0, v0, v236
	v_pk_mul_f32 v[242:243], v[46:47], v[46:47]
	v_add_f32_e32 v0, v0, v237
	v_pk_fma_f32 v[36:37], v[132:133], v[58:59], v[12:13] neg_lo:[1,0,0] neg_hi:[1,0,0]
	v_add_f32_e32 v0, v0, v242
	v_pk_mul_f32 v[240:241], v[36:37], v[36:37]
	v_add_f32_e32 v0, v0, v243
	v_pk_fma_f32 v[58:59], v[132:133], v[62:63], v[48:49] neg_lo:[1,0,0] neg_hi:[1,0,0]
	v_add_f32_e32 v0, v0, v240
	v_pk_mul_f32 v[244:245], v[58:59], v[58:59]
	v_add_f32_e32 v0, v0, v241
	v_pk_fma_f32 v[40:41], v[132:133], v[96:97], v[8:9] neg_lo:[1,0,0] neg_hi:[1,0,0]
	v_add_f32_e32 v0, v0, v244
	v_pk_mul_f32 v[96:97], v[40:41], v[40:41]
	v_add_f32_e32 v0, v0, v245
	v_pk_fma_f32 v[62:63], v[132:133], v[98:99], v[14:15] neg_lo:[1,0,0] neg_hi:[1,0,0]
	v_add_f32_e32 v0, v0, v96
	v_pk_mul_f32 v[98:99], v[62:63], v[62:63]
	v_add_f32_e32 v0, v0, v97
	v_pk_fma_f32 v[48:49], v[132:133], v[100:101], v[72:73] neg_lo:[1,0,0] neg_hi:[1,0,0]
	v_add_f32_e32 v0, v0, v98
	v_pk_mul_f32 v[100:101], v[48:49], v[48:49]
	v_add_f32_e32 v0, v0, v99
	v_pk_fma_f32 v[72:73], v[132:133], v[102:103], v[64:65] neg_lo:[1,0,0] neg_hi:[1,0,0]
	v_add_f32_e32 v0, v0, v100
	v_pk_mul_f32 v[102:103], v[72:73], v[72:73]
	v_add_f32_e32 v0, v0, v101
	v_pk_fma_f32 v[54:55], v[132:133], v[104:105], v[54:55] neg_lo:[1,0,0] neg_hi:[1,0,0]
	v_add_f32_e32 v0, v0, v102
	v_pk_mul_f32 v[104:105], v[54:55], v[54:55]
	v_add_f32_e32 v0, v0, v103
	v_pk_fma_f32 v[64:65], v[132:133], v[108:109], v[78:79] neg_lo:[1,0,0] neg_hi:[1,0,0]
	v_pk_fma_f32 v[78:79], v[132:133], v[106:107], v[70:71] neg_lo:[1,0,0] neg_hi:[1,0,0]
	v_add_f32_e32 v0, v0, v104
	v_pk_mul_f32 v[106:107], v[78:79], v[78:79]
	v_add_f32_e32 v0, v0, v105
	v_add_f32_e32 v0, v0, v106
	v_pk_mul_f32 v[108:109], v[64:65], v[64:65]
	v_add_f32_e32 v0, v0, v107
	s_waitcnt lgkmcnt(12)
	v_pk_fma_f32 v[70:71], v[132:133], v[112:113], v[82:83] neg_lo:[1,0,0] neg_hi:[1,0,0]
	v_pk_fma_f32 v[82:83], v[132:133], v[110:111], v[74:75] neg_lo:[1,0,0] neg_hi:[1,0,0]
	v_add_f32_e32 v0, v0, v108
	v_pk_mul_f32 v[110:111], v[82:83], v[82:83]
	v_add_f32_e32 v0, v0, v109
	v_add_f32_e32 v0, v0, v110
	v_pk_mul_f32 v[112:113], v[70:71], v[70:71]
	v_add_f32_e32 v0, v0, v111
	s_waitcnt lgkmcnt(10)
	v_pk_fma_f32 v[74:75], v[132:133], v[116:117], v[80:81] neg_lo:[1,0,0] neg_hi:[1,0,0]
	v_pk_fma_f32 v[80:81], v[132:133], v[114:115], v[68:69] neg_lo:[1,0,0] neg_hi:[1,0,0]
	v_add_f32_e32 v0, v0, v112
	v_pk_mul_f32 v[114:115], v[80:81], v[80:81]
	v_add_f32_e32 v0, v0, v113
	v_add_f32_e32 v0, v0, v114
	v_pk_mul_f32 v[116:117], v[74:75], v[74:75]
	v_add_f32_e32 v0, v0, v115
	s_waitcnt lgkmcnt(8)
	v_pk_fma_f32 v[68:69], v[132:133], v[120:121], v[76:77] neg_lo:[1,0,0] neg_hi:[1,0,0]
	v_pk_fma_f32 v[76:77], v[132:133], v[118:119], v[60:61] neg_lo:[1,0,0] neg_hi:[1,0,0]
	v_add_f32_e32 v0, v0, v116
	v_pk_mul_f32 v[118:119], v[76:77], v[76:77]
	v_add_f32_e32 v0, v0, v117
	v_add_f32_e32 v0, v0, v118
	v_pk_mul_f32 v[120:121], v[68:69], v[68:69]
	v_add_f32_e32 v0, v0, v119
	s_waitcnt lgkmcnt(2)
	v_pk_fma_f32 v[60:61], v[132:133], v[128:129], v[66:67] neg_lo:[1,0,0] neg_hi:[1,0,0]
	v_pk_fma_f32 v[66:67], v[132:133], v[126:127], v[50:51] neg_lo:[1,0,0] neg_hi:[1,0,0]
	v_add_f32_e32 v0, v0, v120
	v_pk_mul_f32 v[126:127], v[66:67], v[66:67]
	v_add_f32_e32 v0, v0, v121
	v_add_f32_e32 v0, v0, v126
	v_pk_mul_f32 v[128:129], v[60:61], v[60:61]
	v_add_f32_e32 v0, v0, v127
	s_waitcnt lgkmcnt(0)
	v_pk_fma_f32 v[50:51], v[132:133], v[158:159], v[56:57] neg_lo:[1,0,0] neg_hi:[1,0,0]
	v_pk_fma_f32 v[56:57], v[132:133], v[130:131], v[42:43] neg_lo:[1,0,0] neg_hi:[1,0,0]
	v_add_f32_e32 v0, v0, v128
	v_pk_mul_f32 v[130:131], v[56:57], v[56:57]
	v_add_f32_e32 v0, v0, v129
	v_add_f32_e32 v0, v0, v130
	v_pk_mul_f32 v[158:159], v[50:51], v[50:51]
	v_add_f32_e32 v0, v0, v131
	v_pk_fma_f32 v[38:39], v[132:133], v[122:123], v[38:39] neg_lo:[1,0,0] neg_hi:[1,0,0]
	v_add_f32_e32 v0, v0, v158
	v_pk_mul_f32 v[122:123], v[38:39], v[38:39]
	v_add_f32_e32 v0, v0, v159
	v_pk_fma_f32 v[42:43], v[132:133], v[124:125], v[52:53] neg_lo:[1,0,0] neg_hi:[1,0,0]
	v_add_f32_e32 v0, v0, v122
	v_pk_mul_f32 v[52:53], v[42:43], v[42:43]
	v_add_f32_e32 v0, v0, v123
	v_pk_fma_f32 v[30:31], v[132:133], v[30:31], v[18:19] neg_lo:[1,0,0] neg_hi:[1,0,0]
	v_add_f32_e32 v0, v0, v52
	v_pk_mul_f32 v[160:161], v[30:31], v[30:31]
	v_add_f32_e32 v0, v0, v53
	v_pk_fma_f32 v[32:33], v[132:133], v[32:33], v[16:17] neg_lo:[1,0,0] neg_hi:[1,0,0]
	v_add_f32_e32 v0, v0, v160
	v_pk_mul_f32 v[162:163], v[32:33], v[32:33]
	v_add_f32_e32 v0, v0, v161
	global_load_dwordx4 v[10:13], v[144:145], off offset:128
	global_load_dwordx4 v[6:9], v[144:145], off offset:160
	v_add_f32_e32 v0, v0, v162
	v_add_f32_e32 v0, v0, v163
	ds_bpermute_b32 v52, v166, v0
	global_load_dwordx4 v[18:21], v[144:145], off offset:192
	global_load_dwordx4 v[14:17], v[144:145], off offset:224
	global_load_dwordx4 v[26:29], v[144:145], off offset:256
	global_load_dwordx4 v[22:25], v[144:145], off offset:288
	global_load_dwordx4 v[96:99], v[144:145], off offset:320
	global_load_dwordx4 v[100:103], v[144:145], off offset:352
	global_load_dwordx4 v[104:107], v[144:145], off offset:384
	global_load_dwordx4 v[108:111], v[144:145], off offset:416
	global_load_dwordx4 v[112:115], v[144:145], off offset:448
	s_waitcnt lgkmcnt(0)
	v_add_f32_e32 v0, v0, v52
	v_fmamk_f32 v0, v0, 0x3c000000, v205
	v_mul_f32_e32 v52, 0x4b800000, v0
	v_cmp_gt_f32_e32 vcc, s33, v0
	v_readlane_b32 s22, v254, 55
	v_readlane_b32 s23, v254, 56
	v_cndmask_b32_e32 v0, v0, v52, vcc
	v_rsq_f32_e32 v0, v0
	s_lshl_b32 s8, s24, 1
	v_mov_b32_e32 v151, v1
	v_mov_b32_e32 v153, v1
	v_mul_f32_e32 v52, 0x45800000, v0
	v_cndmask_b32_e32 v0, v0, v52, vcc
	v_mul_f32_e32 v0, v167, v0
	v_pk_mul_f32 v[52:53], v[188:189], v[0:1] op_sel_hi:[1,0]
	v_pk_mul_f32 v[44:45], v[44:45], v[0:1] op_sel_hi:[1,0]
	s_waitcnt vmcnt(14)
	v_pk_mul_f32 v[52:53], v[88:89], v[52:53]
	v_pk_mul_f32 v[88:89], v[164:165], v[0:1] op_sel_hi:[1,0]
	v_cvt_pk_bf16_f32 v52, v52, v53
	v_pk_mul_f32 v[88:89], v[90:91], v[88:89]
	v_pk_mul_f32 v[90:91], v[192:193], v[0:1] op_sel_hi:[1,0]
	v_cvt_pk_bf16_f32 v53, v88, v89
	v_pk_mul_f32 v[88:89], v[196:197], v[0:1] op_sel_hi:[1,0]
	s_waitcnt vmcnt(13)
	v_pk_mul_f32 v[90:91], v[94:95], v[90:91]
	v_pk_mul_f32 v[88:89], v[92:93], v[88:89]
	v_pk_mul_f32 v[34:35], v[34:35], v[0:1] op_sel_hi:[1,0]
	v_cvt_pk_bf16_f32 v88, v88, v89
	v_cvt_pk_bf16_f32 v89, v90, v91
	ds_write2_b64 v179, v[52:53], v[88:89] offset1:2
	v_pk_mul_f32 v[52:53], v[232:233], v[0:1] op_sel_hi:[1,0]
	s_waitcnt vmcnt(11)
	v_pk_mul_f32 v[2:3], v[44:45], v[2:3]
	v_pk_mul_f32 v[52:53], v[84:85], v[52:53]
	v_pk_mul_f32 v[84:85], v[200:201], v[0:1] op_sel_hi:[1,0]
	v_cvt_pk_bf16_f32 v52, v52, v53
	v_pk_mul_f32 v[84:85], v[84:85], v[86:87]
	v_pk_mul_f32 v[4:5], v[34:35], v[4:5]
	v_cvt_pk_bf16_f32 v53, v84, v85
	global_load_dwordx4 v[84:87], v[144:145], off offset:480
	v_cvt_pk_bf16_f32 v2, v2, v3
	v_cvt_pk_bf16_f32 v3, v4, v5
	ds_write2_b64 v179, v[52:53], v[2:3] offset0:4 offset1:6
	v_pk_mul_f32 v[2:3], v[46:47], v[0:1] op_sel_hi:[1,0]
	v_pk_mul_f32 v[4:5], v[36:37], v[0:1] op_sel_hi:[1,0]
	v_mov_b32_e32 v155, v1
	v_mov_b32_e32 v157, v1
	s_waitcnt vmcnt(11)
	v_pk_mul_f32 v[2:3], v[2:3], v[10:11]
	v_pk_mul_f32 v[4:5], v[4:5], v[12:13]
	v_cvt_pk_bf16_f32 v2, v2, v3
	v_cvt_pk_bf16_f32 v3, v4, v5
	v_pk_mul_f32 v[4:5], v[58:59], v[0:1] op_sel_hi:[1,0]
	s_waitcnt vmcnt(10)
	v_pk_mul_f32 v[4:5], v[4:5], v[6:7]
	v_pk_mul_f32 v[6:7], v[40:41], v[0:1] op_sel_hi:[1,0]
	v_cvt_pk_bf16_f32 v4, v4, v5
	v_pk_mul_f32 v[6:7], v[6:7], v[8:9]
	s_nop 0
	v_cvt_pk_bf16_f32 v5, v6, v7
	ds_write2_b64 v179, v[2:3], v[4:5] offset0:8 offset1:10
	v_pk_mul_f32 v[2:3], v[62:63], v[0:1] op_sel_hi:[1,0]
	v_pk_mul_f32 v[4:5], v[48:49], v[0:1] op_sel_hi:[1,0]
	s_waitcnt vmcnt(9)
	v_pk_mul_f32 v[2:3], v[2:3], v[18:19]
	v_pk_mul_f32 v[4:5], v[4:5], v[20:21]
	v_cvt_pk_bf16_f32 v2, v2, v3
	v_cvt_pk_bf16_f32 v3, v4, v5
	v_pk_mul_f32 v[4:5], v[72:73], v[0:1] op_sel_hi:[1,0]
	v_pk_mul_f32 v[6:7], v[54:55], v[0:1] op_sel_hi:[1,0]
	s_waitcnt vmcnt(8)
	v_pk_mul_f32 v[4:5], v[4:5], v[14:15]
	v_pk_mul_f32 v[6:7], v[6:7], v[16:17]
	v_cvt_pk_bf16_f32 v4, v4, v5
	v_cvt_pk_bf16_f32 v5, v6, v7
	ds_write2_b64 v179, v[2:3], v[4:5] offset0:12 offset1:14
	v_pk_mul_f32 v[2:3], v[78:79], v[0:1] op_sel_hi:[1,0]
	v_pk_mul_f32 v[4:5], v[64:65], v[0:1] op_sel_hi:[1,0]
	s_waitcnt vmcnt(7)
	v_pk_mul_f32 v[2:3], v[2:3], v[26:27]
	v_pk_mul_f32 v[4:5], v[4:5], v[28:29]
	v_cvt_pk_bf16_f32 v2, v2, v3
	v_cvt_pk_bf16_f32 v3, v4, v5
	v_pk_mul_f32 v[4:5], v[82:83], v[0:1] op_sel_hi:[1,0]
	v_pk_mul_f32 v[6:7], v[70:71], v[0:1] op_sel_hi:[1,0]
	s_waitcnt vmcnt(6)
	v_pk_mul_f32 v[4:5], v[4:5], v[22:23]
	v_pk_mul_f32 v[6:7], v[6:7], v[24:25]
	v_cvt_pk_bf16_f32 v4, v4, v5
	v_cvt_pk_bf16_f32 v5, v6, v7
	ds_write2_b64 v179, v[2:3], v[4:5] offset0:16 offset1:18
	v_pk_mul_f32 v[2:3], v[80:81], v[0:1] op_sel_hi:[1,0]
	v_pk_mul_f32 v[4:5], v[74:75], v[0:1] op_sel_hi:[1,0]
	s_waitcnt vmcnt(5)
	v_pk_mul_f32 v[2:3], v[2:3], v[96:97]
	v_pk_mul_f32 v[4:5], v[4:5], v[98:99]
	v_cvt_pk_bf16_f32 v2, v2, v3
	v_cvt_pk_bf16_f32 v3, v4, v5
	v_pk_mul_f32 v[4:5], v[76:77], v[0:1] op_sel_hi:[1,0]
	v_pk_mul_f32 v[6:7], v[68:69], v[0:1] op_sel_hi:[1,0]
	s_waitcnt vmcnt(4)
	v_pk_mul_f32 v[4:5], v[4:5], v[100:101]
	v_pk_mul_f32 v[6:7], v[6:7], v[102:103]
	v_cvt_pk_bf16_f32 v4, v4, v5
	v_cvt_pk_bf16_f32 v5, v6, v7
	ds_write2_b64 v179, v[2:3], v[4:5] offset0:20 offset1:22
	v_pk_mul_f32 v[2:3], v[66:67], v[0:1] op_sel_hi:[1,0]
	v_pk_mul_f32 v[4:5], v[60:61], v[0:1] op_sel_hi:[1,0]
	s_waitcnt vmcnt(3)
	v_pk_mul_f32 v[2:3], v[2:3], v[104:105]
	v_pk_mul_f32 v[4:5], v[4:5], v[106:107]
	v_cvt_pk_bf16_f32 v2, v2, v3
	v_cvt_pk_bf16_f32 v3, v4, v5
	v_pk_mul_f32 v[4:5], v[56:57], v[0:1] op_sel_hi:[1,0]
	v_pk_mul_f32 v[6:7], v[50:51], v[0:1] op_sel_hi:[1,0]
	s_waitcnt vmcnt(2)
	v_pk_mul_f32 v[4:5], v[4:5], v[108:109]
	v_pk_mul_f32 v[6:7], v[6:7], v[110:111]
	v_cvt_pk_bf16_f32 v4, v4, v5
	v_cvt_pk_bf16_f32 v5, v6, v7
	ds_write2_b64 v179, v[2:3], v[4:5] offset0:24 offset1:26
	v_pk_mul_f32 v[2:3], v[38:39], v[0:1] op_sel_hi:[1,0]
	v_pk_mul_f32 v[4:5], v[42:43], v[0:1] op_sel_hi:[1,0]
	s_waitcnt vmcnt(1)
	v_pk_mul_f32 v[2:3], v[2:3], v[112:113]
	v_pk_mul_f32 v[4:5], v[4:5], v[114:115]
	v_cvt_pk_bf16_f32 v2, v2, v3
	v_cvt_pk_bf16_f32 v3, v4, v5
	v_pk_mul_f32 v[4:5], v[30:31], v[0:1] op_sel_hi:[1,0]
	v_pk_mul_f32 v[6:7], v[32:33], v[0:1] op_sel_hi:[1,0]
	s_waitcnt vmcnt(0)
	v_pk_mul_f32 v[4:5], v[4:5], v[84:85]
	v_pk_mul_f32 v[6:7], v[6:7], v[86:87]
	v_cvt_pk_bf16_f32 v4, v4, v5
	v_cvt_pk_bf16_f32 v5, v6, v7
	ds_write2_b64 v179, v[2:3], v[4:5] offset0:28 offset1:30
	v_mov_b64_e32 v[2:3], s[22:23]
	v_mad_u64_u32 v[2:3], s[22:23], v147, s84, v[2:3]
	v_lshl_add_u64 v[6:7], v[2:3], 0, s[8:9]
	ds_read_b128 v[2:5], v180
	v_lshl_add_u64 v[14:15], v[6:7], 0, v[150:151]
	ds_read_b128 v[6:9], v181
	v_lshl_add_u64 v[16:17], v[14:15], 0, v[152:153]
	s_movk_i32 s8, 0x3000
	s_waitcnt lgkmcnt(1)
	global_store_dwordx4 v[16:17], v[2:5], off sc1
	s_nop 1
	v_add_co_u32_e32 v2, vcc, s8, v16
	s_mov_b32 s8, 0xc000
	s_nop 0
	v_addc_co_u32_e32 v3, vcc, 0, v17, vcc
	s_waitcnt lgkmcnt(0)
	global_store_dwordx4 v[2:3], v[6:9], off sc1
	ds_read_b128 v[2:5], v182
	ds_read_b128 v[6:9], v136
	ds_read_b128 v[10:13], v137
	v_add_co_u32_e32 v18, vcc, s82, v16
	s_nop 1
	v_addc_co_u32_e32 v19, vcc, 0, v17, vcc
	s_waitcnt lgkmcnt(2)
	global_store_dwordx4 v[18:19], v[2:5], off sc1
	v_lshl_add_u64 v[18:19], v[138:139], 1, v[14:15]
	v_add_co_u32_e32 v16, vcc, s8, v16
	ds_read_b128 v[2:5], v140
	s_waitcnt lgkmcnt(2)
	global_store_dwordx4 v[18:19], v[6:9], off sc1
	v_addc_co_u32_e32 v17, vcc, 0, v17, vcc
	ds_read_b128 v[6:9], v183
	s_waitcnt lgkmcnt(2)
	global_store_dwordx4 v[16:17], v[10:13], off sc1
	ds_read_b128 v[10:13], v184
	v_lshl_add_u64 v[16:17], v[14:15], 0, v[154:155]
	s_waitcnt lgkmcnt(1)
	global_store_dwordx4 v[16:17], v[6:9], off sc1
	s_nop 1
	v_lshl_add_u64 v[6:7], v[14:15], 0, v[156:157]
	s_waitcnt lgkmcnt(0)
	global_store_dwordx4 v[6:7], v[10:13], off sc1
	v_lshl_add_u64 v[6:7], v[142:143], 1, v[14:15]
	global_store_dwordx4 v[6:7], v[2:5], off sc1
	s_branch .LBB0_431

.LBB0_483:
	s_waitcnt vmcnt(3)
	v_pk_mul_f32 v[36:37], v[14:15], v[14:15]
	v_pk_mul_f32 v[38:39], v[16:17], v[16:17]
	v_add_f32_e32 v34, v37, v36
	v_add_f32_e32 v34, v38, v34
	s_waitcnt vmcnt(2)
	v_pk_mul_f32 v[44:45], v[10:11], v[10:11]
	v_add_f32_e32 v34, v39, v34
	v_add_f32_e32 v34, v44, v34
	v_pk_mul_f32 v[46:47], v[12:13], v[12:13]
	v_add_f32_e32 v34, v45, v34
	v_add_f32_e32 v34, v46, v34
	s_waitcnt vmcnt(1)
	v_pk_mul_f32 v[48:49], v[6:7], v[6:7]
	v_add_f32_e32 v34, v47, v34
	v_add_f32_e32 v34, v48, v34
	v_pk_mul_f32 v[50:51], v[8:9], v[8:9]
	v_add_f32_e32 v34, v49, v34
	v_add_f32_e32 v34, v50, v34
	s_waitcnt vmcnt(0)
	v_pk_mul_f32 v[52:53], v[2:3], v[2:3]
	v_add_f32_e32 v34, v51, v34
	v_add_f32_e32 v34, v52, v34
	v_pk_mul_f32 v[54:55], v[4:5], v[4:5]
	v_add_f32_e32 v34, v53, v34
	v_add_f32_e32 v34, v54, v34
	v_add_f32_e32 v34, v55, v34
	v_lshrrev_b32_e32 v31, 10, v31
	s_mul_i32 s8, s18, 5
	v_cmp_lt_i32_e32 vcc, s1, v18
	v_mov_b64_e32 v[36:37], s[86:87]
	s_nop 0
	v_cndmask_b32_e32 v31, 4, v31, vcc
	v_add_u32_e32 v31, s8, v31
	v_mad_i64_i32 v[36:37], s[26:27], v31, s82, v[36:37]
	s_mov_b64 s[26:27], 0x1000
	s_nop 0
	v_lshl_add_u64 v[38:39], v[36:37], 0, s[26:27]
	v_lshl_add_u64 v[56:57], v[38:39], 0, v[0:1]
	v_lshl_add_u64 v[36:37], v[36:37], 0, v[0:1]
	v_mov_b32_e32 v31, v1
	v_lshl_add_u64 v[38:39], v[38:39], 0, v[30:31]
	global_load_dwordx4 v[44:47], v[22:23], off offset:16
	global_load_dwordx4 v[48:51], v[22:23], off
	global_load_dwordx4 v[52:55], v[56:57], off offset:16
	s_nop 0
	global_load_dwordx4 v[56:59], v[56:57], off
	s_nop 0
	global_load_dwordx4 v[60:63], v[36:37], off offset:16
	global_load_dwordx4 v[64:67], v[36:37], off
	global_load_dwordx4 v[72:75], v[22:23], off offset:2064
	global_load_dwordx4 v[76:79], v[22:23], off offset:2048
	global_load_dwordx4 v[80:83], v[38:39], off offset:16
	global_load_dwordx4 v[84:87], v[38:39], off
	global_load_dwordx4 v[88:91], v[36:37], off offset:2064
	global_load_dwordx4 v[92:95], v[36:37], off offset:2048
	ds_bpermute_b32 v96, v21, v34
	v_lshl_add_u64 v[32:33], v[24:25], 0, v[32:33]
	s_waitcnt lgkmcnt(0)
	v_add_f32_e32 v34, v34, v96
	ds_bpermute_b32 v96, v35, v34
	s_waitcnt lgkmcnt(0)
	v_add_f32_e32 v34, v34, v96
	ds_bpermute_b32 v96, v40, v34
	s_waitcnt lgkmcnt(0)
	v_add_f32_e32 v34, v34, v96
	ds_bpermute_b32 v96, v41, v34
	s_waitcnt lgkmcnt(0)
	v_add_f32_e32 v34, v34, v96
	ds_bpermute_b32 v96, v42, v34
	s_waitcnt lgkmcnt(0)
	v_add_f32_e32 v34, v34, v96
	ds_bpermute_b32 v96, v43, v34
	s_waitcnt lgkmcnt(0)
	v_add_f32_e32 v34, v34, v96
	v_fmamk_f32 v34, v34, 0x3a800000, v205
	v_cmp_gt_f32_e32 vcc, s33, v34
	v_mul_f32_e32 v96, 0x4b800000, v34
	s_nop 0
	v_cndmask_b32_e32 v34, v34, v96, vcc
	v_rsq_f32_e32 v34, v34
	s_nop 0
	v_mul_f32_e32 v96, 0x45800000, v34
	v_cndmask_b32_e32 v34, v34, v96, vcc
	v_pk_mul_f32 v[10:11], v[10:11], v[34:35] op_sel_hi:[1,0]
	v_pk_mul_f32 v[14:15], v[14:15], v[34:35] op_sel_hi:[1,0]
	v_pk_mul_f32 v[16:17], v[16:17], v[34:35] op_sel_hi:[1,0]
	v_pk_mul_f32 v[2:3], v[2:3], v[34:35] op_sel_hi:[1,0]
	v_pk_mul_f32 v[6:7], v[6:7], v[34:35] op_sel_hi:[1,0]
	v_pk_mul_f32 v[8:9], v[8:9], v[34:35] op_sel_hi:[1,0]
	v_lshl_add_u64 v[18:19], v[18:19], 0, s[70:71]
	v_readlane_b32 s26, v255, 24
	v_readlane_b32 s27, v255, 25
	v_cmp_lt_i32_e32 vcc, s65, v18
	s_or_b64 s[24:25], vcc, s[24:25]
	v_lshl_add_u64 v[26:27], v[26:27], 0, s[26:27]
	s_waitcnt vmcnt(11)
	v_pk_mul_f32 v[10:11], v[44:45], v[10:11]
	s_waitcnt vmcnt(10)
	v_pk_mul_f32 v[14:15], v[48:49], v[14:15]
	s_waitcnt vmcnt(9)
	v_pk_add_f32 v[44:45], v[52:53], 1.0 op_sel_hi:[1,0]
	s_waitcnt vmcnt(8)
	v_pk_add_f32 v[48:49], v[56:57], 1.0 op_sel_hi:[1,0]
	s_waitcnt vmcnt(7)
	v_pk_fma_f32 v[44:45], v[44:45], v[10:11], v[60:61]
	v_pk_mul_f32 v[10:11], v[12:13], v[34:35] op_sel_hi:[1,0]
	s_waitcnt vmcnt(6)
	v_pk_fma_f32 v[14:15], v[48:49], v[14:15], v[64:65]
	v_pk_mul_f32 v[16:17], v[50:51], v[16:17]
	v_pk_add_f32 v[48:49], v[58:59], 1.0 op_sel_hi:[1,0]
	v_pk_mul_f32 v[10:11], v[46:47], v[10:11]
	v_pk_add_f32 v[12:13], v[54:55], 1.0 op_sel_hi:[1,0]
	v_pk_fma_f32 v[16:17], v[48:49], v[16:17], v[66:67]
	v_pk_fma_f32 v[46:47], v[12:13], v[10:11], v[62:63]
	v_cvt_pk_bf16_f32 v10, v14, v15
	v_cvt_pk_bf16_f32 v11, v16, v17
	v_cvt_pk_bf16_f32 v12, v44, v45
	v_cvt_pk_bf16_f32 v13, v46, v47
	global_store_dwordx4 v[32:33], v[10:13], off sc1
	s_waitcnt vmcnt(6)
	v_pk_mul_f32 v[2:3], v[2:3], v[72:73]
	s_waitcnt vmcnt(5)
	v_pk_mul_f32 v[6:7], v[6:7], v[76:77]
	s_waitcnt vmcnt(4)
	v_pk_add_f32 v[10:11], v[80:81], 1.0 op_sel_hi:[1,0]
	s_waitcnt vmcnt(3)
	v_pk_add_f32 v[14:15], v[84:85], 1.0 op_sel_hi:[1,0]
	s_waitcnt vmcnt(2)
	v_pk_fma_f32 v[10:11], v[2:3], v[10:11], v[88:89]
	v_pk_mul_f32 v[2:3], v[4:5], v[34:35] op_sel_hi:[1,0]
	s_waitcnt vmcnt(1)
	v_pk_fma_f32 v[6:7], v[6:7], v[14:15], v[92:93]
	v_pk_mul_f32 v[8:9], v[8:9], v[78:79]
	v_pk_add_f32 v[14:15], v[86:87], 1.0 op_sel_hi:[1,0]
	v_pk_mul_f32 v[2:3], v[2:3], v[74:75]
	v_pk_add_f32 v[4:5], v[82:83], 1.0 op_sel_hi:[1,0]
	v_pk_fma_f32 v[8:9], v[8:9], v[14:15], v[94:95]
	v_pk_fma_f32 v[12:13], v[2:3], v[4:5], v[90:91]
	v_cvt_pk_bf16_f32 v2, v6, v7
	v_cvt_pk_bf16_f32 v3, v8, v9
	v_cvt_pk_bf16_f32 v4, v10, v11
	v_cvt_pk_bf16_f32 v5, v12, v13
	global_store_dwordx4 v[32:33], v[2:5], off offset:1024 sc1
	s_andn2_b64 exec, exec, s[24:25]
	s_cbranch_execz .LBB0_488
